# grid barrier: acquire-side buffer_inv issued at arrival (overlaps the barrier round trips) instead of after the release
# speedup vs baseline: 1.0159x; 1.0085x over previous
; __device__ __forceinline__ unsigned xb_ld(unsigned* p)              { return __hip_atomic_load(p, __ATOMIC_RELAXED, __HIP_MEMORY_SCOPE_AGENT); }
; __device__ __forceinline__ unsigned xb_add(unsigned* p, unsigned v) { return __hip_atomic_fetch_add(p, v, __ATOMIC_RELAXED, __HIP_MEMORY_SCOPE_AGENT); }
; #define XB_SPIN(cond, bar) do { unsigned _sp = 0; while (cond) { __builtin_amdgcn_s_sleep(1); \
;     if ((++_sp & 255u) == 0u) { if (xb_ld(&(bar)[XB_TMO])) break; if (_sp > XB_SPIN_CAP) { atomicAdd(&(bar)[XB_TMO], 1u); break; } } } } while (0)
; __device__ __forceinline__ void xcd_barrier(const XcdBarrier& b, const bool leader) {
;     ...
;         const unsigned old = xb_add(&bar[XB_XSUB(b.x)], 1u);
;         const unsigned gen = old / nloc;
;         if (old + 1u == (gen + 1u) * nloc) {
;             __builtin_amdgcn_fence(__ATOMIC_RELEASE, "agent");
;             asm volatile("s_waitcnt vmcnt(0)" ::: "memory");
;             const unsigned og = xb_add(&bar[XB_TOP], 1u);
;             const unsigned tg = og / nx;
;             if (og + 1u == (tg + 1u) * nx) xb_add(&bar[XB_TOPGEN], 1u);
;             else XB_SPIN(xb_ld(&bar[XB_TOPGEN]) == tg, bar);
;             __builtin_amdgcn_fence(__ATOMIC_ACQUIRE, "agent");
;             xb_add(&bar[XB_XGEN(b.x)], 1u);
;             asm volatile("s_waitcnt vmcnt(0)" ::: "memory");
;         } else {
;             XB_SPIN(xb_ld(&bar[XB_XGEN(b.x)]) == gen, bar);
.LBB0_49:
	s_or_b64 exec, exec, s[10:11]
	v_cvt_f32_u32_e32 v6, v4
	s_waitcnt vmcnt(0)
	v_readfirstlane_b32 s1, v5
	v_sub_u32_e32 v5, 0, v4
	v_rcp_iflag_f32_e32 v6, v6
	v_add_u32_e32 v7, s1, v3
	v_mul_f32_e32 v6, 0x4f7ffffe, v6
	v_cvt_u32_f32_e32 v6, v6
	v_mul_lo_u32 v3, v5, v6
	v_mul_hi_u32 v3, v6, v3
	v_add_u32_e32 v3, v6, v3
	v_mul_hi_u32 v3, v7, v3
	v_mul_lo_u32 v5, v3, v4
	v_sub_u32_e32 v5, v7, v5
	v_add_u32_e32 v6, 1, v3
	v_cmp_ge_u32_e32 vcc, v5, v4
	s_nop 1
	v_cndmask_b32_e32 v3, v3, v6, vcc
	v_sub_u32_e32 v6, v5, v4
	v_cndmask_b32_e32 v5, v5, v6, vcc
	v_add_u32_e32 v6, 1, v3
	v_cmp_ge_u32_e32 vcc, v5, v4
	v_add_u32_e32 v5, 1, v7
	s_nop 0
	v_cndmask_b32_e32 v3, v3, v6, vcc
	v_mul_lo_u32 v6, v4, v3
	v_add_u32_e32 v4, v6, v4
	v_cmp_ne_u32_e32 vcc, v5, v4
	s_and_saveexec_b64 s[2:3], vcc
	s_xor_b64 s[8:9], exec, s[2:3]
	s_cbranch_execz .LBB0_63
	buffer_inv sc1
	s_waitcnt lgkmcnt(0)
	v_mov_b32_e32 v2, 0x2000
	s_load_dwordx2 s[14:15], s[90:91], 0xb0
	s_waitcnt lgkmcnt(0)
	s_add_u32 s14, s14, 0x1d79b500
	s_addc_u32 s15, s15, 0
	v_mov_b32_e32 v2, 0
	global_load_dword v2, v2, s[14:15] sc1
	s_waitcnt vmcnt(0)
	v_cmp_eq_u32_e32 vcc, v2, v3
	s_and_saveexec_b64 s[10:11], vcc
	s_cbranch_execz .LBB0_62
	s_load_dwordx4 s[16:19], s[90:91], 0xa8
	s_mov_b32 s1, 1
	s_waitcnt lgkmcnt(0)
	s_mov_b64 s[16:17], 0
	v_mov_b32_e32 v2, 0
	s_add_u32 s12, s18, 0x1d798200
	s_addc_u32 s13, s19, 0
	s_branch .LBB0_53

; __device__ __forceinline__ unsigned xb_ld(unsigned* p)              { return __hip_atomic_load(p, __ATOMIC_RELAXED, __HIP_MEMORY_SCOPE_AGENT); }
; __device__ __forceinline__ unsigned xb_add(unsigned* p, unsigned v) { return __hip_atomic_fetch_add(p, v, __ATOMIC_RELAXED, __HIP_MEMORY_SCOPE_AGENT); }
; #define XB_SPIN(cond, bar) do { unsigned _sp = 0; while (cond) { __builtin_amdgcn_s_sleep(1); \
;     if ((++_sp & 255u) == 0u) { if (xb_ld(&(bar)[XB_TMO])) break; if (_sp > XB_SPIN_CAP) { atomicAdd(&(bar)[XB_TMO], 1u); break; } } } } while (0)
; __device__ __forceinline__ void xcd_barrier(const XcdBarrier& b, const bool leader) {
;     ...
;         if (old + 1u == (gen + 1u) * nloc) {
;             __builtin_amdgcn_fence(__ATOMIC_RELEASE, "agent");
;             asm volatile("s_waitcnt vmcnt(0)" ::: "memory");
;             const unsigned og = xb_add(&bar[XB_TOP], 1u);
;             const unsigned tg = og / nx;
;             if (og + 1u == (tg + 1u) * nx) xb_add(&bar[XB_TOPGEN], 1u);
;             else XB_SPIN(xb_ld(&bar[XB_TOPGEN]) == tg, bar);
;             __builtin_amdgcn_fence(__ATOMIC_ACQUIRE, "agent");
;             xb_add(&bar[XB_XGEN(b.x)], 1u);
;             asm volatile("s_waitcnt vmcnt(0)" ::: "memory");
;         } else {
;             XB_SPIN(xb_ld(&bar[XB_XGEN(b.x)]) == gen, bar);
;             __builtin_amdgcn_fence(__ATOMIC_ACQUIRE, "agent");
;             asm volatile("s_waitcnt vmcnt(0)" ::: "memory");
.LBB0_63:
	s_andn2_saveexec_b64 s[2:3], s[8:9]
	s_cbranch_execz .LBB0_83
	s_mov_b64 s[8:9], exec
	buffer_wbl2 sc1
	buffer_inv sc1
	s_waitcnt lgkmcnt(0)
	s_waitcnt vmcnt(0)
	v_mbcnt_lo_u32_b32 v3, s8, 0
	v_mbcnt_hi_u32_b32 v3, s9, v3
	v_cmp_eq_u32_e32 vcc, 0, v3
	s_and_saveexec_b64 s[10:11], vcc
	s_cbranch_execz .LBB0_66
	s_load_dwordx4 s[12:15], s[90:91], 0xa8
	s_bcnt1_i32_b64 s1, s[8:9]
	v_mov_b32_e32 v4, 0x1d79b000
	v_mov_b32_e32 v5, s1
	s_waitcnt lgkmcnt(0)
	global_atomic_add v4, v4, v5, s[14:15] offset:1024 sc0

; __device__ __forceinline__ unsigned xb_add(unsigned* p, unsigned v) { return __hip_atomic_fetch_add(p, v, __ATOMIC_RELAXED, __HIP_MEMORY_SCOPE_AGENT); }
; __device__ __forceinline__ void xcd_barrier(const XcdBarrier& b, const bool leader) {
;     ...
;             __builtin_amdgcn_fence(__ATOMIC_ACQUIRE, "agent");
;             xb_add(&bar[XB_XGEN(b.x)], 1u);
;             asm volatile("s_waitcnt vmcnt(0)" ::: "memory");
.LBB0_80:
	s_or_b64 exec, exec, s[8:9]
	s_mov_b64 s[8:9], exec
	v_mbcnt_lo_u32_b32 v2, s8, 0
	v_mbcnt_hi_u32_b32 v2, s9, v2
	v_cmp_eq_u32_e32 vcc, 0, v2
	s_waitcnt vmcnt(0)
	s_and_saveexec_b64 s[10:11], vcc
	s_cbranch_execz .LBB0_82
	s_bcnt1_i32_b64 s1, s[8:9]
	v_mov_b32_e32 v2, 0x2000
	v_mov_b32_e32 v3, s1
	global_atomic_add v2, v3, s[6:7] offset:1024
.LBB0_82:
	s_or_b64 exec, exec, s[10:11]
	s_waitcnt vmcnt(0)

; #define PG8_STAGE(bufoff, gbase, voff) do { _Pragma("unroll") for (int _i = 0; _i < 2; ++_i) \
;         __builtin_amdgcn_global_load_lds((const unsigned*)((const char*)(gbase) + (voff)[_i]), (PG8_LAS unsigned*)(lds + (bufoff) + ldsw + _i * 8192), 16, 0, 0); } while (0)
; #define PG8_LDA(dst, b, h) do { _Pragma("unroll") for (int m = 0; m < 4; ++m) _Pragma("unroll") for (int k = 0; k < 2; ++k) dst[m][k] = *(const PG8_LAS bf16x8*)(lds + PG8_SA(b, h) + aoff + m * 2048 + k * 1024); } while (0)
; #define PG8_LDB(dst, b, h) do { _Pragma("unroll") for (int n = 0; n < 2; ++n) _Pragma("unroll") for (int k = 0; k < 2; ++k) dst[n][k] = *(const PG8_LAS bf16x8*)(lds + PG8_SB(b, h) + boff + n * 2048 + k * 1024); } while (0)
; #define PG8_MMA(ai, bj, At, Bt) do { __builtin_amdgcn_s_setprio(1); _Pragma("unroll") for (int m = 0; m < 4; ++m) _Pragma("unroll") for (int n = 0; n < 2; ++n) _Pragma("unroll") for (int k = 0; k < 2; ++k) \
;         acc[ai][bj][m][n] = __builtin_amdgcn_mfma_f32_16x16x32_bf16(Bt[n][k], At[m][k], acc[ai][bj][m][n], 0, 0, 0); __builtin_amdgcn_s_setprio(0); } while (0)
; #define PG8_WAIT_V(n) asm volatile("s_waitcnt vmcnt(" #n ")" ::: "memory")
; template <class Epi, class Sched, bool ALIGN_EPI = false, bool SP2 = false>
; __device__ __forceinline__ void gemm_phase(PG8_LAS unsigned char* lds, const Gemm g, const Sched& S, const Epi& E, const int tid_arg) {
;     ...
;         for (int t = 0; t < nt; t += 2) {
;             const bool last = (t == nt - 2);
;             const char* a1 = cA + (size_t)(t + 1) * kstep;
;             const char* a2 = last ? nA : cA + (size_t)(t + 2) * kstep; const char* b2 = last ? nB : cB + (size_t)(t + 2) * kstep;
;             const char* a3 = a2 + kstep; const char* b3 = b2 + kstep;
;             if (last && has_next) S.a_ready(nxt);
;             if constexpr (SP2) {
;             PG8_LDB(B0, 0, 0); PG8_LDB(B1, 0, 1); PG8_SCHED; PG8_LDA(At, 0, 0); PG8_STAGE(PG8_SA(1, 1), a1 + hstep, voffA);
;             PG8_WAIT_V(8); PG8_WAIT_L(0); PG8_BAR; PG8_MMA(0, 0, At, B0); PG8_MMA(0, 1, At, B1); PG8_BAR; PG8_SCHED;
;     ...
; #pragma unroll
;         for (int a = 0; a < 2; ++a)
; #pragma unroll
;             for (int b = 0; b < 2; ++b)
; #pragma unroll
;                 for (int m = 0; m < 4; ++m)
; #pragma unroll
;                     for (int n = 0; n < 2; ++n) acc[a][b][m][n] = (f32x4){0.f, 0.f, 0.f, 0.f};
.LBB0_95:
	s_ashr_i32 s21, s20, 31
	s_lshl_b64 s[22:23], s[20:21], 19
	s_add_u32 s22, s1, s22
	s_addc_u32 s23, s2, s23
	s_and_b64 s[24:25], s[6:7], exec
	s_cselect_b32 s21, s23, s29
	s_cselect_b32 s45, s22, s28
	s_ashr_i32 s19, s18, 31
	s_lshl_b64 s[24:25], s[18:19], 19
	s_add_u32 s24, s12, s24
	s_addc_u32 s25, s13, s25
	s_and_b64 s[34:35], s[6:7], exec
	s_cselect_b32 s19, s25, s31
	s_cselect_b32 s46, s24, s30
	s_add_u32 s28, s28, 0x40080
	s_addc_u32 s29, s29, 0
	s_add_u32 s47, s30, 0x100
	v_mov_b32_e32 v2, 0
	s_addc_u32 s48, s31, 0
	s_mov_b32 s49, -2
	v_mov_b32_e32 v3, v2
	v_mov_b32_e32 v4, v2
	v_mov_b32_e32 v5, v2
	v_mov_b32_e32 v6, v2
	v_mov_b32_e32 v7, v2
	v_mov_b32_e32 v8, v2
	v_mov_b32_e32 v9, v2
	v_mov_b32_e32 v18, v2
	v_mov_b32_e32 v19, v2
	v_mov_b32_e32 v20, v2
	v_mov_b32_e32 v21, v2
	v_mov_b32_e32 v22, v2
	v_mov_b32_e32 v23, v2
	v_mov_b32_e32 v24, v2
	v_mov_b32_e32 v25, v2
	v_mov_b32_e32 v34, v2
	v_mov_b32_e32 v35, v2
	v_mov_b32_e32 v36, v2
	v_mov_b32_e32 v37, v2
	v_mov_b32_e32 v38, v2
	v_mov_b32_e32 v39, v2
	v_mov_b32_e32 v40, v2
	v_mov_b32_e32 v41, v2
	v_mov_b32_e32 v50, v2
	v_mov_b32_e32 v51, v2
	v_mov_b32_e32 v52, v2
	v_mov_b32_e32 v53, v2
	v_mov_b32_e32 v54, v2
	v_mov_b32_e32 v55, v2
	v_mov_b32_e32 v56, v2
	v_mov_b32_e32 v57, v2
	v_mov_b32_e32 v10, v2
	v_mov_b32_e32 v11, v2
	v_mov_b32_e32 v12, v2
	v_mov_b32_e32 v13, v2
	v_mov_b32_e32 v14, v2
	v_mov_b32_e32 v15, v2
	v_mov_b32_e32 v16, v2
	v_mov_b32_e32 v17, v2
	v_mov_b32_e32 v26, v2
	v_mov_b32_e32 v27, v2
	v_mov_b32_e32 v28, v2
	v_mov_b32_e32 v29, v2
	v_mov_b32_e32 v30, v2
	v_mov_b32_e32 v31, v2
	v_mov_b32_e32 v32, v2
	v_mov_b32_e32 v33, v2
	v_mov_b32_e32 v42, v2
	v_mov_b32_e32 v43, v2
	v_mov_b32_e32 v44, v2
	v_mov_b32_e32 v45, v2
	v_mov_b32_e32 v46, v2
	v_mov_b32_e32 v47, v2
	v_mov_b32_e32 v48, v2
	v_mov_b32_e32 v49, v2
	v_mov_b32_e32 v58, v2
	v_mov_b32_e32 v59, v2
	v_mov_b32_e32 v60, v2
	v_mov_b32_e32 v61, v2
	v_mov_b32_e32 v62, v2
	v_mov_b32_e32 v63, v2
	v_mov_b32_e32 v64, v2
	v_mov_b32_e32 v65, v2
	v_mov_b32_e32 v66, v2
	v_mov_b32_e32 v67, v2
	v_mov_b32_e32 v68, v2
	v_mov_b32_e32 v69, v2
	v_mov_b32_e32 v70, v2
	v_mov_b32_e32 v71, v2
	v_mov_b32_e32 v72, v2
	v_mov_b32_e32 v73, v2
	v_mov_b32_e32 v82, v2
	v_mov_b32_e32 v83, v2
	v_mov_b32_e32 v84, v2
	v_mov_b32_e32 v85, v2
	v_mov_b32_e32 v86, v2
	v_mov_b32_e32 v87, v2
	v_mov_b32_e32 v88, v2
	v_mov_b32_e32 v89, v2
	v_mov_b32_e32 v98, v2
	v_mov_b32_e32 v99, v2
	v_mov_b32_e32 v100, v2
	v_mov_b32_e32 v101, v2
	v_mov_b32_e32 v102, v2
	v_mov_b32_e32 v103, v2
	v_mov_b32_e32 v104, v2
	v_mov_b32_e32 v105, v2
	v_mov_b32_e32 v114, v2
	v_mov_b32_e32 v115, v2
	v_mov_b32_e32 v116, v2
	v_mov_b32_e32 v117, v2
	v_mov_b32_e32 v118, v2
	v_mov_b32_e32 v119, v2
	v_mov_b32_e32 v120, v2
	v_mov_b32_e32 v121, v2
	v_mov_b32_e32 v74, v2
	v_mov_b32_e32 v75, v2
	v_mov_b32_e32 v76, v2
	v_mov_b32_e32 v77, v2
	v_mov_b32_e32 v78, v2
	v_mov_b32_e32 v79, v2
	v_mov_b32_e32 v80, v2
	v_mov_b32_e32 v81, v2
	v_mov_b32_e32 v90, v2
	v_mov_b32_e32 v91, v2
	v_mov_b32_e32 v92, v2
	v_mov_b32_e32 v93, v2
	v_mov_b32_e32 v94, v2
	v_mov_b32_e32 v95, v2
	v_mov_b32_e32 v96, v2
	v_mov_b32_e32 v97, v2
	v_mov_b32_e32 v106, v2
	v_mov_b32_e32 v107, v2
	v_mov_b32_e32 v108, v2
	v_mov_b32_e32 v109, v2
	v_mov_b32_e32 v110, v2
	v_mov_b32_e32 v111, v2
	v_mov_b32_e32 v112, v2
	v_mov_b32_e32 v113, v2
	v_mov_b32_e32 v122, v2
	v_mov_b32_e32 v123, v2
	v_mov_b32_e32 v124, v2
	v_mov_b32_e32 v125, v2
	v_mov_b32_e32 v126, v2
	v_mov_b32_e32 v127, v2
	v_mov_b32_e32 v128, v2
	v_mov_b32_e32 v129, v2
	s_nop 0
	s_nop 0
	s_nop 0
	s_nop 0
	s_nop 0
	s_nop 0
	s_nop 0
	s_nop 0
	s_nop 0
.LBB0_96:
	ds_read_b128 v[152:155], v149
	ds_read_b128 v[156:159], v149 offset:1024
	ds_read_b128 v[160:163], v149 offset:2048
	ds_read_b128 v[164:167], v149 offset:3072
	ds_read_b128 v[168:171], v150
	ds_read_b128 v[172:175], v150 offset:1024
	ds_read_b128 v[176:179], v150 offset:2048
	ds_read_b128 v[182:185], v150 offset:3072
	s_add_u32 s30, s28, 0xfffc0080
	s_addc_u32 s31, s29, -1
	s_cmp_eq_u32 s49, 12
	s_cselect_b32 s35, s21, s31
	s_cselect_b32 s34, s45, s30
	s_cselect_b32 s31, s19, s48
	s_cselect_b32 s30, s46, s47
	v_lshl_add_u64 v[194:195], s[28:29], 0, v[138:139]
	s_add_i32 m0, s27, 0xc000
	ds_read_b128 v[186:189], v151
	ds_read_b128 v[190:193], v151 offset:1024
	ds_read_b128 v[202:205], v151 offset:2048
	ds_read_b128 v[206:209], v151 offset:3072
	ds_read_b128 v[210:213], v151 offset:4096
	ds_read_b128 v[214:217], v151 offset:5120
	ds_read_b128 v[218:221], v151 offset:6144
	ds_read_b128 v[222:225], v151 offset:7168
	global_load_lds_dwordx4 v[194:195], off
	v_lshl_add_u64 v[194:195], s[28:29], 0, v[140:141]
	s_add_i32 m0, s27, 0xe000
	s_nop 0
	global_load_lds_dwordx4 v[194:195], off
	s_waitcnt vmcnt(8)
	s_waitcnt lgkmcnt(0)
	s_barrier
; #define PG8_STAGE(bufoff, gbase, voff) do { _Pragma("unroll") for (int _i = 0; _i < 2; ++_i) \
;         __builtin_amdgcn_global_load_lds((const unsigned*)((const char*)(gbase) + (voff)[_i]), (PG8_LAS unsigned*)(lds + (bufoff) + ldsw + _i * 8192), 16, 0, 0); } while (0)
; #define PG8_LDA(dst, b, h) do { _Pragma("unroll") for (int m = 0; m < 4; ++m) _Pragma("unroll") for (int k = 0; k < 2; ++k) dst[m][k] = *(const PG8_LAS bf16x8*)(lds + PG8_SA(b, h) + aoff + m * 2048 + k * 1024); } while (0)
; #define PG8_MMA(ai, bj, At, Bt) do { __builtin_amdgcn_s_setprio(1); _Pragma("unroll") for (int m = 0; m < 4; ++m) _Pragma("unroll") for (int n = 0; n < 2; ++n) _Pragma("unroll") for (int k = 0; k < 2; ++k) \
;         acc[ai][bj][m][n] = __builtin_amdgcn_mfma_f32_16x16x32_bf16(Bt[n][k], At[m][k], acc[ai][bj][m][n], 0, 0, 0); __builtin_amdgcn_s_setprio(0); } while (0)
; #define PG8_WAIT_V(n) asm volatile("s_waitcnt vmcnt(" #n ")" ::: "memory")
; #define PG8_WAIT_L(n) asm volatile("s_waitcnt lgkmcnt(" #n ")" ::: "memory")
; #define PG8_BAR __builtin_amdgcn_s_barrier()
; #define PG8_SCHED __builtin_amdgcn_sched_barrier(0)
; template <class Epi, class Sched, bool ALIGN_EPI = false, bool SP2 = false>
; __device__ __forceinline__ void gemm_phase(PG8_LAS unsigned char* lds, const Gemm g, const Sched& S, const Epi& E, const int tid_arg) {
;     ...
;             PG8_WAIT_V(8); PG8_WAIT_L(0); PG8_BAR; PG8_MMA(0, 0, At, B0); PG8_MMA(0, 1, At, B1); PG8_BAR; PG8_SCHED;
;             PG8_LDA(At, 0, 1); PG8_STAGE(PG8_SB(0, 0), b2, voffB); PG8_STAGE(PG8_SB(0, 1), b2 + hstep, voffB); PG8_STAGE(PG8_SA(0, 0), a2, voffA);
;             PG8_WAIT_V(8); PG8_WAIT_L(0); PG8_BAR; PG8_MMA(1, 0, At, B0); PG8_MMA(1, 1, At, B1); PG8_BAR; PG8_SCHED;
	s_setprio 1
	s_waitcnt lgkmcnt(0)
	v_mfma_f32_16x16x32_bf16 v[126:129], v[152:155], v[186:189], v[126:129]
	v_mfma_f32_16x16x32_bf16 v[122:125], v[160:163], v[186:189], v[122:125]
	v_mfma_f32_16x16x32_bf16 v[110:113], v[152:155], v[202:205], v[110:113]
	v_mfma_f32_16x16x32_bf16 v[106:109], v[160:163], v[202:205], v[106:109]
	v_mfma_f32_16x16x32_bf16 v[94:97], v[152:155], v[210:213], v[94:97]
	v_mfma_f32_16x16x32_bf16 v[90:93], v[160:163], v[210:213], v[90:93]
	v_mfma_f32_16x16x32_bf16 v[78:81], v[152:155], v[218:221], v[78:81]
	v_mfma_f32_16x16x32_bf16 v[74:77], v[160:163], v[218:221], v[74:77]
	v_mfma_f32_16x16x32_bf16 v[126:129], v[156:159], v[190:193], v[126:129]
	v_mfma_f32_16x16x32_bf16 v[122:125], v[164:167], v[190:193], v[122:125]
	v_mfma_f32_16x16x32_bf16 v[110:113], v[156:159], v[206:209], v[110:113]
	v_mfma_f32_16x16x32_bf16 v[106:109], v[164:167], v[206:209], v[106:109]
	v_mfma_f32_16x16x32_bf16 v[94:97], v[156:159], v[214:217], v[94:97]
	v_mfma_f32_16x16x32_bf16 v[90:93], v[164:167], v[214:217], v[90:93]
	v_mfma_f32_16x16x32_bf16 v[78:81], v[156:159], v[222:225], v[78:81]
	v_mfma_f32_16x16x32_bf16 v[74:77], v[164:167], v[222:225], v[74:77]
	s_setprio 0
	s_setprio 1
	v_mfma_f32_16x16x32_bf16 v[118:121], v[168:171], v[186:189], v[118:121]
	v_mfma_f32_16x16x32_bf16 v[114:117], v[176:179], v[186:189], v[114:117]
	v_mfma_f32_16x16x32_bf16 v[102:105], v[168:171], v[202:205], v[102:105]
	v_mfma_f32_16x16x32_bf16 v[98:101], v[176:179], v[202:205], v[98:101]
	v_mfma_f32_16x16x32_bf16 v[86:89], v[168:171], v[210:213], v[86:89]
	v_mfma_f32_16x16x32_bf16 v[82:85], v[176:179], v[210:213], v[82:85]
	v_mfma_f32_16x16x32_bf16 v[70:73], v[168:171], v[218:221], v[70:73]
	v_mfma_f32_16x16x32_bf16 v[66:69], v[176:179], v[218:221], v[66:69]
	v_mfma_f32_16x16x32_bf16 v[118:121], v[172:175], v[190:193], v[118:121]
	v_mfma_f32_16x16x32_bf16 v[114:117], v[182:185], v[190:193], v[114:117]
	v_mfma_f32_16x16x32_bf16 v[102:105], v[172:175], v[206:209], v[102:105]
	v_mfma_f32_16x16x32_bf16 v[98:101], v[182:185], v[206:209], v[98:101]
	v_mfma_f32_16x16x32_bf16 v[86:89], v[172:175], v[214:217], v[86:89]
	v_mfma_f32_16x16x32_bf16 v[82:85], v[182:185], v[214:217], v[82:85]
	v_mfma_f32_16x16x32_bf16 v[70:73], v[172:175], v[222:225], v[70:73]
	v_mfma_f32_16x16x32_bf16 v[66:69], v[182:185], v[222:225], v[66:69]
	s_setprio 0
	s_barrier
	s_add_i32 s50, s41, s3
	v_lshl_add_u64 v[194:195], s[30:31], 0, v[134:135]
	s_mov_b32 m0, s50
	ds_read_b128 v[186:189], v151 offset:16384
	ds_read_b128 v[190:193], v151 offset:17408
	ds_read_b128 v[202:205], v151 offset:18432
	ds_read_b128 v[206:209], v151 offset:19456
	ds_read_b128 v[210:213], v151 offset:20480
	ds_read_b128 v[214:217], v151 offset:21504
	ds_read_b128 v[218:221], v151 offset:22528
	ds_read_b128 v[222:225], v151 offset:23552
	global_load_lds_dwordx4 v[194:195], off
	s_add_i32 m0, s50, 0x2000
	s_add_u32 s50, s30, 0x40000
	v_lshl_add_u64 v[226:227], s[30:31], 0, v[130:131]
	s_addc_u32 s51, s31, 0
	s_add_i32 s52, s42, s3
	global_load_lds_dwordx4 v[226:227], off
	v_lshl_add_u64 v[228:229], s[50:51], 0, v[134:135]
	s_mov_b32 m0, s52
	v_lshl_add_u64 v[230:231], s[34:35], 0, v[132:133]
	global_load_lds_dwordx4 v[228:229], off
	v_lshl_add_u64 v[228:229], s[50:51], 0, v[130:131]
	s_add_i32 m0, s52, 0x2000
	s_nop 0
	global_load_lds_dwordx4 v[228:229], off
	v_lshl_add_u64 v[228:229], s[34:35], 0, v[136:137]
	s_mov_b32 m0, s27
	s_nop 0
	global_load_lds_dwordx4 v[228:229], off
	s_mov_b32 m0, s33
	s_nop 0
	global_load_lds_dwordx4 v[230:231], off
	s_waitcnt vmcnt(8)
	s_waitcnt lgkmcnt(0)
	s_barrier
	s_setprio 1
	s_waitcnt lgkmcnt(0)
	v_mfma_f32_16x16x32_bf16 v[62:65], v[152:155], v[186:189], v[62:65]
	v_mfma_f32_16x16x32_bf16 v[58:61], v[160:163], v[186:189], v[58:61]
	v_mfma_f32_16x16x32_bf16 v[46:49], v[152:155], v[202:205], v[46:49]
	v_mfma_f32_16x16x32_bf16 v[42:45], v[160:163], v[202:205], v[42:45]
	v_mfma_f32_16x16x32_bf16 v[30:33], v[152:155], v[210:213], v[30:33]
	v_mfma_f32_16x16x32_bf16 v[26:29], v[160:163], v[210:213], v[26:29]
	v_mfma_f32_16x16x32_bf16 v[14:17], v[152:155], v[218:221], v[14:17]
	v_mfma_f32_16x16x32_bf16 v[10:13], v[160:163], v[218:221], v[10:13]
	v_mfma_f32_16x16x32_bf16 v[62:65], v[156:159], v[190:193], v[62:65]
	v_mfma_f32_16x16x32_bf16 v[58:61], v[164:167], v[190:193], v[58:61]
	v_mfma_f32_16x16x32_bf16 v[46:49], v[156:159], v[206:209], v[46:49]
	v_mfma_f32_16x16x32_bf16 v[42:45], v[164:167], v[206:209], v[42:45]
	v_mfma_f32_16x16x32_bf16 v[30:33], v[156:159], v[214:217], v[30:33]
	v_mfma_f32_16x16x32_bf16 v[26:29], v[164:167], v[214:217], v[26:29]
	v_mfma_f32_16x16x32_bf16 v[14:17], v[156:159], v[222:225], v[14:17]
	v_mfma_f32_16x16x32_bf16 v[10:13], v[164:167], v[222:225], v[10:13]
	s_setprio 0
	s_setprio 1
	v_mfma_f32_16x16x32_bf16 v[54:57], v[168:171], v[186:189], v[54:57]
	v_mfma_f32_16x16x32_bf16 v[50:53], v[176:179], v[186:189], v[50:53]
	v_mfma_f32_16x16x32_bf16 v[38:41], v[168:171], v[202:205], v[38:41]
	v_mfma_f32_16x16x32_bf16 v[34:37], v[176:179], v[202:205], v[34:37]
	v_mfma_f32_16x16x32_bf16 v[22:25], v[168:171], v[210:213], v[22:25]
	v_mfma_f32_16x16x32_bf16 v[18:21], v[176:179], v[210:213], v[18:21]
	v_mfma_f32_16x16x32_bf16 v[6:9], v[168:171], v[218:221], v[6:9]
	v_mfma_f32_16x16x32_bf16 v[2:5], v[176:179], v[218:221], v[2:5]
	v_mfma_f32_16x16x32_bf16 v[54:57], v[172:175], v[190:193], v[54:57]
	v_mfma_f32_16x16x32_bf16 v[50:53], v[182:185], v[190:193], v[50:53]
	v_mfma_f32_16x16x32_bf16 v[38:41], v[172:175], v[206:209], v[38:41]
	v_mfma_f32_16x16x32_bf16 v[34:37], v[182:185], v[206:209], v[34:37]
	v_mfma_f32_16x16x32_bf16 v[22:25], v[172:175], v[214:217], v[22:25]
	v_mfma_f32_16x16x32_bf16 v[18:21], v[182:185], v[214:217], v[18:21]
	v_mfma_f32_16x16x32_bf16 v[6:9], v[172:175], v[222:225], v[6:9]
	v_mfma_f32_16x16x32_bf16 v[2:5], v[182:185], v[222:225], v[2:5]
	s_setprio 0
	s_barrier
; #define PG8_STAGE(bufoff, gbase, voff) do { _Pragma("unroll") for (int _i = 0; _i < 2; ++_i) \
;         __builtin_amdgcn_global_load_lds((const unsigned*)((const char*)(gbase) + (voff)[_i]), (PG8_LAS unsigned*)(lds + (bufoff) + ldsw + _i * 8192), 16, 0, 0); } while (0)
; #define PG8_LDA(dst, b, h) do { _Pragma("unroll") for (int m = 0; m < 4; ++m) _Pragma("unroll") for (int k = 0; k < 2; ++k) dst[m][k] = *(const PG8_LAS bf16x8*)(lds + PG8_SA(b, h) + aoff + m * 2048 + k * 1024); } while (0)
; #define PG8_LDB(dst, b, h) do { _Pragma("unroll") for (int n = 0; n < 2; ++n) _Pragma("unroll") for (int k = 0; k < 2; ++k) dst[n][k] = *(const PG8_LAS bf16x8*)(lds + PG8_SB(b, h) + boff + n * 2048 + k * 1024); } while (0)
; #define PG8_MMA(ai, bj, At, Bt) do { __builtin_amdgcn_s_setprio(1); _Pragma("unroll") for (int m = 0; m < 4; ++m) _Pragma("unroll") for (int n = 0; n < 2; ++n) _Pragma("unroll") for (int k = 0; k < 2; ++k) \
;         acc[ai][bj][m][n] = __builtin_amdgcn_mfma_f32_16x16x32_bf16(Bt[n][k], At[m][k], acc[ai][bj][m][n], 0, 0, 0); __builtin_amdgcn_s_setprio(0); } while (0)
; #define PG8_WAIT_V(n) asm volatile("s_waitcnt vmcnt(" #n ")" ::: "memory")
; #define PG8_WAIT_L(n) asm volatile("s_waitcnt lgkmcnt(" #n ")" ::: "memory")
; #define PG8_BAR __builtin_amdgcn_s_barrier()
; #define PG8_SCHED __builtin_amdgcn_sched_barrier(0)
; template <class Epi, class Sched, bool ALIGN_EPI = false, bool SP2 = false>
; __device__ __forceinline__ void gemm_phase(PG8_LAS unsigned char* lds, const Gemm g, const Sched& S, const Epi& E, const int tid_arg) {
;     ...
;             PG8_LDB(B0, 1, 0); PG8_LDB(B1, 1, 1); PG8_SCHED; PG8_LDA(At, 1, 0); PG8_STAGE(PG8_SA(0, 1), a2 + hstep, voffA);
;             PG8_WAIT_V(8); PG8_WAIT_L(0); PG8_BAR; PG8_MMA(0, 0, At, B0); PG8_MMA(0, 1, At, B1); PG8_BAR; PG8_SCHED;
	s_add_i32 s50, 0, 0x18000
	s_add_i32 s51, 0, 0x1c000
	v_add_u32_e32 v164, s50, v147
	v_add_u32_e32 v180, s51, v147
	ds_read_b128 v[152:155], v164
	ds_read_b128 v[156:159], v164 offset:1024
	ds_read_b128 v[160:163], v164 offset:2048
	ds_read_b128 v[164:167], v164 offset:3072
	ds_read_b128 v[168:171], v180
	ds_read_b128 v[172:175], v180 offset:1024
	ds_read_b128 v[176:179], v180 offset:2048
	ds_read_b128 v[182:185], v180 offset:3072
	s_add_u32 s34, s34, 0x40000
	s_addc_u32 s35, s35, 0
	s_mov_b32 m0, s36
	v_lshl_add_u64 v[232:233], s[34:35], 0, v[136:137]
	ds_read_b128 v[186:189], v151 offset:32768
	ds_read_b128 v[190:193], v151 offset:33792
	ds_read_b128 v[202:205], v151 offset:34816
	ds_read_b128 v[206:209], v151 offset:35840
	ds_read_b128 v[210:213], v151 offset:36864
	ds_read_b128 v[214:217], v151 offset:37888
	ds_read_b128 v[218:221], v151 offset:38912
	ds_read_b128 v[222:225], v151 offset:39936
	global_load_lds_dwordx4 v[232:233], off
	v_lshl_add_u64 v[232:233], s[34:35], 0, v[132:133]
	s_mov_b32 m0, s37
	s_nop 0
	global_load_lds_dwordx4 v[232:233], off
	s_waitcnt vmcnt(8)
	s_waitcnt lgkmcnt(0)
	s_barrier
	s_setprio 1
	s_waitcnt lgkmcnt(0)
	v_mfma_f32_16x16x32_bf16 v[126:129], v[152:155], v[186:189], v[126:129]
	v_mfma_f32_16x16x32_bf16 v[122:125], v[160:163], v[186:189], v[122:125]
	v_mfma_f32_16x16x32_bf16 v[110:113], v[152:155], v[202:205], v[110:113]
	v_mfma_f32_16x16x32_bf16 v[106:109], v[160:163], v[202:205], v[106:109]
	v_mfma_f32_16x16x32_bf16 v[94:97], v[152:155], v[210:213], v[94:97]
	v_mfma_f32_16x16x32_bf16 v[90:93], v[160:163], v[210:213], v[90:93]
	v_mfma_f32_16x16x32_bf16 v[78:81], v[152:155], v[218:221], v[78:81]
	v_mfma_f32_16x16x32_bf16 v[74:77], v[160:163], v[218:221], v[74:77]
	v_mfma_f32_16x16x32_bf16 v[126:129], v[156:159], v[190:193], v[126:129]
	v_mfma_f32_16x16x32_bf16 v[122:125], v[164:167], v[190:193], v[122:125]
	v_mfma_f32_16x16x32_bf16 v[110:113], v[156:159], v[206:209], v[110:113]
	v_mfma_f32_16x16x32_bf16 v[106:109], v[164:167], v[206:209], v[106:109]
	v_mfma_f32_16x16x32_bf16 v[94:97], v[156:159], v[214:217], v[94:97]
	v_mfma_f32_16x16x32_bf16 v[90:93], v[164:167], v[214:217], v[90:93]
	v_mfma_f32_16x16x32_bf16 v[78:81], v[156:159], v[222:225], v[78:81]
	v_mfma_f32_16x16x32_bf16 v[74:77], v[164:167], v[222:225], v[74:77]
	s_setprio 0
	s_setprio 1
	v_mfma_f32_16x16x32_bf16 v[118:121], v[168:171], v[186:189], v[118:121]
	v_mfma_f32_16x16x32_bf16 v[114:117], v[176:179], v[186:189], v[114:117]
	v_mfma_f32_16x16x32_bf16 v[102:105], v[168:171], v[202:205], v[102:105]
	v_mfma_f32_16x16x32_bf16 v[98:101], v[176:179], v[202:205], v[98:101]
	v_mfma_f32_16x16x32_bf16 v[86:89], v[168:171], v[210:213], v[86:89]
	v_mfma_f32_16x16x32_bf16 v[82:85], v[176:179], v[210:213], v[82:85]
	v_mfma_f32_16x16x32_bf16 v[70:73], v[168:171], v[218:221], v[70:73]
	v_mfma_f32_16x16x32_bf16 v[66:69], v[176:179], v[218:221], v[66:69]
	v_mfma_f32_16x16x32_bf16 v[118:121], v[172:175], v[190:193], v[118:121]
	v_mfma_f32_16x16x32_bf16 v[114:117], v[182:185], v[190:193], v[114:117]
	v_mfma_f32_16x16x32_bf16 v[102:105], v[172:175], v[206:209], v[102:105]
	v_mfma_f32_16x16x32_bf16 v[98:101], v[182:185], v[206:209], v[98:101]
	v_mfma_f32_16x16x32_bf16 v[86:89], v[172:175], v[214:217], v[86:89]
	v_mfma_f32_16x16x32_bf16 v[82:85], v[182:185], v[214:217], v[82:85]
	v_mfma_f32_16x16x32_bf16 v[70:73], v[172:175], v[222:225], v[70:73]
	v_mfma_f32_16x16x32_bf16 v[66:69], v[182:185], v[222:225], v[66:69]
	s_setprio 0
	s_barrier
; #define PG8_STAGE(bufoff, gbase, voff) do { _Pragma("unroll") for (int _i = 0; _i < 2; ++_i) \
;         __builtin_amdgcn_global_load_lds((const unsigned*)((const char*)(gbase) + (voff)[_i]), (PG8_LAS unsigned*)(lds + (bufoff) + ldsw + _i * 8192), 16, 0, 0); } while (0)
; #define PG8_LDA(dst, b, h) do { _Pragma("unroll") for (int m = 0; m < 4; ++m) _Pragma("unroll") for (int k = 0; k < 2; ++k) dst[m][k] = *(const PG8_LAS bf16x8*)(lds + PG8_SA(b, h) + aoff + m * 2048 + k * 1024); } while (0)
; #define PG8_MMA(ai, bj, At, Bt) do { __builtin_amdgcn_s_setprio(1); _Pragma("unroll") for (int m = 0; m < 4; ++m) _Pragma("unroll") for (int n = 0; n < 2; ++n) _Pragma("unroll") for (int k = 0; k < 2; ++k) \
;         acc[ai][bj][m][n] = __builtin_amdgcn_mfma_f32_16x16x32_bf16(Bt[n][k], At[m][k], acc[ai][bj][m][n], 0, 0, 0); __builtin_amdgcn_s_setprio(0); } while (0)
; #define PG8_WAIT_V(n) asm volatile("s_waitcnt vmcnt(" #n ")" ::: "memory")
; #define PG8_WAIT_L(n) asm volatile("s_waitcnt lgkmcnt(" #n ")" ::: "memory")
; #define PG8_BAR __builtin_amdgcn_s_barrier()
; #define PG8_SCHED __builtin_amdgcn_sched_barrier(0)
; template <class Epi, class Sched, bool ALIGN_EPI = false, bool SP2 = false>
; __device__ __forceinline__ void gemm_phase(PG8_LAS unsigned char* lds, const Gemm g, const Sched& S, const Epi& E, const int tid_arg) {
;     ...
;             PG8_LDA(At, 1, 1); PG8_STAGE(PG8_SB(1, 0), b3, voffB); PG8_STAGE(PG8_SB(1, 1), b3 + hstep, voffB); PG8_STAGE(PG8_SA(1, 0), a3, voffA);
;             PG8_WAIT_V(8); PG8_WAIT_L(0); PG8_BAR; PG8_MMA(1, 0, At, B0); PG8_MMA(1, 1, At, B1); PG8_BAR; PG8_SCHED;
;     ...
;         if constexpr (ALIGN_EPI) { if (wr == 0) PG8_BAR; }
	s_add_i32 s34, s50, s3
	v_lshl_add_u64 v[194:195], v[194:195], 0, s[14:15]
	s_mov_b32 m0, s34
	ds_read_b128 v[186:189], v151 offset:49152
	ds_read_b128 v[190:193], v151 offset:50176
	ds_read_b128 v[202:205], v151 offset:51200
	ds_read_b128 v[206:209], v151 offset:52224
	ds_read_b128 v[210:213], v151 offset:53248
	ds_read_b128 v[214:217], v151 offset:54272
	ds_read_b128 v[218:221], v151 offset:55296
	ds_read_b128 v[222:225], v151 offset:56320
	global_load_lds_dwordx4 v[194:195], off
	s_add_i32 m0, s34, 0x2000
	s_add_u32 s30, s30, 0x40080
	v_lshl_add_u64 v[194:195], v[226:227], 0, s[14:15]
	s_addc_u32 s31, s31, 0
	s_add_i32 s34, s51, s3
	global_load_lds_dwordx4 v[194:195], off
	v_lshl_add_u64 v[194:195], s[30:31], 0, v[134:135]
	s_mov_b32 m0, s34
	s_nop 0
	global_load_lds_dwordx4 v[194:195], off
	v_lshl_add_u64 v[194:195], s[30:31], 0, v[130:131]
	s_add_i32 m0, s34, 0x2000
	s_nop 0
	global_load_lds_dwordx4 v[194:195], off
	v_lshl_add_u64 v[194:195], v[228:229], 0, s[14:15]
	s_mov_b32 m0, s39
	s_nop 0
	global_load_lds_dwordx4 v[194:195], off
	v_lshl_add_u64 v[194:195], v[230:231], 0, s[14:15]
	s_mov_b32 m0, s40
	s_nop 0
	global_load_lds_dwordx4 v[194:195], off
	s_waitcnt vmcnt(8)
	s_waitcnt lgkmcnt(0)
	s_barrier
	s_setprio 1
	s_waitcnt lgkmcnt(0)
	v_mfma_f32_16x16x32_bf16 v[62:65], v[152:155], v[186:189], v[62:65]
	v_mfma_f32_16x16x32_bf16 v[58:61], v[160:163], v[186:189], v[58:61]
	v_mfma_f32_16x16x32_bf16 v[46:49], v[152:155], v[202:205], v[46:49]
	v_mfma_f32_16x16x32_bf16 v[42:45], v[160:163], v[202:205], v[42:45]
	v_mfma_f32_16x16x32_bf16 v[30:33], v[152:155], v[210:213], v[30:33]
	v_mfma_f32_16x16x32_bf16 v[26:29], v[160:163], v[210:213], v[26:29]
	v_mfma_f32_16x16x32_bf16 v[14:17], v[152:155], v[218:221], v[14:17]
	v_mfma_f32_16x16x32_bf16 v[10:13], v[160:163], v[218:221], v[10:13]
	v_mfma_f32_16x16x32_bf16 v[62:65], v[156:159], v[190:193], v[62:65]
	v_mfma_f32_16x16x32_bf16 v[58:61], v[164:167], v[190:193], v[58:61]
	v_mfma_f32_16x16x32_bf16 v[46:49], v[156:159], v[206:209], v[46:49]
	v_mfma_f32_16x16x32_bf16 v[42:45], v[164:167], v[206:209], v[42:45]
	v_mfma_f32_16x16x32_bf16 v[30:33], v[156:159], v[214:217], v[30:33]
	v_mfma_f32_16x16x32_bf16 v[26:29], v[164:167], v[214:217], v[26:29]
	v_mfma_f32_16x16x32_bf16 v[14:17], v[156:159], v[222:225], v[14:17]
	v_mfma_f32_16x16x32_bf16 v[10:13], v[164:167], v[222:225], v[10:13]
	s_setprio 0
	s_setprio 1
	v_mfma_f32_16x16x32_bf16 v[54:57], v[168:171], v[186:189], v[54:57]
	v_mfma_f32_16x16x32_bf16 v[50:53], v[176:179], v[186:189], v[50:53]
	v_mfma_f32_16x16x32_bf16 v[38:41], v[168:171], v[202:205], v[38:41]
	v_mfma_f32_16x16x32_bf16 v[34:37], v[176:179], v[202:205], v[34:37]
	v_mfma_f32_16x16x32_bf16 v[22:25], v[168:171], v[210:213], v[22:25]
	v_mfma_f32_16x16x32_bf16 v[18:21], v[176:179], v[210:213], v[18:21]
	v_mfma_f32_16x16x32_bf16 v[6:9], v[168:171], v[218:221], v[6:9]
	v_mfma_f32_16x16x32_bf16 v[2:5], v[176:179], v[218:221], v[2:5]
	v_mfma_f32_16x16x32_bf16 v[54:57], v[172:175], v[190:193], v[54:57]
	v_mfma_f32_16x16x32_bf16 v[50:53], v[182:185], v[190:193], v[50:53]
	v_mfma_f32_16x16x32_bf16 v[38:41], v[172:175], v[206:209], v[38:41]
	v_mfma_f32_16x16x32_bf16 v[34:37], v[182:185], v[206:209], v[34:37]
	v_mfma_f32_16x16x32_bf16 v[22:25], v[172:175], v[214:217], v[22:25]
	v_mfma_f32_16x16x32_bf16 v[18:21], v[182:185], v[214:217], v[18:21]
	v_mfma_f32_16x16x32_bf16 v[6:9], v[172:175], v[222:225], v[6:9]
	v_mfma_f32_16x16x32_bf16 v[2:5], v[182:185], v[222:225], v[2:5]
	s_setprio 0
	s_barrier
	s_add_i32 s49, s49, 2
	s_add_u32 s28, s28, 0x100
	s_addc_u32 s29, s29, 0
	s_add_u32 s47, s47, 0x100
	s_addc_u32 s48, s48, 0
	s_cmp_gt_u32 s49, 13
	s_cbranch_scc0 .LBB0_96
	s_and_b64 vcc, exec, s[16:17]
	s_cbranch_vccz .LBB0_99
	s_barrier

; __device__ __forceinline__ unsigned xb_ld(unsigned* p)              { return __hip_atomic_load(p, __ATOMIC_RELAXED, __HIP_MEMORY_SCOPE_AGENT); }
; __device__ __forceinline__ unsigned xb_add(unsigned* p, unsigned v) { return __hip_atomic_fetch_add(p, v, __ATOMIC_RELAXED, __HIP_MEMORY_SCOPE_AGENT); }
; #define XB_SPIN(cond, bar) do { unsigned _sp = 0; while (cond) { __builtin_amdgcn_s_sleep(1); \
;     if ((++_sp & 255u) == 0u) { if (xb_ld(&(bar)[XB_TMO])) break; if (_sp > XB_SPIN_CAP) { atomicAdd(&(bar)[XB_TMO], 1u); break; } } } } while (0)
; __device__ __forceinline__ void xcd_barrier(const XcdBarrier& b, const bool leader) {
;     ...
;         const unsigned old = xb_add(&bar[XB_XSUB(b.x)], 1u);
;         const unsigned gen = old / nloc;
;         if (old + 1u == (gen + 1u) * nloc) {
;             __builtin_amdgcn_fence(__ATOMIC_RELEASE, "agent");
;             asm volatile("s_waitcnt vmcnt(0)" ::: "memory");
;             const unsigned og = xb_add(&bar[XB_TOP], 1u);
;             const unsigned tg = og / nx;
;             if (og + 1u == (tg + 1u) * nx) xb_add(&bar[XB_TOPGEN], 1u);
;             else XB_SPIN(xb_ld(&bar[XB_TOPGEN]) == tg, bar);
;             __builtin_amdgcn_fence(__ATOMIC_ACQUIRE, "agent");
;             xb_add(&bar[XB_XGEN(b.x)], 1u);
;             asm volatile("s_waitcnt vmcnt(0)" ::: "memory");
;         } else {
;             XB_SPIN(xb_ld(&bar[XB_XGEN(b.x)]) == gen, bar);
.LBB0_207:
	s_or_b64 exec, exec, s[10:11]
	v_cvt_f32_u32_e32 v6, v4
	s_waitcnt vmcnt(0)
	v_readfirstlane_b32 s1, v5
	v_sub_u32_e32 v5, 0, v4
	v_rcp_iflag_f32_e32 v6, v6
	v_add_u32_e32 v7, s1, v3
	v_mul_f32_e32 v6, 0x4f7ffffe, v6
	v_cvt_u32_f32_e32 v6, v6
	v_mul_lo_u32 v3, v5, v6
	v_mul_hi_u32 v3, v6, v3
	v_add_u32_e32 v3, v6, v3
	v_mul_hi_u32 v3, v7, v3
	v_mul_lo_u32 v5, v3, v4
	v_sub_u32_e32 v5, v7, v5
	v_add_u32_e32 v6, 1, v3
	v_cmp_ge_u32_e32 vcc, v5, v4
	s_nop 1
	v_cndmask_b32_e32 v3, v3, v6, vcc
	v_sub_u32_e32 v6, v5, v4
	v_cndmask_b32_e32 v5, v5, v6, vcc
	v_add_u32_e32 v6, 1, v3
	v_cmp_ge_u32_e32 vcc, v5, v4
	v_add_u32_e32 v5, 1, v7
	s_nop 0
	v_cndmask_b32_e32 v3, v3, v6, vcc
	v_mul_lo_u32 v6, v4, v3
	v_add_u32_e32 v4, v6, v4
	v_cmp_ne_u32_e32 vcc, v5, v4
	s_and_saveexec_b64 s[2:3], vcc
	s_xor_b64 s[8:9], exec, s[2:3]
	s_cbranch_execz .LBB0_221
	buffer_inv sc1
	s_waitcnt lgkmcnt(0)
	v_mov_b32_e32 v2, 0x2000
	s_load_dwordx2 s[16:17], s[90:91], 0xb0
	s_waitcnt lgkmcnt(0)
	s_add_u32 s16, s16, 0x1d79b500
	s_addc_u32 s17, s17, 0
	v_mov_b32_e32 v2, 0
	global_load_dword v2, v2, s[16:17] sc1
	s_waitcnt vmcnt(0)
	v_cmp_eq_u32_e32 vcc, v2, v3
	s_and_saveexec_b64 s[10:11], vcc
	s_cbranch_execz .LBB0_220
	s_add_u32 s14, s12, 0x1d798200
	s_addc_u32 s15, s13, 0
	s_mov_b32 s1, 1
	s_mov_b64 s[18:19], 0
	v_mov_b32_e32 v2, 0
	s_branch .LBB0_211

; __device__ __forceinline__ unsigned xb_ld(unsigned* p)              { return __hip_atomic_load(p, __ATOMIC_RELAXED, __HIP_MEMORY_SCOPE_AGENT); }
; __device__ __forceinline__ unsigned xb_add(unsigned* p, unsigned v) { return __hip_atomic_fetch_add(p, v, __ATOMIC_RELAXED, __HIP_MEMORY_SCOPE_AGENT); }
; #define XB_SPIN(cond, bar) do { unsigned _sp = 0; while (cond) { __builtin_amdgcn_s_sleep(1); \
;     if ((++_sp & 255u) == 0u) { if (xb_ld(&(bar)[XB_TMO])) break; if (_sp > XB_SPIN_CAP) { atomicAdd(&(bar)[XB_TMO], 1u); break; } } } } while (0)
; __device__ __forceinline__ void xcd_barrier(const XcdBarrier& b, const bool leader) {
;     ...
;         if (old + 1u == (gen + 1u) * nloc) {
;             __builtin_amdgcn_fence(__ATOMIC_RELEASE, "agent");
;             asm volatile("s_waitcnt vmcnt(0)" ::: "memory");
;             const unsigned og = xb_add(&bar[XB_TOP], 1u);
;             const unsigned tg = og / nx;
;             if (og + 1u == (tg + 1u) * nx) xb_add(&bar[XB_TOPGEN], 1u);
;             else XB_SPIN(xb_ld(&bar[XB_TOPGEN]) == tg, bar);
;             __builtin_amdgcn_fence(__ATOMIC_ACQUIRE, "agent");
;             xb_add(&bar[XB_XGEN(b.x)], 1u);
;             asm volatile("s_waitcnt vmcnt(0)" ::: "memory");
;         } else {
;             XB_SPIN(xb_ld(&bar[XB_XGEN(b.x)]) == gen, bar);
;             __builtin_amdgcn_fence(__ATOMIC_ACQUIRE, "agent");
;             asm volatile("s_waitcnt vmcnt(0)" ::: "memory");
.LBB0_221:
	s_andn2_saveexec_b64 s[2:3], s[8:9]
	s_cbranch_execz .LBB0_241
	s_mov_b64 s[8:9], exec
	buffer_wbl2 sc1
	buffer_inv sc1
	s_waitcnt lgkmcnt(0)
	s_waitcnt vmcnt(0)
	v_mbcnt_lo_u32_b32 v3, s8, 0
	v_mbcnt_hi_u32_b32 v3, s9, v3
	v_cmp_eq_u32_e32 vcc, 0, v3
	s_and_saveexec_b64 s[10:11], vcc
	s_cbranch_execz .LBB0_224
	s_bcnt1_i32_b64 s1, s[8:9]
	v_mov_b32_e32 v4, 0x1d79b000
	v_mov_b32_e32 v5, s1
	global_atomic_add v4, v4, v5, s[12:13] offset:1024 sc0

; __device__ __forceinline__ unsigned xb_add(unsigned* p, unsigned v) { return __hip_atomic_fetch_add(p, v, __ATOMIC_RELAXED, __HIP_MEMORY_SCOPE_AGENT); }
; __device__ __forceinline__ void xcd_barrier(const XcdBarrier& b, const bool leader) {
;     ...
;             __builtin_amdgcn_fence(__ATOMIC_ACQUIRE, "agent");
;             xb_add(&bar[XB_XGEN(b.x)], 1u);
;             asm volatile("s_waitcnt vmcnt(0)" ::: "memory");
.LBB0_238:
	s_or_b64 exec, exec, s[8:9]
	s_mov_b64 s[8:9], exec
	v_mbcnt_lo_u32_b32 v2, s8, 0
	v_mbcnt_hi_u32_b32 v2, s9, v2
	v_cmp_eq_u32_e32 vcc, 0, v2
	s_waitcnt vmcnt(0)
	s_and_saveexec_b64 s[10:11], vcc
	s_cbranch_execz .LBB0_240
	s_bcnt1_i32_b64 s1, s[8:9]
	v_mov_b32_e32 v2, 0x2000
	v_mov_b32_e32 v3, s1
	global_atomic_add v2, v3, s[6:7] offset:1024
.LBB0_240:
	s_or_b64 exec, exec, s[10:11]
	s_waitcnt vmcnt(0)

; #define PG8_STAGE(bufoff, gbase, voff) do { _Pragma("unroll") for (int _i = 0; _i < 2; ++_i) \
;         __builtin_amdgcn_global_load_lds((const unsigned*)((const char*)(gbase) + (voff)[_i]), (PG8_LAS unsigned*)(lds + (bufoff) + ldsw + _i * 8192), 16, 0, 0); } while (0)
; #define PG8_LDA(dst, b, h) do { _Pragma("unroll") for (int m = 0; m < 4; ++m) _Pragma("unroll") for (int k = 0; k < 2; ++k) dst[m][k] = *(const PG8_LAS bf16x8*)(lds + PG8_SA(b, h) + aoff + m * 2048 + k * 1024); } while (0)
; #define PG8_LDB(dst, b, h) do { _Pragma("unroll") for (int n = 0; n < 2; ++n) _Pragma("unroll") for (int k = 0; k < 2; ++k) dst[n][k] = *(const PG8_LAS bf16x8*)(lds + PG8_SB(b, h) + boff + n * 2048 + k * 1024); } while (0)
; #define PG8_MMA(ai, bj, At, Bt) do { __builtin_amdgcn_s_setprio(1); _Pragma("unroll") for (int m = 0; m < 4; ++m) _Pragma("unroll") for (int n = 0; n < 2; ++n) _Pragma("unroll") for (int k = 0; k < 2; ++k) \
;         acc[ai][bj][m][n] = __builtin_amdgcn_mfma_f32_16x16x32_bf16(Bt[n][k], At[m][k], acc[ai][bj][m][n], 0, 0, 0); __builtin_amdgcn_s_setprio(0); } while (0)
; #define PG8_WAIT_V(n) asm volatile("s_waitcnt vmcnt(" #n ")" ::: "memory")
; template <class Epi, class Sched, bool ALIGN_EPI = false, bool SP2 = false>
; __device__ __forceinline__ void gemm_phase(PG8_LAS unsigned char* lds, const Gemm g, const Sched& S, const Epi& E, const int tid_arg) {
;     ...
;         for (int t = 0; t < nt; t += 2) {
;             const bool last = (t == nt - 2);
;             const char* a1 = cA + (size_t)(t + 1) * kstep;
;             const char* a2 = last ? nA : cA + (size_t)(t + 2) * kstep; const char* b2 = last ? nB : cB + (size_t)(t + 2) * kstep;
;             const char* a3 = a2 + kstep; const char* b3 = b2 + kstep;
;             if (last && has_next) S.a_ready(nxt);
;             if constexpr (SP2) {
;             PG8_LDB(B0, 0, 0); PG8_LDB(B1, 0, 1); PG8_SCHED; PG8_LDA(At, 0, 0); PG8_STAGE(PG8_SA(1, 1), a1 + hstep, voffA);
;             PG8_WAIT_V(8); PG8_WAIT_L(0); PG8_BAR; PG8_MMA(0, 0, At, B0); PG8_MMA(0, 1, At, B1); PG8_BAR; PG8_SCHED;
;     ...
; #pragma unroll
;         for (int a = 0; a < 2; ++a)
; #pragma unroll
;             for (int b = 0; b < 2; ++b)
; #pragma unroll
;                 for (int m = 0; m < 4; ++m)
; #pragma unroll
;                     for (int n = 0; n < 2; ++n) acc[a][b][m][n] = (f32x4){0.f, 0.f, 0.f, 0.f};
.LBB0_259:
	s_add_u32 s16, s36, 0x100
	v_mov_b32_e32 v2, 0
	s_addc_u32 s31, s37, 0
	s_mov_b32 s56, -2
	s_waitcnt lgkmcnt(0)
	v_mov_b32_e32 v3, v2
	v_mov_b32_e32 v4, v2
	v_mov_b32_e32 v5, v2
	v_mov_b32_e32 v6, v2
	v_mov_b32_e32 v7, v2
	v_mov_b32_e32 v8, v2
	v_mov_b32_e32 v9, v2
	v_mov_b32_e32 v18, v2
	v_mov_b32_e32 v19, v2
	v_mov_b32_e32 v20, v2
	v_mov_b32_e32 v21, v2
	v_mov_b32_e32 v22, v2
	v_mov_b32_e32 v23, v2
	v_mov_b32_e32 v24, v2
	v_mov_b32_e32 v25, v2
	v_mov_b32_e32 v34, v2
	v_mov_b32_e32 v35, v2
	v_mov_b32_e32 v36, v2
	v_mov_b32_e32 v37, v2
	v_mov_b32_e32 v38, v2
	v_mov_b32_e32 v39, v2
	v_mov_b32_e32 v40, v2
	v_mov_b32_e32 v41, v2
	v_mov_b32_e32 v50, v2
	v_mov_b32_e32 v51, v2
	v_mov_b32_e32 v52, v2
	v_mov_b32_e32 v53, v2
	v_mov_b32_e32 v54, v2
	v_mov_b32_e32 v55, v2
	v_mov_b32_e32 v56, v2
	v_mov_b32_e32 v57, v2
	v_mov_b32_e32 v10, v2
	v_mov_b32_e32 v11, v2
	v_mov_b32_e32 v12, v2
	v_mov_b32_e32 v13, v2
	v_mov_b32_e32 v14, v2
	v_mov_b32_e32 v15, v2
	v_mov_b32_e32 v16, v2
	v_mov_b32_e32 v17, v2
	v_mov_b32_e32 v26, v2
	v_mov_b32_e32 v27, v2
	v_mov_b32_e32 v28, v2
	v_mov_b32_e32 v29, v2
	v_mov_b32_e32 v30, v2
	v_mov_b32_e32 v31, v2
	v_mov_b32_e32 v32, v2
	v_mov_b32_e32 v33, v2
	v_mov_b32_e32 v42, v2
	v_mov_b32_e32 v43, v2
	v_mov_b32_e32 v44, v2
	v_mov_b32_e32 v45, v2
	v_mov_b32_e32 v46, v2
	v_mov_b32_e32 v47, v2
	v_mov_b32_e32 v48, v2
	v_mov_b32_e32 v49, v2
	v_mov_b32_e32 v58, v2
	v_mov_b32_e32 v59, v2
	v_mov_b32_e32 v60, v2
	v_mov_b32_e32 v61, v2
	v_mov_b32_e32 v62, v2
	v_mov_b32_e32 v63, v2
	v_mov_b32_e32 v64, v2
	v_mov_b32_e32 v65, v2
	v_mov_b32_e32 v66, v2
	v_mov_b32_e32 v67, v2
	v_mov_b32_e32 v68, v2
	v_mov_b32_e32 v69, v2
	v_mov_b32_e32 v70, v2
	v_mov_b32_e32 v71, v2
	v_mov_b32_e32 v72, v2
	v_mov_b32_e32 v73, v2
	v_mov_b32_e32 v82, v2
	v_mov_b32_e32 v83, v2
	v_mov_b32_e32 v84, v2
	v_mov_b32_e32 v85, v2
	v_mov_b32_e32 v86, v2
	v_mov_b32_e32 v87, v2
	v_mov_b32_e32 v88, v2
	v_mov_b32_e32 v89, v2
	v_mov_b32_e32 v98, v2
	v_mov_b32_e32 v99, v2
	v_mov_b32_e32 v100, v2
	v_mov_b32_e32 v101, v2
	v_mov_b32_e32 v102, v2
	v_mov_b32_e32 v103, v2
	v_mov_b32_e32 v104, v2
	v_mov_b32_e32 v105, v2
	v_mov_b32_e32 v114, v2
	v_mov_b32_e32 v115, v2
	v_mov_b32_e32 v116, v2
	v_mov_b32_e32 v117, v2
	v_mov_b32_e32 v118, v2
	v_mov_b32_e32 v119, v2
	v_mov_b32_e32 v120, v2
	v_mov_b32_e32 v121, v2
	v_mov_b32_e32 v74, v2
	v_mov_b32_e32 v75, v2
	v_mov_b32_e32 v76, v2
	v_mov_b32_e32 v77, v2
	v_mov_b32_e32 v78, v2
	v_mov_b32_e32 v79, v2
	v_mov_b32_e32 v80, v2
	v_mov_b32_e32 v81, v2
	v_mov_b32_e32 v90, v2
	v_mov_b32_e32 v91, v2
	v_mov_b32_e32 v92, v2
	v_mov_b32_e32 v93, v2
	v_mov_b32_e32 v94, v2
	v_mov_b32_e32 v95, v2
	v_mov_b32_e32 v96, v2
	v_mov_b32_e32 v97, v2
	v_mov_b32_e32 v106, v2
	v_mov_b32_e32 v107, v2
	v_mov_b32_e32 v108, v2
	v_mov_b32_e32 v109, v2
	v_mov_b32_e32 v110, v2
	v_mov_b32_e32 v111, v2
	v_mov_b32_e32 v112, v2
	v_mov_b32_e32 v113, v2
	v_mov_b32_e32 v122, v2
	v_mov_b32_e32 v123, v2
	v_mov_b32_e32 v124, v2
	v_mov_b32_e32 v125, v2
	v_mov_b32_e32 v126, v2
	v_mov_b32_e32 v127, v2
	v_mov_b32_e32 v128, v2
	v_mov_b32_e32 v129, v2
	s_nop 0
	s_nop 0
	s_nop 0
.LBB0_260:
	ds_read_b128 v[146:149], v162
	ds_read_b128 v[166:169], v162 offset:1024
	ds_read_b128 v[170:173], v162 offset:2048
	ds_read_b128 v[174:177], v162 offset:3072
	ds_read_b128 v[182:185], v163
	ds_read_b128 v[186:189], v163 offset:1024
	ds_read_b128 v[190:193], v163 offset:2048
	ds_read_b128 v[202:205], v163 offset:3072
	s_add_u32 s36, s34, 0x100
	s_addc_u32 s37, s35, 0
	s_cmp_eq_u32 s56, 40
	s_cselect_b32 s41, s13, s37
	s_cselect_b32 s40, s12, s36
	s_cselect_b32 s39, s29, s31
	s_cselect_b32 s38, s28, s16
	v_lshl_add_u64 v[150:151], s[34:35], 0, v[138:139]
	s_add_i32 m0, s43, 0xc000
	ds_read_b128 v[206:209], v164
	ds_read_b128 v[210:213], v164 offset:1024
	ds_read_b128 v[214:217], v164 offset:2048
	ds_read_b128 v[218:221], v164 offset:3072
	ds_read_b128 v[222:225], v164 offset:4096
	ds_read_b128 v[226:229], v164 offset:5120
	ds_read_b128 v[230:233], v164 offset:6144
	ds_read_b128 v[234:237], v164 offset:7168
	global_load_lds_dwordx4 v[150:151], off
	v_lshl_add_u64 v[150:151], s[34:35], 0, v[140:141]
	s_add_i32 m0, s43, 0xe000
	s_nop 0
	global_load_lds_dwordx4 v[150:151], off
	s_waitcnt vmcnt(8)
	s_waitcnt lgkmcnt(0)
	s_barrier
	s_setprio 1
	s_waitcnt lgkmcnt(0)
	v_mfma_f32_16x16x32_bf16 v[126:129], v[146:149], v[206:209], v[126:129]
	v_mfma_f32_16x16x32_bf16 v[122:125], v[170:173], v[206:209], v[122:125]
	v_mfma_f32_16x16x32_bf16 v[110:113], v[146:149], v[214:217], v[110:113]
	v_mfma_f32_16x16x32_bf16 v[106:109], v[170:173], v[214:217], v[106:109]
	v_mfma_f32_16x16x32_bf16 v[94:97], v[146:149], v[222:225], v[94:97]
	v_mfma_f32_16x16x32_bf16 v[90:93], v[170:173], v[222:225], v[90:93]
	v_mfma_f32_16x16x32_bf16 v[78:81], v[146:149], v[230:233], v[78:81]
	v_mfma_f32_16x16x32_bf16 v[74:77], v[170:173], v[230:233], v[74:77]
	v_mfma_f32_16x16x32_bf16 v[126:129], v[166:169], v[210:213], v[126:129]
	v_mfma_f32_16x16x32_bf16 v[122:125], v[174:177], v[210:213], v[122:125]
	v_mfma_f32_16x16x32_bf16 v[110:113], v[166:169], v[218:221], v[110:113]
	v_mfma_f32_16x16x32_bf16 v[106:109], v[174:177], v[218:221], v[106:109]
	v_mfma_f32_16x16x32_bf16 v[94:97], v[166:169], v[226:229], v[94:97]
	v_mfma_f32_16x16x32_bf16 v[90:93], v[174:177], v[226:229], v[90:93]
	v_mfma_f32_16x16x32_bf16 v[78:81], v[166:169], v[234:237], v[78:81]
	v_mfma_f32_16x16x32_bf16 v[74:77], v[174:177], v[234:237], v[74:77]
	s_setprio 0
	s_setprio 1
	v_mfma_f32_16x16x32_bf16 v[118:121], v[182:185], v[206:209], v[118:121]
	v_mfma_f32_16x16x32_bf16 v[114:117], v[190:193], v[206:209], v[114:117]
	v_mfma_f32_16x16x32_bf16 v[102:105], v[182:185], v[214:217], v[102:105]
	v_mfma_f32_16x16x32_bf16 v[98:101], v[190:193], v[214:217], v[98:101]
	v_mfma_f32_16x16x32_bf16 v[86:89], v[182:185], v[222:225], v[86:89]
	v_mfma_f32_16x16x32_bf16 v[82:85], v[190:193], v[222:225], v[82:85]
	v_mfma_f32_16x16x32_bf16 v[70:73], v[182:185], v[230:233], v[70:73]
	v_mfma_f32_16x16x32_bf16 v[66:69], v[190:193], v[230:233], v[66:69]
	v_mfma_f32_16x16x32_bf16 v[118:121], v[186:189], v[210:213], v[118:121]
	v_mfma_f32_16x16x32_bf16 v[114:117], v[202:205], v[210:213], v[114:117]
	v_mfma_f32_16x16x32_bf16 v[102:105], v[186:189], v[218:221], v[102:105]
	v_mfma_f32_16x16x32_bf16 v[98:101], v[202:205], v[218:221], v[98:101]
	v_mfma_f32_16x16x32_bf16 v[86:89], v[186:189], v[226:229], v[86:89]
	v_mfma_f32_16x16x32_bf16 v[82:85], v[202:205], v[226:229], v[82:85]
	v_mfma_f32_16x16x32_bf16 v[70:73], v[186:189], v[234:237], v[70:73]
	v_mfma_f32_16x16x32_bf16 v[66:69], v[202:205], v[234:237], v[66:69]
	s_setprio 0
	s_barrier
; #define PG8_STAGE(bufoff, gbase, voff) do { _Pragma("unroll") for (int _i = 0; _i < 2; ++_i) \
;         __builtin_amdgcn_global_load_lds((const unsigned*)((const char*)(gbase) + (voff)[_i]), (PG8_LAS unsigned*)(lds + (bufoff) + ldsw + _i * 8192), 16, 0, 0); } while (0)
; #define PG8_LDA(dst, b, h) do { _Pragma("unroll") for (int m = 0; m < 4; ++m) _Pragma("unroll") for (int k = 0; k < 2; ++k) dst[m][k] = *(const PG8_LAS bf16x8*)(lds + PG8_SA(b, h) + aoff + m * 2048 + k * 1024); } while (0)
; #define PG8_LDB(dst, b, h) do { _Pragma("unroll") for (int n = 0; n < 2; ++n) _Pragma("unroll") for (int k = 0; k < 2; ++k) dst[n][k] = *(const PG8_LAS bf16x8*)(lds + PG8_SB(b, h) + boff + n * 2048 + k * 1024); } while (0)
; #define PG8_MMA(ai, bj, At, Bt) do { __builtin_amdgcn_s_setprio(1); _Pragma("unroll") for (int m = 0; m < 4; ++m) _Pragma("unroll") for (int n = 0; n < 2; ++n) _Pragma("unroll") for (int k = 0; k < 2; ++k) \
;         acc[ai][bj][m][n] = __builtin_amdgcn_mfma_f32_16x16x32_bf16(Bt[n][k], At[m][k], acc[ai][bj][m][n], 0, 0, 0); __builtin_amdgcn_s_setprio(0); } while (0)
; #define PG8_WAIT_V(n) asm volatile("s_waitcnt vmcnt(" #n ")" ::: "memory")
; #define PG8_WAIT_L(n) asm volatile("s_waitcnt lgkmcnt(" #n ")" ::: "memory")
; #define PG8_BAR __builtin_amdgcn_s_barrier()
; #define PG8_SCHED __builtin_amdgcn_sched_barrier(0)
; template <class Epi, class Sched, bool ALIGN_EPI = false, bool SP2 = false>
; __device__ __forceinline__ void gemm_phase(PG8_LAS unsigned char* lds, const Gemm g, const Sched& S, const Epi& E, const int tid_arg) {
;     ...
;             PG8_LDA(At, 0, 1); PG8_STAGE(PG8_SB(0, 0), b2, voffB); PG8_STAGE(PG8_SB(0, 1), b2 + hstep, voffB); PG8_STAGE(PG8_SA(0, 0), a2, voffA);
;             PG8_WAIT_V(8); PG8_WAIT_L(0); PG8_BAR; PG8_MMA(1, 0, At, B0); PG8_MMA(1, 1, At, B1); PG8_BAR; PG8_SCHED;
;             PG8_LDB(B0, 1, 0); PG8_LDB(B1, 1, 1); PG8_SCHED; PG8_LDA(At, 1, 0); PG8_STAGE(PG8_SA(0, 1), a2 + hstep, voffA);
;             PG8_WAIT_V(8); PG8_WAIT_L(0); PG8_BAR; PG8_MMA(0, 0, At, B0); PG8_MMA(0, 1, At, B1); PG8_BAR; PG8_SCHED;
	s_add_i32 s34, s50, s42
	v_lshl_add_u64 v[150:151], s[38:39], 0, v[132:133]
	s_mov_b32 m0, s34
	ds_read_b128 v[206:209], v164 offset:16384
	ds_read_b128 v[210:213], v164 offset:17408
	ds_read_b128 v[214:217], v164 offset:18432
	ds_read_b128 v[218:221], v164 offset:19456
	ds_read_b128 v[222:225], v164 offset:20480
	ds_read_b128 v[226:229], v164 offset:21504
	ds_read_b128 v[230:233], v164 offset:22528
	ds_read_b128 v[234:237], v164 offset:23552
	global_load_lds_dwordx4 v[150:151], off
	s_add_i32 m0, s34, 0x2000
	s_add_u32 s34, s38, 0xb0000
	v_lshl_add_u64 v[178:179], s[38:39], 0, v[136:137]
	s_addc_u32 s35, s39, 0
	s_add_i32 s57, s51, s42
	global_load_lds_dwordx4 v[178:179], off
	v_lshl_add_u64 v[194:195], s[34:35], 0, v[132:133]
	s_mov_b32 m0, s57
	v_lshl_add_u64 v[238:239], s[40:41], 0, v[134:135]
	global_load_lds_dwordx4 v[194:195], off
	v_lshl_add_u64 v[194:195], s[34:35], 0, v[136:137]
	s_add_i32 m0, s57, 0x2000
	s_nop 0
	global_load_lds_dwordx4 v[194:195], off
	v_lshl_add_u64 v[194:195], s[40:41], 0, v[130:131]
	s_mov_b32 m0, s43
	s_nop 0
	global_load_lds_dwordx4 v[194:195], off
	s_mov_b32 m0, s44
	s_nop 0
	global_load_lds_dwordx4 v[238:239], off
	s_waitcnt vmcnt(8)
	s_waitcnt lgkmcnt(0)
	s_barrier
	s_setprio 1
	s_waitcnt lgkmcnt(0)
	v_mfma_f32_16x16x32_bf16 v[62:65], v[146:149], v[206:209], v[62:65]
	v_mfma_f32_16x16x32_bf16 v[58:61], v[170:173], v[206:209], v[58:61]
	v_mfma_f32_16x16x32_bf16 v[46:49], v[146:149], v[214:217], v[46:49]
	v_mfma_f32_16x16x32_bf16 v[42:45], v[170:173], v[214:217], v[42:45]
	v_mfma_f32_16x16x32_bf16 v[30:33], v[146:149], v[222:225], v[30:33]
	v_mfma_f32_16x16x32_bf16 v[26:29], v[170:173], v[222:225], v[26:29]
	v_mfma_f32_16x16x32_bf16 v[14:17], v[146:149], v[230:233], v[14:17]
	v_mfma_f32_16x16x32_bf16 v[10:13], v[170:173], v[230:233], v[10:13]
	v_mfma_f32_16x16x32_bf16 v[62:65], v[166:169], v[210:213], v[62:65]
	v_mfma_f32_16x16x32_bf16 v[58:61], v[174:177], v[210:213], v[58:61]
	v_mfma_f32_16x16x32_bf16 v[46:49], v[166:169], v[218:221], v[46:49]
	v_mfma_f32_16x16x32_bf16 v[42:45], v[174:177], v[218:221], v[42:45]
	v_mfma_f32_16x16x32_bf16 v[30:33], v[166:169], v[226:229], v[30:33]
	v_mfma_f32_16x16x32_bf16 v[26:29], v[174:177], v[226:229], v[26:29]
	v_mfma_f32_16x16x32_bf16 v[14:17], v[166:169], v[234:237], v[14:17]
	v_mfma_f32_16x16x32_bf16 v[10:13], v[174:177], v[234:237], v[10:13]
	s_setprio 0
	s_setprio 1
	v_mfma_f32_16x16x32_bf16 v[54:57], v[182:185], v[206:209], v[54:57]
	v_mfma_f32_16x16x32_bf16 v[50:53], v[190:193], v[206:209], v[50:53]
	v_mfma_f32_16x16x32_bf16 v[38:41], v[182:185], v[214:217], v[38:41]
	v_mfma_f32_16x16x32_bf16 v[34:37], v[190:193], v[214:217], v[34:37]
	v_mfma_f32_16x16x32_bf16 v[22:25], v[182:185], v[222:225], v[22:25]
	v_mfma_f32_16x16x32_bf16 v[18:21], v[190:193], v[222:225], v[18:21]
	v_mfma_f32_16x16x32_bf16 v[6:9], v[182:185], v[230:233], v[6:9]
	v_mfma_f32_16x16x32_bf16 v[2:5], v[190:193], v[230:233], v[2:5]
	v_mfma_f32_16x16x32_bf16 v[54:57], v[186:189], v[210:213], v[54:57]
	v_mfma_f32_16x16x32_bf16 v[50:53], v[202:205], v[210:213], v[50:53]
	v_mfma_f32_16x16x32_bf16 v[38:41], v[186:189], v[218:221], v[38:41]
	v_mfma_f32_16x16x32_bf16 v[34:37], v[202:205], v[218:221], v[34:37]
	v_mfma_f32_16x16x32_bf16 v[22:25], v[186:189], v[226:229], v[22:25]
	v_mfma_f32_16x16x32_bf16 v[18:21], v[202:205], v[226:229], v[18:21]
	v_mfma_f32_16x16x32_bf16 v[6:9], v[186:189], v[234:237], v[6:9]
	v_mfma_f32_16x16x32_bf16 v[2:5], v[202:205], v[234:237], v[2:5]
	s_setprio 0
	s_barrier
	s_add_i32 s57, 0, 0x18000
	v_add_u32_e32 v165, s57, v153
	s_add_i32 s58, 0, 0x1c000
	ds_read_b128 v[146:149], v165
	ds_read_b128 v[166:169], v165 offset:1024
	ds_read_b128 v[170:173], v165 offset:2048
	ds_read_b128 v[174:177], v165 offset:3072
	v_add_u32_e32 v165, s58, v153
	ds_read_b128 v[182:185], v165
	ds_read_b128 v[186:189], v165 offset:1024
	ds_read_b128 v[190:193], v165 offset:2048
	ds_read_b128 v[202:205], v165 offset:3072
	s_add_u32 s34, s40, 0xb0000
	s_addc_u32 s35, s41, 0
	s_mov_b32 m0, s45
	v_lshl_add_u64 v[240:241], s[34:35], 0, v[130:131]
	ds_read_b128 v[206:209], v164 offset:32768
	ds_read_b128 v[210:213], v164 offset:33792
	ds_read_b128 v[214:217], v164 offset:34816
	ds_read_b128 v[218:221], v164 offset:35840
	ds_read_b128 v[222:225], v164 offset:36864
	ds_read_b128 v[226:229], v164 offset:37888
	ds_read_b128 v[230:233], v164 offset:38912
	ds_read_b128 v[234:237], v164 offset:39936
	global_load_lds_dwordx4 v[240:241], off
	v_lshl_add_u64 v[240:241], s[34:35], 0, v[134:135]
	s_mov_b32 m0, s46
	s_nop 0
	global_load_lds_dwordx4 v[240:241], off
	s_waitcnt vmcnt(8)
	s_waitcnt lgkmcnt(0)
	s_barrier
; #define PG8_STAGE(bufoff, gbase, voff) do { _Pragma("unroll") for (int _i = 0; _i < 2; ++_i) \
;         __builtin_amdgcn_global_load_lds((const unsigned*)((const char*)(gbase) + (voff)[_i]), (PG8_LAS unsigned*)(lds + (bufoff) + ldsw + _i * 8192), 16, 0, 0); } while (0)
; #define PG8_LDA(dst, b, h) do { _Pragma("unroll") for (int m = 0; m < 4; ++m) _Pragma("unroll") for (int k = 0; k < 2; ++k) dst[m][k] = *(const PG8_LAS bf16x8*)(lds + PG8_SA(b, h) + aoff + m * 2048 + k * 1024); } while (0)
; #define PG8_MMA(ai, bj, At, Bt) do { __builtin_amdgcn_s_setprio(1); _Pragma("unroll") for (int m = 0; m < 4; ++m) _Pragma("unroll") for (int n = 0; n < 2; ++n) _Pragma("unroll") for (int k = 0; k < 2; ++k) \
;         acc[ai][bj][m][n] = __builtin_amdgcn_mfma_f32_16x16x32_bf16(Bt[n][k], At[m][k], acc[ai][bj][m][n], 0, 0, 0); __builtin_amdgcn_s_setprio(0); } while (0)
; #define PG8_WAIT_V(n) asm volatile("s_waitcnt vmcnt(" #n ")" ::: "memory")
; #define PG8_WAIT_L(n) asm volatile("s_waitcnt lgkmcnt(" #n ")" ::: "memory")
; #define PG8_BAR __builtin_amdgcn_s_barrier()
; #define PG8_SCHED __builtin_amdgcn_sched_barrier(0)
;     __device__ __forceinline__ void operator()(const f32x4 (&acc)[2][2][4][2], const Unit& u, int wr, int wc, int fr, int fq) const {
;         const float* base = (u.pm < split_pm) ? base0 + (size_t)u.pm * BM * 1024 : base1 + (size_t)(u.pm - split_pm) * BM * 1024;
; template <class Epi, class Sched, bool ALIGN_EPI = false, bool SP2 = false>
; __device__ __forceinline__ void gemm_phase(PG8_LAS unsigned char* lds, const Gemm g, const Sched& S, const Epi& E, const int tid_arg) {
;     ...
;             PG8_WAIT_V(8); PG8_WAIT_L(0); PG8_BAR; PG8_MMA(0, 0, At, B0); PG8_MMA(0, 1, At, B1); PG8_BAR; PG8_SCHED;
;             PG8_LDA(At, 1, 1); PG8_STAGE(PG8_SB(1, 0), b3, voffB); PG8_STAGE(PG8_SB(1, 1), b3 + hstep, voffB); PG8_STAGE(PG8_SA(1, 0), a3, voffA);
;             PG8_WAIT_V(8); PG8_WAIT_L(0); PG8_BAR; PG8_MMA(1, 0, At, B0); PG8_MMA(1, 1, At, B1); PG8_BAR; PG8_SCHED;
	s_setprio 1
	s_waitcnt lgkmcnt(0)
	v_mfma_f32_16x16x32_bf16 v[126:129], v[146:149], v[206:209], v[126:129]
	v_mfma_f32_16x16x32_bf16 v[122:125], v[170:173], v[206:209], v[122:125]
	v_mfma_f32_16x16x32_bf16 v[110:113], v[146:149], v[214:217], v[110:113]
	v_mfma_f32_16x16x32_bf16 v[106:109], v[170:173], v[214:217], v[106:109]
	v_mfma_f32_16x16x32_bf16 v[94:97], v[146:149], v[222:225], v[94:97]
	v_mfma_f32_16x16x32_bf16 v[90:93], v[170:173], v[222:225], v[90:93]
	v_mfma_f32_16x16x32_bf16 v[78:81], v[146:149], v[230:233], v[78:81]
	v_mfma_f32_16x16x32_bf16 v[74:77], v[170:173], v[230:233], v[74:77]
	v_mfma_f32_16x16x32_bf16 v[126:129], v[166:169], v[210:213], v[126:129]
	v_mfma_f32_16x16x32_bf16 v[122:125], v[174:177], v[210:213], v[122:125]
	v_mfma_f32_16x16x32_bf16 v[110:113], v[166:169], v[218:221], v[110:113]
	v_mfma_f32_16x16x32_bf16 v[106:109], v[174:177], v[218:221], v[106:109]
	v_mfma_f32_16x16x32_bf16 v[94:97], v[166:169], v[226:229], v[94:97]
	v_mfma_f32_16x16x32_bf16 v[90:93], v[174:177], v[226:229], v[90:93]
	v_mfma_f32_16x16x32_bf16 v[78:81], v[166:169], v[234:237], v[78:81]
	v_mfma_f32_16x16x32_bf16 v[74:77], v[174:177], v[234:237], v[74:77]
	s_setprio 0
	s_setprio 1
	v_mfma_f32_16x16x32_bf16 v[118:121], v[182:185], v[206:209], v[118:121]
	v_mfma_f32_16x16x32_bf16 v[114:117], v[190:193], v[206:209], v[114:117]
	v_mfma_f32_16x16x32_bf16 v[102:105], v[182:185], v[214:217], v[102:105]
	v_mfma_f32_16x16x32_bf16 v[98:101], v[190:193], v[214:217], v[98:101]
	v_mfma_f32_16x16x32_bf16 v[86:89], v[182:185], v[222:225], v[86:89]
	v_mfma_f32_16x16x32_bf16 v[82:85], v[190:193], v[222:225], v[82:85]
	v_mfma_f32_16x16x32_bf16 v[70:73], v[182:185], v[230:233], v[70:73]
	v_mfma_f32_16x16x32_bf16 v[66:69], v[190:193], v[230:233], v[66:69]
	v_mfma_f32_16x16x32_bf16 v[118:121], v[186:189], v[210:213], v[118:121]
	v_mfma_f32_16x16x32_bf16 v[114:117], v[202:205], v[210:213], v[114:117]
	v_mfma_f32_16x16x32_bf16 v[102:105], v[186:189], v[218:221], v[102:105]
	v_mfma_f32_16x16x32_bf16 v[98:101], v[202:205], v[218:221], v[98:101]
	v_mfma_f32_16x16x32_bf16 v[86:89], v[186:189], v[226:229], v[86:89]
	v_mfma_f32_16x16x32_bf16 v[82:85], v[202:205], v[226:229], v[82:85]
	v_mfma_f32_16x16x32_bf16 v[70:73], v[186:189], v[234:237], v[70:73]
	v_mfma_f32_16x16x32_bf16 v[66:69], v[202:205], v[234:237], v[66:69]
	s_setprio 0
	s_barrier
	s_add_i32 s34, s57, s42
	v_lshl_add_u64 v[150:151], v[150:151], 0, s[24:25]
	s_mov_b32 m0, s34
	ds_read_b128 v[206:209], v164 offset:49152
	ds_read_b128 v[210:213], v164 offset:50176
	ds_read_b128 v[214:217], v164 offset:51200
	ds_read_b128 v[218:221], v164 offset:52224
	ds_read_b128 v[222:225], v164 offset:53248
	ds_read_b128 v[226:229], v164 offset:54272
	ds_read_b128 v[230:233], v164 offset:55296
	ds_read_b128 v[234:237], v164 offset:56320
	global_load_lds_dwordx4 v[150:151], off
	s_add_i32 m0, s34, 0x2000
	s_add_u32 s34, s38, 0xb0080
	v_lshl_add_u64 v[150:151], v[178:179], 0, s[24:25]
	s_addc_u32 s35, s39, 0
	s_add_i32 s38, s58, s42
	global_load_lds_dwordx4 v[150:151], off
	v_lshl_add_u64 v[150:151], s[34:35], 0, v[132:133]
	s_mov_b32 m0, s38
	s_nop 0
	global_load_lds_dwordx4 v[150:151], off
	v_lshl_add_u64 v[150:151], s[34:35], 0, v[136:137]
	s_add_i32 m0, s38, 0x2000
	s_nop 0
	global_load_lds_dwordx4 v[150:151], off
	v_lshl_add_u64 v[150:151], v[194:195], 0, s[24:25]
	s_mov_b32 m0, s48
	s_nop 0
	global_load_lds_dwordx4 v[150:151], off
	v_lshl_add_u64 v[150:151], v[238:239], 0, s[24:25]
	s_mov_b32 m0, s49
	s_nop 0
	global_load_lds_dwordx4 v[150:151], off
	s_waitcnt vmcnt(8)
	s_waitcnt lgkmcnt(0)
	s_barrier
	s_setprio 1
	s_waitcnt lgkmcnt(0)
	v_mfma_f32_16x16x32_bf16 v[62:65], v[146:149], v[206:209], v[62:65]
	v_mfma_f32_16x16x32_bf16 v[58:61], v[170:173], v[206:209], v[58:61]
	v_mfma_f32_16x16x32_bf16 v[46:49], v[146:149], v[214:217], v[46:49]
	v_mfma_f32_16x16x32_bf16 v[42:45], v[170:173], v[214:217], v[42:45]
	v_mfma_f32_16x16x32_bf16 v[30:33], v[146:149], v[222:225], v[30:33]
	v_mfma_f32_16x16x32_bf16 v[26:29], v[170:173], v[222:225], v[26:29]
	v_mfma_f32_16x16x32_bf16 v[14:17], v[146:149], v[230:233], v[14:17]
	v_mfma_f32_16x16x32_bf16 v[10:13], v[170:173], v[230:233], v[10:13]
	v_mfma_f32_16x16x32_bf16 v[62:65], v[166:169], v[210:213], v[62:65]
	v_mfma_f32_16x16x32_bf16 v[58:61], v[174:177], v[210:213], v[58:61]
	v_mfma_f32_16x16x32_bf16 v[46:49], v[166:169], v[218:221], v[46:49]
	v_mfma_f32_16x16x32_bf16 v[42:45], v[174:177], v[218:221], v[42:45]
	v_mfma_f32_16x16x32_bf16 v[30:33], v[166:169], v[226:229], v[30:33]
	v_mfma_f32_16x16x32_bf16 v[26:29], v[174:177], v[226:229], v[26:29]
	v_mfma_f32_16x16x32_bf16 v[14:17], v[166:169], v[234:237], v[14:17]
	v_mfma_f32_16x16x32_bf16 v[10:13], v[174:177], v[234:237], v[10:13]
	s_setprio 0
	s_setprio 1
	v_mfma_f32_16x16x32_bf16 v[54:57], v[182:185], v[206:209], v[54:57]
	v_mfma_f32_16x16x32_bf16 v[50:53], v[190:193], v[206:209], v[50:53]
	v_mfma_f32_16x16x32_bf16 v[38:41], v[182:185], v[214:217], v[38:41]
	v_mfma_f32_16x16x32_bf16 v[34:37], v[190:193], v[214:217], v[34:37]
	v_mfma_f32_16x16x32_bf16 v[22:25], v[182:185], v[222:225], v[22:25]
	v_mfma_f32_16x16x32_bf16 v[18:21], v[190:193], v[222:225], v[18:21]
	v_mfma_f32_16x16x32_bf16 v[6:9], v[182:185], v[230:233], v[6:9]
	v_mfma_f32_16x16x32_bf16 v[2:5], v[190:193], v[230:233], v[2:5]
	v_mfma_f32_16x16x32_bf16 v[54:57], v[186:189], v[210:213], v[54:57]
	v_mfma_f32_16x16x32_bf16 v[50:53], v[202:205], v[210:213], v[50:53]
	v_mfma_f32_16x16x32_bf16 v[38:41], v[186:189], v[218:221], v[38:41]
	v_mfma_f32_16x16x32_bf16 v[34:37], v[202:205], v[218:221], v[34:37]
	v_mfma_f32_16x16x32_bf16 v[22:25], v[186:189], v[226:229], v[22:25]
	v_mfma_f32_16x16x32_bf16 v[18:21], v[202:205], v[226:229], v[18:21]
	v_mfma_f32_16x16x32_bf16 v[6:9], v[186:189], v[234:237], v[6:9]
	v_mfma_f32_16x16x32_bf16 v[2:5], v[202:205], v[234:237], v[2:5]
	s_setprio 0
	s_barrier
	s_add_i32 s56, s56, 2
	s_add_u32 s16, s16, 0x100
	s_addc_u32 s31, s31, 0
	s_cmp_gt_u32 s56, 41
	s_mov_b64 s[34:35], s[36:37]
	s_cbranch_scc0 .LBB0_260
	s_and_b64 vcc, exec, s[26:27]
	s_cbranch_vccz .LBB0_284
	s_barrier
	s_cmpk_gt_i32 s30, 0x7f
	s_mov_b64 s[36:37], -1
	s_cbranch_scc1 .LBB0_285

; __device__ __forceinline__ unsigned xb_ld(unsigned* p)              { return __hip_atomic_load(p, __ATOMIC_RELAXED, __HIP_MEMORY_SCOPE_AGENT); }
; __device__ __forceinline__ unsigned xb_add(unsigned* p, unsigned v) { return __hip_atomic_fetch_add(p, v, __ATOMIC_RELAXED, __HIP_MEMORY_SCOPE_AGENT); }
; #define XB_SPIN(cond, bar) do { unsigned _sp = 0; while (cond) { __builtin_amdgcn_s_sleep(1); \
;     if ((++_sp & 255u) == 0u) { if (xb_ld(&(bar)[XB_TMO])) break; if (_sp > XB_SPIN_CAP) { atomicAdd(&(bar)[XB_TMO], 1u); break; } } } } while (0)
; __device__ __forceinline__ void xcd_barrier(const XcdBarrier& b, const bool leader) {
;     ...
;         const unsigned old = xb_add(&bar[XB_XSUB(b.x)], 1u);
;         const unsigned gen = old / nloc;
;         if (old + 1u == (gen + 1u) * nloc) {
;             __builtin_amdgcn_fence(__ATOMIC_RELEASE, "agent");
;             asm volatile("s_waitcnt vmcnt(0)" ::: "memory");
;             const unsigned og = xb_add(&bar[XB_TOP], 1u);
;             const unsigned tg = og / nx;
;             if (og + 1u == (tg + 1u) * nx) xb_add(&bar[XB_TOPGEN], 1u);
;             else XB_SPIN(xb_ld(&bar[XB_TOPGEN]) == tg, bar);
;             __builtin_amdgcn_fence(__ATOMIC_ACQUIRE, "agent");
;             xb_add(&bar[XB_XGEN(b.x)], 1u);
;             asm volatile("s_waitcnt vmcnt(0)" ::: "memory");
;         } else {
;             XB_SPIN(xb_ld(&bar[XB_XGEN(b.x)]) == gen, bar);
.LBB0_310:
	s_or_b64 exec, exec, s[12:13]
	v_cvt_f32_u32_e32 v6, v4
	s_waitcnt vmcnt(0)
	v_readfirstlane_b32 s1, v5
	v_sub_u32_e32 v5, 0, v4
	v_rcp_iflag_f32_e32 v6, v6
	v_add_u32_e32 v7, s1, v3
	v_mul_f32_e32 v6, 0x4f7ffffe, v6
	v_cvt_u32_f32_e32 v6, v6
	v_mul_lo_u32 v3, v5, v6
	v_mul_hi_u32 v3, v6, v3
	v_add_u32_e32 v3, v6, v3
	v_mul_hi_u32 v3, v7, v3
	v_mul_lo_u32 v5, v3, v4
	v_sub_u32_e32 v5, v7, v5
	v_add_u32_e32 v6, 1, v3
	v_cmp_ge_u32_e32 vcc, v5, v4
	s_nop 1
	v_cndmask_b32_e32 v3, v3, v6, vcc
	v_sub_u32_e32 v6, v5, v4
	v_cndmask_b32_e32 v5, v5, v6, vcc
	v_add_u32_e32 v6, 1, v3
	v_cmp_ge_u32_e32 vcc, v5, v4
	v_add_u32_e32 v5, 1, v7
	s_nop 0
	v_cndmask_b32_e32 v3, v3, v6, vcc
	v_mul_lo_u32 v6, v4, v3
	v_add_u32_e32 v4, v6, v4
	v_cmp_ne_u32_e32 vcc, v5, v4
	s_and_saveexec_b64 s[2:3], vcc
	s_xor_b64 s[10:11], exec, s[2:3]
	s_cbranch_execz .LBB0_324
	buffer_inv sc1
	s_waitcnt lgkmcnt(0)
	v_mov_b32_e32 v2, 0x2000
	s_load_dwordx2 s[16:17], s[90:91], 0xb0
	s_waitcnt lgkmcnt(0)
	s_add_u32 s16, s16, 0x1d79b500
	s_addc_u32 s17, s17, 0
	v_mov_b32_e32 v2, 0
	global_load_dword v2, v2, s[16:17] sc1
	s_waitcnt vmcnt(0)
	v_cmp_eq_u32_e32 vcc, v2, v3
	s_and_saveexec_b64 s[12:13], vcc
	s_cbranch_execz .LBB0_323
	s_add_u32 s14, s4, 0x1d798200
	s_addc_u32 s15, s5, 0
	s_mov_b32 s1, 1
	s_mov_b64 s[18:19], 0
	v_mov_b32_e32 v2, 0
	s_branch .LBB0_314

; __device__ __forceinline__ unsigned xb_ld(unsigned* p)              { return __hip_atomic_load(p, __ATOMIC_RELAXED, __HIP_MEMORY_SCOPE_AGENT); }
; __device__ __forceinline__ unsigned xb_add(unsigned* p, unsigned v) { return __hip_atomic_fetch_add(p, v, __ATOMIC_RELAXED, __HIP_MEMORY_SCOPE_AGENT); }
; #define XB_SPIN(cond, bar) do { unsigned _sp = 0; while (cond) { __builtin_amdgcn_s_sleep(1); \
;     if ((++_sp & 255u) == 0u) { if (xb_ld(&(bar)[XB_TMO])) break; if (_sp > XB_SPIN_CAP) { atomicAdd(&(bar)[XB_TMO], 1u); break; } } } } while (0)
; __device__ __forceinline__ void xcd_barrier(const XcdBarrier& b, const bool leader) {
;     ...
;         if (old + 1u == (gen + 1u) * nloc) {
;             __builtin_amdgcn_fence(__ATOMIC_RELEASE, "agent");
;             asm volatile("s_waitcnt vmcnt(0)" ::: "memory");
;             const unsigned og = xb_add(&bar[XB_TOP], 1u);
;             const unsigned tg = og / nx;
;             if (og + 1u == (tg + 1u) * nx) xb_add(&bar[XB_TOPGEN], 1u);
;             else XB_SPIN(xb_ld(&bar[XB_TOPGEN]) == tg, bar);
;             __builtin_amdgcn_fence(__ATOMIC_ACQUIRE, "agent");
;             xb_add(&bar[XB_XGEN(b.x)], 1u);
;             asm volatile("s_waitcnt vmcnt(0)" ::: "memory");
;         } else {
;             XB_SPIN(xb_ld(&bar[XB_XGEN(b.x)]) == gen, bar);
;             __builtin_amdgcn_fence(__ATOMIC_ACQUIRE, "agent");
;             asm volatile("s_waitcnt vmcnt(0)" ::: "memory");
.LBB0_324:
	s_andn2_saveexec_b64 s[2:3], s[10:11]
	s_cbranch_execz .LBB0_344
	s_mov_b64 s[10:11], exec
	buffer_wbl2 sc1
	buffer_inv sc1
	s_waitcnt lgkmcnt(0)
	s_waitcnt vmcnt(0)
	v_mbcnt_lo_u32_b32 v3, s10, 0
	v_mbcnt_hi_u32_b32 v3, s11, v3
	v_cmp_eq_u32_e32 vcc, 0, v3
	s_and_saveexec_b64 s[12:13], vcc
	s_cbranch_execz .LBB0_327
	s_bcnt1_i32_b64 s1, s[10:11]
	v_mov_b32_e32 v4, 0x1d79b000
	v_mov_b32_e32 v5, s1
	global_atomic_add v4, v4, v5, s[4:5] offset:1024 sc0

; __device__ __forceinline__ unsigned xb_add(unsigned* p, unsigned v) { return __hip_atomic_fetch_add(p, v, __ATOMIC_RELAXED, __HIP_MEMORY_SCOPE_AGENT); }
; __device__ __forceinline__ void xcd_barrier(const XcdBarrier& b, const bool leader) {
;     ...
;             __builtin_amdgcn_fence(__ATOMIC_ACQUIRE, "agent");
;             xb_add(&bar[XB_XGEN(b.x)], 1u);
;             asm volatile("s_waitcnt vmcnt(0)" ::: "memory");
.LBB0_341:
	s_or_b64 exec, exec, s[4:5]
	s_mov_b64 s[4:5], exec
	v_mbcnt_lo_u32_b32 v2, s4, 0
	v_mbcnt_hi_u32_b32 v2, s5, v2
	v_cmp_eq_u32_e32 vcc, 0, v2
	s_waitcnt vmcnt(0)
	s_and_saveexec_b64 s[10:11], vcc
	s_cbranch_execz .LBB0_343
	s_bcnt1_i32_b64 s1, s[4:5]
	v_mov_b32_e32 v2, 0x2000
	v_mov_b32_e32 v3, s1
	global_atomic_add v2, v3, s[8:9] offset:1024
.LBB0_343:
	s_or_b64 exec, exec, s[10:11]
	s_waitcnt vmcnt(0)

; #define PG8_STAGE(bufoff, gbase, voff) do { _Pragma("unroll") for (int _i = 0; _i < 2; ++_i) \
;         __builtin_amdgcn_global_load_lds((const unsigned*)((const char*)(gbase) + (voff)[_i]), (PG8_LAS unsigned*)(lds + (bufoff) + ldsw + _i * 8192), 16, 0, 0); } while (0)
; #define PG8_LDA(dst, b, h) do { _Pragma("unroll") for (int m = 0; m < 4; ++m) _Pragma("unroll") for (int k = 0; k < 2; ++k) dst[m][k] = *(const PG8_LAS bf16x8*)(lds + PG8_SA(b, h) + aoff + m * 2048 + k * 1024); } while (0)
; #define PG8_LDB(dst, b, h) do { _Pragma("unroll") for (int n = 0; n < 2; ++n) _Pragma("unroll") for (int k = 0; k < 2; ++k) dst[n][k] = *(const PG8_LAS bf16x8*)(lds + PG8_SB(b, h) + boff + n * 2048 + k * 1024); } while (0)
; #define PG8_MMA(ai, bj, At, Bt) do { __builtin_amdgcn_s_setprio(1); _Pragma("unroll") for (int m = 0; m < 4; ++m) _Pragma("unroll") for (int n = 0; n < 2; ++n) _Pragma("unroll") for (int k = 0; k < 2; ++k) \
;         acc[ai][bj][m][n] = __builtin_amdgcn_mfma_f32_16x16x32_bf16(Bt[n][k], At[m][k], acc[ai][bj][m][n], 0, 0, 0); __builtin_amdgcn_s_setprio(0); } while (0)
; #define PG8_WAIT_V(n) asm volatile("s_waitcnt vmcnt(" #n ")" ::: "memory")
; template <class Epi, class Sched, bool ALIGN_EPI = false, bool SP2 = false>
; __device__ __forceinline__ void gemm_phase(PG8_LAS unsigned char* lds, const Gemm g, const Sched& S, const Epi& E, const int tid_arg) {
;     ...
;         for (int t = 0; t < nt; t += 2) {
;             const bool last = (t == nt - 2);
;             const char* a1 = cA + (size_t)(t + 1) * kstep;
;             const char* a2 = last ? nA : cA + (size_t)(t + 2) * kstep; const char* b2 = last ? nB : cB + (size_t)(t + 2) * kstep;
;             const char* a3 = a2 + kstep; const char* b3 = b2 + kstep;
;             if (last && has_next) S.a_ready(nxt);
;             if constexpr (SP2) {
;             PG8_LDB(B0, 0, 0); PG8_LDB(B1, 0, 1); PG8_SCHED; PG8_LDA(At, 0, 0); PG8_STAGE(PG8_SA(1, 1), a1 + hstep, voffA);
;             PG8_WAIT_V(8); PG8_WAIT_L(0); PG8_BAR; PG8_MMA(0, 0, At, B0); PG8_MMA(0, 1, At, B1); PG8_BAR; PG8_SCHED;
;     ...
; #pragma unroll
;         for (int a = 0; a < 2; ++a)
; #pragma unroll
;             for (int b = 0; b < 2; ++b)
; #pragma unroll
;                 for (int m = 0; m < 4; ++m)
; #pragma unroll
;                     for (int n = 0; n < 2; ++n) acc[a][b][m][n] = (f32x4){0.f, 0.f, 0.f, 0.f};
.LBB0_362:
	s_ashr_i32 s29, s28, 31
	s_lshl_b64 s[6:7], s[28:29], 19
	s_add_u32 s30, s50, s6
	s_addc_u32 s31, s51, s7
	s_and_b64 s[6:7], s[8:9], exec
	s_cselect_b32 s6, s31, s15
	s_cselect_b32 s7, s30, s14
	s_ashr_i32 s27, s26, 31
	s_lshl_b64 s[34:35], s[26:27], 19
	s_add_u32 s34, s52, s34
	s_addc_u32 s35, s53, s35
	s_and_b64 s[38:39], s[8:9], exec
	s_cselect_b32 s11, s35, s37
	s_cselect_b32 s13, s34, s36
	s_add_u32 s14, s14, 0x40080
	s_addc_u32 s15, s15, 0
	s_add_u32 s27, s36, 0x100
	v_mov_b32_e32 v4, 0
	s_addc_u32 s29, s37, 0
	s_mov_b32 s40, -2
	v_mov_b32_e32 v5, v4
	v_mov_b32_e32 v6, v4
	v_mov_b32_e32 v7, v4
	v_mov_b32_e32 v8, v4
	v_mov_b32_e32 v9, v4
	v_mov_b32_e32 v10, v4
	v_mov_b32_e32 v11, v4
	v_mov_b32_e32 v20, v4
	v_mov_b32_e32 v21, v4
	v_mov_b32_e32 v22, v4
	v_mov_b32_e32 v23, v4
	v_mov_b32_e32 v24, v4
	v_mov_b32_e32 v25, v4
	v_mov_b32_e32 v26, v4
	v_mov_b32_e32 v27, v4
	v_mov_b32_e32 v36, v4
	v_mov_b32_e32 v37, v4
	v_mov_b32_e32 v38, v4
	v_mov_b32_e32 v39, v4
	v_mov_b32_e32 v40, v4
	v_mov_b32_e32 v41, v4
	v_mov_b32_e32 v42, v4
	v_mov_b32_e32 v43, v4
	v_mov_b32_e32 v52, v4
	v_mov_b32_e32 v53, v4
	v_mov_b32_e32 v54, v4
	v_mov_b32_e32 v55, v4
	v_mov_b32_e32 v56, v4
	v_mov_b32_e32 v57, v4
	v_mov_b32_e32 v58, v4
	v_mov_b32_e32 v59, v4
	v_mov_b32_e32 v12, v4
	v_mov_b32_e32 v13, v4
	v_mov_b32_e32 v14, v4
	v_mov_b32_e32 v15, v4
	v_mov_b32_e32 v16, v4
	v_mov_b32_e32 v17, v4
	v_mov_b32_e32 v18, v4
	v_mov_b32_e32 v19, v4
	v_mov_b32_e32 v28, v4
	v_mov_b32_e32 v29, v4
	v_mov_b32_e32 v30, v4
	v_mov_b32_e32 v31, v4
	v_mov_b32_e32 v32, v4
	v_mov_b32_e32 v33, v4
	v_mov_b32_e32 v34, v4
	v_mov_b32_e32 v35, v4
	v_mov_b32_e32 v44, v4
	v_mov_b32_e32 v45, v4
	v_mov_b32_e32 v46, v4
	v_mov_b32_e32 v47, v4
	v_mov_b32_e32 v48, v4
	v_mov_b32_e32 v49, v4
	v_mov_b32_e32 v50, v4
	v_mov_b32_e32 v51, v4
	v_mov_b32_e32 v60, v4
	v_mov_b32_e32 v61, v4
	v_mov_b32_e32 v62, v4
	v_mov_b32_e32 v63, v4
	v_mov_b32_e32 v64, v4
	v_mov_b32_e32 v65, v4
	v_mov_b32_e32 v66, v4
	v_mov_b32_e32 v67, v4
	v_mov_b32_e32 v68, v4
	v_mov_b32_e32 v69, v4
	v_mov_b32_e32 v70, v4
	v_mov_b32_e32 v71, v4
	v_mov_b32_e32 v72, v4
	v_mov_b32_e32 v73, v4
	v_mov_b32_e32 v74, v4
	v_mov_b32_e32 v75, v4
	v_mov_b32_e32 v84, v4
	v_mov_b32_e32 v85, v4
	v_mov_b32_e32 v86, v4
	v_mov_b32_e32 v87, v4
	v_mov_b32_e32 v88, v4
	v_mov_b32_e32 v89, v4
	v_mov_b32_e32 v90, v4
	v_mov_b32_e32 v91, v4
	v_mov_b32_e32 v100, v4
	v_mov_b32_e32 v101, v4
	v_mov_b32_e32 v102, v4
	v_mov_b32_e32 v103, v4
	v_mov_b32_e32 v104, v4
	v_mov_b32_e32 v105, v4
	v_mov_b32_e32 v106, v4
	v_mov_b32_e32 v107, v4
	v_mov_b32_e32 v116, v4
	v_mov_b32_e32 v117, v4
	v_mov_b32_e32 v118, v4
	v_mov_b32_e32 v119, v4
	s_waitcnt vmcnt(0)
	v_mov_b32_e32 v120, v4
	v_mov_b32_e32 v121, v4
	v_mov_b32_e32 v122, v4
	v_mov_b32_e32 v123, v4
	v_mov_b32_e32 v76, v4
	v_mov_b32_e32 v77, v4
	v_mov_b32_e32 v78, v4
	v_mov_b32_e32 v79, v4
	v_mov_b32_e32 v80, v4
	v_mov_b32_e32 v81, v4
	v_mov_b32_e32 v82, v4
	v_mov_b32_e32 v83, v4
	v_mov_b32_e32 v92, v4
	v_mov_b32_e32 v93, v4
	v_mov_b32_e32 v94, v4
	v_mov_b32_e32 v95, v4
	v_mov_b32_e32 v96, v4
	v_mov_b32_e32 v97, v4
	v_mov_b32_e32 v98, v4
	v_mov_b32_e32 v99, v4
	v_mov_b32_e32 v108, v4
	v_mov_b32_e32 v109, v4
	v_mov_b32_e32 v110, v4
	v_mov_b32_e32 v111, v4
	v_mov_b32_e32 v112, v4
	v_mov_b32_e32 v113, v4
	v_mov_b32_e32 v114, v4
	v_mov_b32_e32 v115, v4
	v_mov_b32_e32 v124, v4
	v_mov_b32_e32 v125, v4
	v_mov_b32_e32 v126, v4
	v_mov_b32_e32 v127, v4
	v_mov_b32_e32 v128, v4
	v_mov_b32_e32 v129, v4
	v_mov_b32_e32 v130, v4
	v_mov_b32_e32 v131, v4
	s_nop 0
.LBB0_363:
	s_add_u32 s36, s14, 0xfffc0080
	s_addc_u32 s37, s15, -1
	s_add_i32 s41, 0, 0x10000
	s_cmp_eq_u32 s40, 12
	s_cselect_b32 s39, s6, s37
	s_cselect_b32 s38, s7, s36
	v_add_u32_e32 v2, s41, v167
	s_cselect_b32 s37, s11, s29
	s_cselect_b32 s36, s13, s27
	s_add_i32 s64, 0, 0x14000
	ds_read_b128 v[156:159], v2
	ds_read_b128 v[160:163], v2 offset:1024
	ds_read_b128 v[170:173], v2 offset:2048
	ds_read_b128 v[174:177], v2 offset:3072
	v_add_u32_e32 v2, s64, v167
	ds_read_b128 v[182:185], v2
	ds_read_b128 v[186:189], v2 offset:1024
	ds_read_b128 v[190:193], v2 offset:2048
	ds_read_b128 v[210:213], v2 offset:3072
	v_lshl_add_u64 v[164:165], s[14:15], 0, v[150:151]
	s_add_i32 m0, s55, 0xc000
	ds_read_b128 v[214:217], v169
	ds_read_b128 v[218:221], v169 offset:1024
	ds_read_b128 v[222:225], v169 offset:2048
	ds_read_b128 v[226:229], v169 offset:3072
	ds_read_b128 v[230:233], v169 offset:4096
	ds_read_b128 v[234:237], v169 offset:5120
	ds_read_b128 v[238:241], v169 offset:6144
	ds_read_b128 v[242:245], v169 offset:7168
	global_load_lds_dwordx4 v[164:165], off
	v_lshl_add_u64 v[164:165], s[14:15], 0, v[152:153]
	s_add_i32 m0, s55, 0xe000
	s_nop 0
	global_load_lds_dwordx4 v[164:165], off
	s_waitcnt vmcnt(8)
	s_waitcnt lgkmcnt(0)
	s_barrier
; #define PG8_STAGE(bufoff, gbase, voff) do { _Pragma("unroll") for (int _i = 0; _i < 2; ++_i) \
;         __builtin_amdgcn_global_load_lds((const unsigned*)((const char*)(gbase) + (voff)[_i]), (PG8_LAS unsigned*)(lds + (bufoff) + ldsw + _i * 8192), 16, 0, 0); } while (0)
; #define PG8_LDA(dst, b, h) do { _Pragma("unroll") for (int m = 0; m < 4; ++m) _Pragma("unroll") for (int k = 0; k < 2; ++k) dst[m][k] = *(const PG8_LAS bf16x8*)(lds + PG8_SA(b, h) + aoff + m * 2048 + k * 1024); } while (0)
; #define PG8_MMA(ai, bj, At, Bt) do { __builtin_amdgcn_s_setprio(1); _Pragma("unroll") for (int m = 0; m < 4; ++m) _Pragma("unroll") for (int n = 0; n < 2; ++n) _Pragma("unroll") for (int k = 0; k < 2; ++k) \
;         acc[ai][bj][m][n] = __builtin_amdgcn_mfma_f32_16x16x32_bf16(Bt[n][k], At[m][k], acc[ai][bj][m][n], 0, 0, 0); __builtin_amdgcn_s_setprio(0); } while (0)
; #define PG8_WAIT_V(n) asm volatile("s_waitcnt vmcnt(" #n ")" ::: "memory")
; #define PG8_WAIT_L(n) asm volatile("s_waitcnt lgkmcnt(" #n ")" ::: "memory")
; #define PG8_BAR __builtin_amdgcn_s_barrier()
; #define PG8_SCHED __builtin_amdgcn_sched_barrier(0)
; template <class Epi, class Sched, bool ALIGN_EPI = false, bool SP2 = false>
; __device__ __forceinline__ void gemm_phase(PG8_LAS unsigned char* lds, const Gemm g, const Sched& S, const Epi& E, const int tid_arg) {
;     ...
;             PG8_WAIT_V(8); PG8_WAIT_L(0); PG8_BAR; PG8_MMA(0, 0, At, B0); PG8_MMA(0, 1, At, B1); PG8_BAR; PG8_SCHED;
;             PG8_LDA(At, 0, 1); PG8_STAGE(PG8_SB(0, 0), b2, voffB); PG8_STAGE(PG8_SB(0, 1), b2 + hstep, voffB); PG8_STAGE(PG8_SA(0, 0), a2, voffA);
;             PG8_WAIT_V(8); PG8_WAIT_L(0); PG8_BAR; PG8_MMA(1, 0, At, B0); PG8_MMA(1, 1, At, B1); PG8_BAR; PG8_SCHED;
	s_setprio 1
	s_waitcnt lgkmcnt(0)
	v_mfma_f32_16x16x32_bf16 v[128:131], v[156:159], v[214:217], v[128:131]
	v_mfma_f32_16x16x32_bf16 v[124:127], v[170:173], v[214:217], v[124:127]
	v_mfma_f32_16x16x32_bf16 v[112:115], v[156:159], v[222:225], v[112:115]
	v_mfma_f32_16x16x32_bf16 v[108:111], v[170:173], v[222:225], v[108:111]
	v_mfma_f32_16x16x32_bf16 v[96:99], v[156:159], v[230:233], v[96:99]
	v_mfma_f32_16x16x32_bf16 v[92:95], v[170:173], v[230:233], v[92:95]
	v_mfma_f32_16x16x32_bf16 v[80:83], v[156:159], v[238:241], v[80:83]
	v_mfma_f32_16x16x32_bf16 v[76:79], v[170:173], v[238:241], v[76:79]
	v_mfma_f32_16x16x32_bf16 v[128:131], v[160:163], v[218:221], v[128:131]
	v_mfma_f32_16x16x32_bf16 v[124:127], v[174:177], v[218:221], v[124:127]
	v_mfma_f32_16x16x32_bf16 v[112:115], v[160:163], v[226:229], v[112:115]
	v_mfma_f32_16x16x32_bf16 v[108:111], v[174:177], v[226:229], v[108:111]
	v_mfma_f32_16x16x32_bf16 v[96:99], v[160:163], v[234:237], v[96:99]
	v_mfma_f32_16x16x32_bf16 v[92:95], v[174:177], v[234:237], v[92:95]
	v_mfma_f32_16x16x32_bf16 v[80:83], v[160:163], v[242:245], v[80:83]
	v_mfma_f32_16x16x32_bf16 v[76:79], v[174:177], v[242:245], v[76:79]
	s_setprio 0
	s_setprio 1
	v_mfma_f32_16x16x32_bf16 v[120:123], v[182:185], v[214:217], v[120:123]
	v_mfma_f32_16x16x32_bf16 v[116:119], v[190:193], v[214:217], v[116:119]
	v_mfma_f32_16x16x32_bf16 v[104:107], v[182:185], v[222:225], v[104:107]
	v_mfma_f32_16x16x32_bf16 v[100:103], v[190:193], v[222:225], v[100:103]
	v_mfma_f32_16x16x32_bf16 v[88:91], v[182:185], v[230:233], v[88:91]
	v_mfma_f32_16x16x32_bf16 v[84:87], v[190:193], v[230:233], v[84:87]
	v_mfma_f32_16x16x32_bf16 v[72:75], v[182:185], v[238:241], v[72:75]
	v_mfma_f32_16x16x32_bf16 v[68:71], v[190:193], v[238:241], v[68:71]
	v_mfma_f32_16x16x32_bf16 v[120:123], v[186:189], v[218:221], v[120:123]
	v_mfma_f32_16x16x32_bf16 v[116:119], v[210:213], v[218:221], v[116:119]
	v_mfma_f32_16x16x32_bf16 v[104:107], v[186:189], v[226:229], v[104:107]
	v_mfma_f32_16x16x32_bf16 v[100:103], v[210:213], v[226:229], v[100:103]
	v_mfma_f32_16x16x32_bf16 v[88:91], v[186:189], v[234:237], v[88:91]
	v_mfma_f32_16x16x32_bf16 v[84:87], v[210:213], v[234:237], v[84:87]
	v_mfma_f32_16x16x32_bf16 v[72:75], v[186:189], v[242:245], v[72:75]
	v_mfma_f32_16x16x32_bf16 v[68:71], v[210:213], v[242:245], v[68:71]
	s_setprio 0
	s_barrier
	s_add_i32 s41, s41, s54
	v_lshl_add_u64 v[164:165], s[36:37], 0, v[134:135]
	s_mov_b32 m0, s41
	ds_read_b128 v[214:217], v169 offset:16384
	ds_read_b128 v[218:221], v169 offset:17408
	ds_read_b128 v[222:225], v169 offset:18432
	ds_read_b128 v[226:229], v169 offset:19456
	ds_read_b128 v[230:233], v169 offset:20480
	ds_read_b128 v[234:237], v169 offset:21504
	ds_read_b128 v[238:241], v169 offset:22528
	ds_read_b128 v[242:245], v169 offset:23552
	global_load_lds_dwordx4 v[164:165], off
	s_add_i32 m0, s41, 0x2000
	s_add_u32 s42, s36, 0x40000
	v_lshl_add_u64 v[178:179], s[36:37], 0, v[138:139]
	s_addc_u32 s43, s37, 0
	s_add_i32 s41, s64, s54
	global_load_lds_dwordx4 v[178:179], off
	v_lshl_add_u64 v[194:195], s[42:43], 0, v[134:135]
	s_mov_b32 m0, s41
	v_lshl_add_u64 v[246:247], s[38:39], 0, v[136:137]
	global_load_lds_dwordx4 v[194:195], off
	v_lshl_add_u64 v[194:195], s[42:43], 0, v[138:139]
	s_add_i32 m0, s41, 0x2000
	s_nop 0
	global_load_lds_dwordx4 v[194:195], off
	v_lshl_add_u64 v[194:195], s[38:39], 0, v[132:133]
	s_mov_b32 m0, s55
	s_nop 0
	global_load_lds_dwordx4 v[194:195], off
	s_mov_b32 m0, s56
	s_nop 0
	global_load_lds_dwordx4 v[246:247], off
	s_waitcnt vmcnt(8)
	s_waitcnt lgkmcnt(0)
	s_barrier
	s_setprio 1
	s_waitcnt lgkmcnt(0)
	v_mfma_f32_16x16x32_bf16 v[64:67], v[156:159], v[214:217], v[64:67]
	v_mfma_f32_16x16x32_bf16 v[60:63], v[170:173], v[214:217], v[60:63]
	v_mfma_f32_16x16x32_bf16 v[48:51], v[156:159], v[222:225], v[48:51]
	v_mfma_f32_16x16x32_bf16 v[44:47], v[170:173], v[222:225], v[44:47]
	v_mfma_f32_16x16x32_bf16 v[32:35], v[156:159], v[230:233], v[32:35]
	v_mfma_f32_16x16x32_bf16 v[28:31], v[170:173], v[230:233], v[28:31]
	v_mfma_f32_16x16x32_bf16 v[16:19], v[156:159], v[238:241], v[16:19]
	v_mfma_f32_16x16x32_bf16 v[12:15], v[170:173], v[238:241], v[12:15]
	v_mfma_f32_16x16x32_bf16 v[64:67], v[160:163], v[218:221], v[64:67]
	v_mfma_f32_16x16x32_bf16 v[60:63], v[174:177], v[218:221], v[60:63]
	v_mfma_f32_16x16x32_bf16 v[48:51], v[160:163], v[226:229], v[48:51]
	v_mfma_f32_16x16x32_bf16 v[44:47], v[174:177], v[226:229], v[44:47]
	v_mfma_f32_16x16x32_bf16 v[32:35], v[160:163], v[234:237], v[32:35]
	v_mfma_f32_16x16x32_bf16 v[28:31], v[174:177], v[234:237], v[28:31]
	v_mfma_f32_16x16x32_bf16 v[16:19], v[160:163], v[242:245], v[16:19]
	v_mfma_f32_16x16x32_bf16 v[12:15], v[174:177], v[242:245], v[12:15]
	s_setprio 0
	s_setprio 1
	v_mfma_f32_16x16x32_bf16 v[56:59], v[182:185], v[214:217], v[56:59]
	v_mfma_f32_16x16x32_bf16 v[52:55], v[190:193], v[214:217], v[52:55]
	v_mfma_f32_16x16x32_bf16 v[40:43], v[182:185], v[222:225], v[40:43]
	v_mfma_f32_16x16x32_bf16 v[36:39], v[190:193], v[222:225], v[36:39]
	v_mfma_f32_16x16x32_bf16 v[24:27], v[182:185], v[230:233], v[24:27]
	v_mfma_f32_16x16x32_bf16 v[20:23], v[190:193], v[230:233], v[20:23]
	v_mfma_f32_16x16x32_bf16 v[8:11], v[182:185], v[238:241], v[8:11]
	v_mfma_f32_16x16x32_bf16 v[4:7], v[190:193], v[238:241], v[4:7]
	v_mfma_f32_16x16x32_bf16 v[56:59], v[186:189], v[218:221], v[56:59]
	v_mfma_f32_16x16x32_bf16 v[52:55], v[210:213], v[218:221], v[52:55]
	v_mfma_f32_16x16x32_bf16 v[40:43], v[186:189], v[226:229], v[40:43]
	v_mfma_f32_16x16x32_bf16 v[36:39], v[210:213], v[226:229], v[36:39]
	v_mfma_f32_16x16x32_bf16 v[24:27], v[186:189], v[234:237], v[24:27]
	v_mfma_f32_16x16x32_bf16 v[20:23], v[210:213], v[234:237], v[20:23]
	v_mfma_f32_16x16x32_bf16 v[8:11], v[186:189], v[242:245], v[8:11]
	v_mfma_f32_16x16x32_bf16 v[4:7], v[210:213], v[242:245], v[4:7]
	s_setprio 0
	s_barrier
; #define PG8_STAGE(bufoff, gbase, voff) do { _Pragma("unroll") for (int _i = 0; _i < 2; ++_i) \
;         __builtin_amdgcn_global_load_lds((const unsigned*)((const char*)(gbase) + (voff)[_i]), (PG8_LAS unsigned*)(lds + (bufoff) + ldsw + _i * 8192), 16, 0, 0); } while (0)
; #define PG8_LDA(dst, b, h) do { _Pragma("unroll") for (int m = 0; m < 4; ++m) _Pragma("unroll") for (int k = 0; k < 2; ++k) dst[m][k] = *(const PG8_LAS bf16x8*)(lds + PG8_SA(b, h) + aoff + m * 2048 + k * 1024); } while (0)
; #define PG8_LDB(dst, b, h) do { _Pragma("unroll") for (int n = 0; n < 2; ++n) _Pragma("unroll") for (int k = 0; k < 2; ++k) dst[n][k] = *(const PG8_LAS bf16x8*)(lds + PG8_SB(b, h) + boff + n * 2048 + k * 1024); } while (0)
; #define PG8_MMA(ai, bj, At, Bt) do { __builtin_amdgcn_s_setprio(1); _Pragma("unroll") for (int m = 0; m < 4; ++m) _Pragma("unroll") for (int n = 0; n < 2; ++n) _Pragma("unroll") for (int k = 0; k < 2; ++k) \
;         acc[ai][bj][m][n] = __builtin_amdgcn_mfma_f32_16x16x32_bf16(Bt[n][k], At[m][k], acc[ai][bj][m][n], 0, 0, 0); __builtin_amdgcn_s_setprio(0); } while (0)
; #define PG8_WAIT_V(n) asm volatile("s_waitcnt vmcnt(" #n ")" ::: "memory")
; #define PG8_WAIT_L(n) asm volatile("s_waitcnt lgkmcnt(" #n ")" ::: "memory")
; #define PG8_BAR __builtin_amdgcn_s_barrier()
; #define PG8_SCHED __builtin_amdgcn_sched_barrier(0)
; template <class Epi, class Sched, bool ALIGN_EPI = false, bool SP2 = false>
; __device__ __forceinline__ void gemm_phase(PG8_LAS unsigned char* lds, const Gemm g, const Sched& S, const Epi& E, const int tid_arg) {
;     ...
;             PG8_LDB(B0, 1, 0); PG8_LDB(B1, 1, 1); PG8_SCHED; PG8_LDA(At, 1, 0); PG8_STAGE(PG8_SA(0, 1), a2 + hstep, voffA);
;             PG8_WAIT_V(8); PG8_WAIT_L(0); PG8_BAR; PG8_MMA(0, 0, At, B0); PG8_MMA(0, 1, At, B1); PG8_BAR; PG8_SCHED;
	s_add_i32 s41, 0, 0x18000
	v_add_u32_e32 v2, s41, v167
	s_add_i32 s42, 0, 0x1c000
	ds_read_b128 v[156:159], v2
	ds_read_b128 v[160:163], v2 offset:1024
	ds_read_b128 v[170:173], v2 offset:2048
	ds_read_b128 v[174:177], v2 offset:3072
	v_add_u32_e32 v2, s42, v167
	ds_read_b128 v[182:185], v2
	ds_read_b128 v[186:189], v2 offset:1024
	ds_read_b128 v[190:193], v2 offset:2048
	ds_read_b128 v[210:213], v2 offset:3072
	s_add_u32 s38, s38, 0x40000
	s_addc_u32 s39, s39, 0
	s_mov_b32 m0, s57
	v_lshl_add_u64 v[248:249], s[38:39], 0, v[132:133]
	ds_read_b128 v[214:217], v169 offset:32768
	ds_read_b128 v[218:221], v169 offset:33792
	ds_read_b128 v[222:225], v169 offset:34816
	ds_read_b128 v[226:229], v169 offset:35840
	ds_read_b128 v[230:233], v169 offset:36864
	ds_read_b128 v[234:237], v169 offset:37888
	ds_read_b128 v[238:241], v169 offset:38912
	ds_read_b128 v[242:245], v169 offset:39936
	global_load_lds_dwordx4 v[248:249], off
	v_lshl_add_u64 v[248:249], s[38:39], 0, v[136:137]
	s_mov_b32 m0, s58
	s_nop 0
	global_load_lds_dwordx4 v[248:249], off
	s_waitcnt vmcnt(8)
	s_waitcnt lgkmcnt(0)
	s_barrier
	s_setprio 1
	s_waitcnt lgkmcnt(0)
	v_mfma_f32_16x16x32_bf16 v[128:131], v[156:159], v[214:217], v[128:131]
	v_mfma_f32_16x16x32_bf16 v[124:127], v[170:173], v[214:217], v[124:127]
	v_mfma_f32_16x16x32_bf16 v[112:115], v[156:159], v[222:225], v[112:115]
	v_mfma_f32_16x16x32_bf16 v[108:111], v[170:173], v[222:225], v[108:111]
	v_mfma_f32_16x16x32_bf16 v[96:99], v[156:159], v[230:233], v[96:99]
	v_mfma_f32_16x16x32_bf16 v[92:95], v[170:173], v[230:233], v[92:95]
	v_mfma_f32_16x16x32_bf16 v[80:83], v[156:159], v[238:241], v[80:83]
	v_mfma_f32_16x16x32_bf16 v[76:79], v[170:173], v[238:241], v[76:79]
	v_mfma_f32_16x16x32_bf16 v[128:131], v[160:163], v[218:221], v[128:131]
	v_mfma_f32_16x16x32_bf16 v[124:127], v[174:177], v[218:221], v[124:127]
	v_mfma_f32_16x16x32_bf16 v[112:115], v[160:163], v[226:229], v[112:115]
	v_mfma_f32_16x16x32_bf16 v[108:111], v[174:177], v[226:229], v[108:111]
	v_mfma_f32_16x16x32_bf16 v[96:99], v[160:163], v[234:237], v[96:99]
	v_mfma_f32_16x16x32_bf16 v[92:95], v[174:177], v[234:237], v[92:95]
	v_mfma_f32_16x16x32_bf16 v[80:83], v[160:163], v[242:245], v[80:83]
	v_mfma_f32_16x16x32_bf16 v[76:79], v[174:177], v[242:245], v[76:79]
	s_setprio 0
	s_setprio 1
	v_mfma_f32_16x16x32_bf16 v[120:123], v[182:185], v[214:217], v[120:123]
	v_mfma_f32_16x16x32_bf16 v[116:119], v[190:193], v[214:217], v[116:119]
	v_mfma_f32_16x16x32_bf16 v[104:107], v[182:185], v[222:225], v[104:107]
	v_mfma_f32_16x16x32_bf16 v[100:103], v[190:193], v[222:225], v[100:103]
	v_mfma_f32_16x16x32_bf16 v[88:91], v[182:185], v[230:233], v[88:91]
	v_mfma_f32_16x16x32_bf16 v[84:87], v[190:193], v[230:233], v[84:87]
	v_mfma_f32_16x16x32_bf16 v[72:75], v[182:185], v[238:241], v[72:75]
	v_mfma_f32_16x16x32_bf16 v[68:71], v[190:193], v[238:241], v[68:71]
	v_mfma_f32_16x16x32_bf16 v[120:123], v[186:189], v[218:221], v[120:123]
	v_mfma_f32_16x16x32_bf16 v[116:119], v[210:213], v[218:221], v[116:119]
	v_mfma_f32_16x16x32_bf16 v[104:107], v[186:189], v[226:229], v[104:107]
	v_mfma_f32_16x16x32_bf16 v[100:103], v[210:213], v[226:229], v[100:103]
	v_mfma_f32_16x16x32_bf16 v[88:91], v[186:189], v[234:237], v[88:91]
	v_mfma_f32_16x16x32_bf16 v[84:87], v[210:213], v[234:237], v[84:87]
	v_mfma_f32_16x16x32_bf16 v[72:75], v[186:189], v[242:245], v[72:75]
	v_mfma_f32_16x16x32_bf16 v[68:71], v[210:213], v[242:245], v[68:71]
	s_setprio 0
	s_barrier
; #define PG8_STAGE(bufoff, gbase, voff) do { _Pragma("unroll") for (int _i = 0; _i < 2; ++_i) \
;         __builtin_amdgcn_global_load_lds((const unsigned*)((const char*)(gbase) + (voff)[_i]), (PG8_LAS unsigned*)(lds + (bufoff) + ldsw + _i * 8192), 16, 0, 0); } while (0)
; #define PG8_LDA(dst, b, h) do { _Pragma("unroll") for (int m = 0; m < 4; ++m) _Pragma("unroll") for (int k = 0; k < 2; ++k) dst[m][k] = *(const PG8_LAS bf16x8*)(lds + PG8_SA(b, h) + aoff + m * 2048 + k * 1024); } while (0)
; #define PG8_WAIT_V(n) asm volatile("s_waitcnt vmcnt(" #n ")" ::: "memory")
; #define PG8_WAIT_L(n) asm volatile("s_waitcnt lgkmcnt(" #n ")" ::: "memory")
; #define PG8_BAR __builtin_amdgcn_s_barrier()
;     __device__ __forceinline__ void operator()(const f32x4 (&acc)[2][2][4][2], const Unit& u, int wr, int wc, int fr, int fq) const {
;         const int pn = u.pn; const int lrow0 = u.pm * BM + wr * 64 + fr;
;         bf16_t* dst; int ldc, colt;
;         if (pn < 24) { dst = PB + (size_t)(pn >> 2) * pbs; ldc = 1024; colt = (pn & 3) * 256; } else { dst = GG; ldc = 2048; colt = (pn - 24) * 256; }
;         const int col0 = colt + wc * 32 + 8 * fq;
;         float* kvo = nullptr; long kvrow0 = 0;
;         if (pn >= 16 && pn < 24) {
;             const int gt = grow0 + u.pm * BM;
;             if (gt >= 32768) { kvo = (pn < 20) ? oks : ovs; kvrow0 = (long)(gt - 32768) - (long)(u.pm * BM); }
;             else if ((gt & 2047) >= 1536) { kvo = (pn < 20) ? okp : ovp; kvrow0 = (long)((gt >> 11) * 512 + ((gt & 2047) - 1536)) - (long)(u.pm * BM); }
;         }
; #pragma unroll
;         for (int ai = 0; ai < 2; ++ai)
; #pragma unroll
;             for (int m = 0; m < 4; ++m) {
;                 int row = lrow0 + ai * HALF + m * 16; asm volatile("" : "+v"(row));
;                 const float rs = rstd_from_ss(SS + (size_t)row * 16, fq);
;                 if (pn < 32) {
; template <class Epi, class Sched, bool ALIGN_EPI = false, bool SP2 = false>
; __device__ __forceinline__ void gemm_phase(PG8_LAS unsigned char* lds, const Gemm g, const Sched& S, const Epi& E, const int tid_arg) {
;     ...
;             PG8_LDA(At, 1, 1); PG8_STAGE(PG8_SB(1, 0), b3, voffB); PG8_STAGE(PG8_SB(1, 1), b3 + hstep, voffB); PG8_STAGE(PG8_SA(1, 0), a3, voffA);
;             PG8_WAIT_V(8); PG8_WAIT_L(0); PG8_BAR; PG8_MMA(1, 0, At, B0); PG8_MMA(1, 1, At, B1); PG8_BAR; PG8_SCHED;
	s_add_i32 s38, s41, s54
	v_lshl_add_u64 v[164:165], v[164:165], 0, s[76:77]
	s_mov_b32 m0, s38
	ds_read_b128 v[214:217], v169 offset:49152
	ds_read_b128 v[218:221], v169 offset:50176
	ds_read_b128 v[222:225], v169 offset:51200
	ds_read_b128 v[226:229], v169 offset:52224
	ds_read_b128 v[230:233], v169 offset:53248
	ds_read_b128 v[234:237], v169 offset:54272
	ds_read_b128 v[238:241], v169 offset:55296
	ds_read_b128 v[242:245], v169 offset:56320
	global_load_lds_dwordx4 v[164:165], off
	s_add_i32 m0, s38, 0x2000
	s_add_u32 s36, s36, 0x40080
	v_lshl_add_u64 v[164:165], v[178:179], 0, s[76:77]
	s_addc_u32 s37, s37, 0
	s_add_i32 s38, s42, s54
	global_load_lds_dwordx4 v[164:165], off
	v_lshl_add_u64 v[164:165], s[36:37], 0, v[134:135]
	s_mov_b32 m0, s38
	s_nop 0
	global_load_lds_dwordx4 v[164:165], off
	v_lshl_add_u64 v[164:165], s[36:37], 0, v[138:139]
	s_add_i32 m0, s38, 0x2000
	s_nop 0
	global_load_lds_dwordx4 v[164:165], off
	v_lshl_add_u64 v[164:165], v[194:195], 0, s[76:77]
	s_mov_b32 m0, s61
	s_nop 0
	global_load_lds_dwordx4 v[164:165], off
	v_lshl_add_u64 v[164:165], v[246:247], 0, s[76:77]
	s_mov_b32 m0, s62
	s_nop 0
	global_load_lds_dwordx4 v[164:165], off
	s_waitcnt vmcnt(8)
	s_waitcnt lgkmcnt(0)
	s_barrier
	s_setprio 1
	s_waitcnt lgkmcnt(0)
	v_mfma_f32_16x16x32_bf16 v[64:67], v[156:159], v[214:217], v[64:67]
	v_mfma_f32_16x16x32_bf16 v[60:63], v[170:173], v[214:217], v[60:63]
	v_mfma_f32_16x16x32_bf16 v[48:51], v[156:159], v[222:225], v[48:51]
	v_mfma_f32_16x16x32_bf16 v[44:47], v[170:173], v[222:225], v[44:47]
	v_mfma_f32_16x16x32_bf16 v[32:35], v[156:159], v[230:233], v[32:35]
	v_mfma_f32_16x16x32_bf16 v[28:31], v[170:173], v[230:233], v[28:31]
	v_mfma_f32_16x16x32_bf16 v[16:19], v[156:159], v[238:241], v[16:19]
	v_mfma_f32_16x16x32_bf16 v[12:15], v[170:173], v[238:241], v[12:15]
	v_mfma_f32_16x16x32_bf16 v[64:67], v[160:163], v[218:221], v[64:67]
	v_mfma_f32_16x16x32_bf16 v[60:63], v[174:177], v[218:221], v[60:63]
	v_mfma_f32_16x16x32_bf16 v[48:51], v[160:163], v[226:229], v[48:51]
	v_mfma_f32_16x16x32_bf16 v[44:47], v[174:177], v[226:229], v[44:47]
	v_mfma_f32_16x16x32_bf16 v[32:35], v[160:163], v[234:237], v[32:35]
	v_mfma_f32_16x16x32_bf16 v[28:31], v[174:177], v[234:237], v[28:31]
	v_mfma_f32_16x16x32_bf16 v[16:19], v[160:163], v[242:245], v[16:19]
	v_mfma_f32_16x16x32_bf16 v[12:15], v[174:177], v[242:245], v[12:15]
	s_setprio 0
	s_setprio 1
	v_mfma_f32_16x16x32_bf16 v[56:59], v[182:185], v[214:217], v[56:59]
	v_mfma_f32_16x16x32_bf16 v[52:55], v[190:193], v[214:217], v[52:55]
	v_mfma_f32_16x16x32_bf16 v[40:43], v[182:185], v[222:225], v[40:43]
	v_mfma_f32_16x16x32_bf16 v[36:39], v[190:193], v[222:225], v[36:39]
	v_mfma_f32_16x16x32_bf16 v[24:27], v[182:185], v[230:233], v[24:27]
	v_mfma_f32_16x16x32_bf16 v[20:23], v[190:193], v[230:233], v[20:23]
	v_mfma_f32_16x16x32_bf16 v[8:11], v[182:185], v[238:241], v[8:11]
	v_mfma_f32_16x16x32_bf16 v[4:7], v[190:193], v[238:241], v[4:7]
	v_mfma_f32_16x16x32_bf16 v[56:59], v[186:189], v[218:221], v[56:59]
	v_mfma_f32_16x16x32_bf16 v[52:55], v[210:213], v[218:221], v[52:55]
	v_mfma_f32_16x16x32_bf16 v[40:43], v[186:189], v[226:229], v[40:43]
	v_mfma_f32_16x16x32_bf16 v[36:39], v[210:213], v[226:229], v[36:39]
	v_mfma_f32_16x16x32_bf16 v[24:27], v[186:189], v[234:237], v[24:27]
	v_mfma_f32_16x16x32_bf16 v[20:23], v[210:213], v[234:237], v[20:23]
	v_mfma_f32_16x16x32_bf16 v[8:11], v[186:189], v[242:245], v[8:11]
	v_mfma_f32_16x16x32_bf16 v[4:7], v[210:213], v[242:245], v[4:7]
	s_setprio 0
	s_barrier
	s_add_i32 s40, s40, 2
	s_add_u32 s14, s14, 0x100
	s_addc_u32 s15, s15, 0
	s_add_u32 s27, s27, 0x100
	s_addc_u32 s29, s29, 0
	s_cmp_gt_u32 s40, 13
	s_cbranch_scc0 .LBB0_363
	s_lshl_b32 s40, s12, 8
	v_add_u32_e32 v170, s40, v166
	v_ashrrev_i32_e32 v171, 31, v170
	v_lshlrev_b64 v[172:173], 6, v[170:171]
	s_mov_b64 s[40:41], 0x2000
	v_lshl_add_u64 v[172:173], v[146:147], 0, v[172:173]
	v_lshl_add_u64 v[174:175], v[172:173], 0, s[40:41]
	global_load_dwordx4 v[210:213], v[172:173], off
	global_load_dwordx4 v[214:217], v[172:173], off offset:1024
	global_load_dwordx4 v[218:221], v[172:173], off offset:2048
	global_load_dwordx4 v[222:225], v[172:173], off offset:3072
	global_load_dwordx4 v[226:229], v[174:175], off
	global_load_dwordx4 v[230:233], v[174:175], off offset:1024
	global_load_dwordx4 v[234:237], v[174:175], off offset:2048
	global_load_dwordx4 v[238:241], v[174:175], off offset:3072
	s_and_b64 vcc, exec, s[22:23]
	s_cbranch_vccz .LBB0_449
	s_barrier
	s_cmp_gt_i32 s10, 23
	s_mov_b64 s[14:15], -1
	s_cbranch_scc1 .LBB0_450

; __device__ __forceinline__ unsigned xb_ld(unsigned* p)              { return __hip_atomic_load(p, __ATOMIC_RELAXED, __HIP_MEMORY_SCOPE_AGENT); }
; __device__ __forceinline__ unsigned xb_add(unsigned* p, unsigned v) { return __hip_atomic_fetch_add(p, v, __ATOMIC_RELAXED, __HIP_MEMORY_SCOPE_AGENT); }
; #define XB_SPIN(cond, bar) do { unsigned _sp = 0; while (cond) { __builtin_amdgcn_s_sleep(1); \
;     if ((++_sp & 255u) == 0u) { if (xb_ld(&(bar)[XB_TMO])) break; if (_sp > XB_SPIN_CAP) { atomicAdd(&(bar)[XB_TMO], 1u); break; } } } } while (0)
; __device__ __forceinline__ void xcd_barrier(const XcdBarrier& b, const bool leader) {
;     ...
;         const unsigned old = xb_add(&bar[XB_XSUB(b.x)], 1u);
;         const unsigned gen = old / nloc;
;         if (old + 1u == (gen + 1u) * nloc) {
;             __builtin_amdgcn_fence(__ATOMIC_RELEASE, "agent");
;             asm volatile("s_waitcnt vmcnt(0)" ::: "memory");
;             const unsigned og = xb_add(&bar[XB_TOP], 1u);
;             const unsigned tg = og / nx;
;             if (og + 1u == (tg + 1u) * nx) xb_add(&bar[XB_TOPGEN], 1u);
;             else XB_SPIN(xb_ld(&bar[XB_TOPGEN]) == tg, bar);
;             __builtin_amdgcn_fence(__ATOMIC_ACQUIRE, "agent");
;             xb_add(&bar[XB_XGEN(b.x)], 1u);
;             asm volatile("s_waitcnt vmcnt(0)" ::: "memory");
;         } else {
;             XB_SPIN(xb_ld(&bar[XB_XGEN(b.x)]) == gen, bar);
.LBB0_470:
	s_or_b64 exec, exec, s[14:15]
	v_cvt_f32_u32_e32 v7, v5
	s_waitcnt vmcnt(0)
	v_readfirstlane_b32 s2, v6
	v_sub_u32_e32 v6, 0, v5
	v_rcp_iflag_f32_e32 v7, v7
	v_add_u32_e32 v8, s2, v2
	v_mul_f32_e32 v7, 0x4f7ffffe, v7
	v_cvt_u32_f32_e32 v7, v7
	v_mul_lo_u32 v2, v6, v7
	v_mul_hi_u32 v2, v7, v2
	v_add_u32_e32 v2, v7, v2
	v_mul_hi_u32 v2, v8, v2
	v_mul_lo_u32 v6, v2, v5
	v_sub_u32_e32 v6, v8, v6
	v_add_u32_e32 v7, 1, v2
	v_cmp_ge_u32_e32 vcc, v6, v5
	s_nop 1
	v_cndmask_b32_e32 v2, v2, v7, vcc
	v_sub_u32_e32 v7, v6, v5
	v_cndmask_b32_e32 v6, v6, v7, vcc
	v_add_u32_e32 v7, 1, v2
	v_cmp_ge_u32_e32 vcc, v6, v5
	v_add_u32_e32 v6, 1, v8
	s_nop 0
	v_cndmask_b32_e32 v2, v2, v7, vcc
	v_mul_lo_u32 v7, v5, v2
	v_add_u32_e32 v5, v7, v5
	v_cmp_ne_u32_e32 vcc, v6, v5
	s_and_saveexec_b64 s[2:3], vcc
	s_xor_b64 s[12:13], exec, s[2:3]
	s_cbranch_execz .LBB0_484
	buffer_inv sc1
	s_waitcnt lgkmcnt(0)
	s_load_dwordx2 s[20:21], s[90:91], 0xb0
	s_waitcnt lgkmcnt(0)
	s_add_u32 s20, s20, 0x1d79b500
	s_addc_u32 s21, s21, 0
	v_mov_b32_e32 v4, 0
	global_load_dword v4, v4, s[20:21] sc1
	s_waitcnt vmcnt(0)
	v_cmp_eq_u32_e32 vcc, v4, v2
	s_and_saveexec_b64 s[14:15], vcc
	s_cbranch_execz .LBB0_483
	s_add_u32 s16, s18, 0x1d798200
	s_addc_u32 s17, s19, 0
	s_mov_b32 s2, 1
	s_mov_b64 s[22:23], 0
	s_branch .LBB0_474

; __device__ __forceinline__ unsigned xb_ld(unsigned* p)              { return __hip_atomic_load(p, __ATOMIC_RELAXED, __HIP_MEMORY_SCOPE_AGENT); }
; __device__ __forceinline__ unsigned xb_add(unsigned* p, unsigned v) { return __hip_atomic_fetch_add(p, v, __ATOMIC_RELAXED, __HIP_MEMORY_SCOPE_AGENT); }
; #define XB_SPIN(cond, bar) do { unsigned _sp = 0; while (cond) { __builtin_amdgcn_s_sleep(1); \
;     if ((++_sp & 255u) == 0u) { if (xb_ld(&(bar)[XB_TMO])) break; if (_sp > XB_SPIN_CAP) { atomicAdd(&(bar)[XB_TMO], 1u); break; } } } } while (0)
; __device__ __forceinline__ void xcd_barrier(const XcdBarrier& b, const bool leader) {
;     ...
;         if (old + 1u == (gen + 1u) * nloc) {
;             __builtin_amdgcn_fence(__ATOMIC_RELEASE, "agent");
;             asm volatile("s_waitcnt vmcnt(0)" ::: "memory");
;             const unsigned og = xb_add(&bar[XB_TOP], 1u);
;             const unsigned tg = og / nx;
;             if (og + 1u == (tg + 1u) * nx) xb_add(&bar[XB_TOPGEN], 1u);
;             else XB_SPIN(xb_ld(&bar[XB_TOPGEN]) == tg, bar);
;             __builtin_amdgcn_fence(__ATOMIC_ACQUIRE, "agent");
;             xb_add(&bar[XB_XGEN(b.x)], 1u);
;             asm volatile("s_waitcnt vmcnt(0)" ::: "memory");
;         } else {
;             XB_SPIN(xb_ld(&bar[XB_XGEN(b.x)]) == gen, bar);
;             __builtin_amdgcn_fence(__ATOMIC_ACQUIRE, "agent");
;             asm volatile("s_waitcnt vmcnt(0)" ::: "memory");
.LBB0_484:
	s_andn2_saveexec_b64 s[12:13], s[12:13]
	s_cbranch_execz .LBB0_504
	s_mov_b64 s[14:15], exec
	buffer_wbl2 sc1
	buffer_inv sc1
	s_waitcnt lgkmcnt(0)
	s_waitcnt vmcnt(0)
	v_mbcnt_lo_u32_b32 v2, s14, 0
	v_mbcnt_hi_u32_b32 v2, s15, v2
	v_cmp_eq_u32_e32 vcc, 0, v2
	s_and_saveexec_b64 s[16:17], vcc
	s_cbranch_execz .LBB0_487
	s_bcnt1_i32_b64 s2, s[14:15]
	v_mov_b32_e32 v5, s2
	global_atomic_add v5, v203, v5, s[18:19] offset:1024 sc0

; __device__ __forceinline__ unsigned xb_add(unsigned* p, unsigned v) { return __hip_atomic_fetch_add(p, v, __ATOMIC_RELAXED, __HIP_MEMORY_SCOPE_AGENT); }
; __device__ __forceinline__ void xcd_barrier(const XcdBarrier& b, const bool leader) {
;     ...
;             __builtin_amdgcn_fence(__ATOMIC_ACQUIRE, "agent");
;             xb_add(&bar[XB_XGEN(b.x)], 1u);
;             asm volatile("s_waitcnt vmcnt(0)" ::: "memory");
.LBB0_501:
	s_or_b64 exec, exec, s[6:7]
	s_mov_b64 s[14:15], exec
	v_mbcnt_lo_u32_b32 v2, s14, 0
	v_mbcnt_hi_u32_b32 v2, s15, v2
	v_cmp_eq_u32_e32 vcc, 0, v2
	s_waitcnt vmcnt(0)
	s_and_saveexec_b64 s[6:7], vcc
	s_cbranch_execz .LBB0_503
	s_bcnt1_i32_b64 s2, s[14:15]
	v_mov_b32_e32 v2, s2
	global_atomic_add v202, v2, s[10:11] offset:1024
.LBB0_503:
	s_or_b64 exec, exec, s[6:7]
	s_waitcnt vmcnt(0)

; __device__ __forceinline__ unsigned xb_ld(unsigned* p)              { return __hip_atomic_load(p, __ATOMIC_RELAXED, __HIP_MEMORY_SCOPE_AGENT); }
; __device__ __forceinline__ unsigned xb_add(unsigned* p, unsigned v) { return __hip_atomic_fetch_add(p, v, __ATOMIC_RELAXED, __HIP_MEMORY_SCOPE_AGENT); }
; #define XB_SPIN(cond, bar) do { unsigned _sp = 0; while (cond) { __builtin_amdgcn_s_sleep(1); \
;     if ((++_sp & 255u) == 0u) { if (xb_ld(&(bar)[XB_TMO])) break; if (_sp > XB_SPIN_CAP) { atomicAdd(&(bar)[XB_TMO], 1u); break; } } } } while (0)
; __device__ __forceinline__ void xcd_barrier(const XcdBarrier& b, const bool leader) {
;     ...
;         const unsigned old = xb_add(&bar[XB_XSUB(b.x)], 1u);
;         const unsigned gen = old / nloc;
;         if (old + 1u == (gen + 1u) * nloc) {
;             __builtin_amdgcn_fence(__ATOMIC_RELEASE, "agent");
;             asm volatile("s_waitcnt vmcnt(0)" ::: "memory");
;             const unsigned og = xb_add(&bar[XB_TOP], 1u);
;             const unsigned tg = og / nx;
;             if (og + 1u == (tg + 1u) * nx) xb_add(&bar[XB_TOPGEN], 1u);
;             else XB_SPIN(xb_ld(&bar[XB_TOPGEN]) == tg, bar);
;             __builtin_amdgcn_fence(__ATOMIC_ACQUIRE, "agent");
;             xb_add(&bar[XB_XGEN(b.x)], 1u);
;             asm volatile("s_waitcnt vmcnt(0)" ::: "memory");
;         } else {
;             XB_SPIN(xb_ld(&bar[XB_XGEN(b.x)]) == gen, bar);
.LBB0_582:
	s_or_b64 exec, exec, s[12:13]
	v_cvt_f32_u32_e32 v7, v5
	s_waitcnt vmcnt(0)
	v_readfirstlane_b32 s2, v6
	v_sub_u32_e32 v6, 0, v5
	v_rcp_iflag_f32_e32 v7, v7
	v_add_u32_e32 v8, s2, v2
	v_mul_f32_e32 v7, 0x4f7ffffe, v7
	v_cvt_u32_f32_e32 v7, v7
	v_mul_lo_u32 v2, v6, v7
	v_mul_hi_u32 v2, v7, v2
	v_add_u32_e32 v2, v7, v2
	v_mul_hi_u32 v2, v8, v2
	v_mul_lo_u32 v6, v2, v5
	v_sub_u32_e32 v6, v8, v6
	v_add_u32_e32 v7, 1, v2
	v_cmp_ge_u32_e32 vcc, v6, v5
	s_nop 1
	v_cndmask_b32_e32 v2, v2, v7, vcc
	v_sub_u32_e32 v7, v6, v5
	v_cndmask_b32_e32 v6, v6, v7, vcc
	v_add_u32_e32 v7, 1, v2
	v_cmp_ge_u32_e32 vcc, v6, v5
	v_add_u32_e32 v6, 1, v8
	s_nop 0
	v_cndmask_b32_e32 v2, v2, v7, vcc
	v_mul_lo_u32 v7, v5, v2
	v_add_u32_e32 v5, v7, v5
	v_cmp_ne_u32_e32 vcc, v6, v5
	s_and_saveexec_b64 s[2:3], vcc
	s_xor_b64 s[10:11], exec, s[2:3]
	s_cbranch_execz .LBB0_596
	buffer_inv sc1
	s_waitcnt lgkmcnt(0)
	s_load_dwordx2 s[16:17], s[90:91], 0xb0
	s_waitcnt lgkmcnt(0)
	s_add_u32 s16, s16, 0x1d79b500
	s_addc_u32 s17, s17, 0
	v_mov_b32_e32 v4, 0
	global_load_dword v4, v4, s[16:17] sc1
	s_waitcnt vmcnt(0)
	v_cmp_eq_u32_e32 vcc, v4, v2
	s_and_saveexec_b64 s[12:13], vcc
	s_cbranch_execz .LBB0_595
	s_add_u32 s14, s50, 0x1d798200
	s_addc_u32 s15, s51, 0
	s_mov_b32 s2, 1
	s_mov_b64 s[18:19], 0
	s_branch .LBB0_586

; __device__ __forceinline__ unsigned xb_ld(unsigned* p)              { return __hip_atomic_load(p, __ATOMIC_RELAXED, __HIP_MEMORY_SCOPE_AGENT); }
; __device__ __forceinline__ unsigned xb_add(unsigned* p, unsigned v) { return __hip_atomic_fetch_add(p, v, __ATOMIC_RELAXED, __HIP_MEMORY_SCOPE_AGENT); }
; #define XB_SPIN(cond, bar) do { unsigned _sp = 0; while (cond) { __builtin_amdgcn_s_sleep(1); \
;     if ((++_sp & 255u) == 0u) { if (xb_ld(&(bar)[XB_TMO])) break; if (_sp > XB_SPIN_CAP) { atomicAdd(&(bar)[XB_TMO], 1u); break; } } } } while (0)
; __device__ __forceinline__ void xcd_barrier(const XcdBarrier& b, const bool leader) {
;     ...
;         if (old + 1u == (gen + 1u) * nloc) {
;             __builtin_amdgcn_fence(__ATOMIC_RELEASE, "agent");
;             asm volatile("s_waitcnt vmcnt(0)" ::: "memory");
;             const unsigned og = xb_add(&bar[XB_TOP], 1u);
;             const unsigned tg = og / nx;
;             if (og + 1u == (tg + 1u) * nx) xb_add(&bar[XB_TOPGEN], 1u);
;             else XB_SPIN(xb_ld(&bar[XB_TOPGEN]) == tg, bar);
;             __builtin_amdgcn_fence(__ATOMIC_ACQUIRE, "agent");
;             xb_add(&bar[XB_XGEN(b.x)], 1u);
;             asm volatile("s_waitcnt vmcnt(0)" ::: "memory");
;         } else {
;             XB_SPIN(xb_ld(&bar[XB_XGEN(b.x)]) == gen, bar);
;             __builtin_amdgcn_fence(__ATOMIC_ACQUIRE, "agent");
;             asm volatile("s_waitcnt vmcnt(0)" ::: "memory");
.LBB0_596:
	s_andn2_saveexec_b64 s[2:3], s[10:11]
	s_cbranch_execz .LBB0_616
	s_mov_b64 s[10:11], exec
	buffer_wbl2 sc1
	buffer_inv sc1
	s_waitcnt lgkmcnt(0)
	s_waitcnt vmcnt(0)
	v_mbcnt_lo_u32_b32 v2, s10, 0
	v_mbcnt_hi_u32_b32 v2, s11, v2
	v_cmp_eq_u32_e32 vcc, 0, v2
	s_and_saveexec_b64 s[12:13], vcc
	s_cbranch_execz .LBB0_599
	s_bcnt1_i32_b64 s2, s[10:11]
	v_mov_b32_e32 v5, s2
	global_atomic_add v5, v203, v5, s[50:51] offset:1024 sc0

; __device__ __forceinline__ unsigned xb_add(unsigned* p, unsigned v) { return __hip_atomic_fetch_add(p, v, __ATOMIC_RELAXED, __HIP_MEMORY_SCOPE_AGENT); }
; __device__ __forceinline__ void xcd_barrier(const XcdBarrier& b, const bool leader) {
;     ...
;             __builtin_amdgcn_fence(__ATOMIC_ACQUIRE, "agent");
;             xb_add(&bar[XB_XGEN(b.x)], 1u);
;             asm volatile("s_waitcnt vmcnt(0)" ::: "memory");
.LBB0_613:
	s_or_b64 exec, exec, s[6:7]
	s_mov_b64 s[10:11], exec
	v_mbcnt_lo_u32_b32 v2, s10, 0
	v_mbcnt_hi_u32_b32 v2, s11, v2
	v_cmp_eq_u32_e32 vcc, 0, v2
	s_waitcnt vmcnt(0)
	s_and_saveexec_b64 s[6:7], vcc
	s_cbranch_execz .LBB0_615
	s_bcnt1_i32_b64 s2, s[10:11]
	v_mov_b32_e32 v2, s2
	global_atomic_add v202, v2, s[8:9] offset:1024
.LBB0_615:
	s_or_b64 exec, exec, s[6:7]
	s_waitcnt vmcnt(0)

; __device__ __forceinline__ unsigned xb_ld(unsigned* p)              { return __hip_atomic_load(p, __ATOMIC_RELAXED, __HIP_MEMORY_SCOPE_AGENT); }
; __device__ __forceinline__ unsigned xb_add(unsigned* p, unsigned v) { return __hip_atomic_fetch_add(p, v, __ATOMIC_RELAXED, __HIP_MEMORY_SCOPE_AGENT); }
; #define XB_SPIN(cond, bar) do { unsigned _sp = 0; while (cond) { __builtin_amdgcn_s_sleep(1); \
;     if ((++_sp & 255u) == 0u) { if (xb_ld(&(bar)[XB_TMO])) break; if (_sp > XB_SPIN_CAP) { atomicAdd(&(bar)[XB_TMO], 1u); break; } } } } while (0)
; __device__ __forceinline__ void xcd_barrier(const XcdBarrier& b, const bool leader) {
;     ...
;         const unsigned old = xb_add(&bar[XB_XSUB(b.x)], 1u);
;         const unsigned gen = old / nloc;
;         if (old + 1u == (gen + 1u) * nloc) {
;             __builtin_amdgcn_fence(__ATOMIC_RELEASE, "agent");
;             asm volatile("s_waitcnt vmcnt(0)" ::: "memory");
;             const unsigned og = xb_add(&bar[XB_TOP], 1u);
;             const unsigned tg = og / nx;
;             if (og + 1u == (tg + 1u) * nx) xb_add(&bar[XB_TOPGEN], 1u);
;             else XB_SPIN(xb_ld(&bar[XB_TOPGEN]) == tg, bar);
;             __builtin_amdgcn_fence(__ATOMIC_ACQUIRE, "agent");
;             xb_add(&bar[XB_XGEN(b.x)], 1u);
;             asm volatile("s_waitcnt vmcnt(0)" ::: "memory");
;         } else {
;             XB_SPIN(xb_ld(&bar[XB_XGEN(b.x)]) == gen, bar);
.LBB0_660:
	s_or_b64 exec, exec, s[6:7]
	v_cvt_f32_u32_e32 v7, v5
	s_waitcnt vmcnt(0)
	v_readfirstlane_b32 s2, v6
	v_sub_u32_e32 v6, 0, v5
	v_rcp_iflag_f32_e32 v7, v7
	v_add_u32_e32 v8, s2, v2
	v_mul_f32_e32 v7, 0x4f7ffffe, v7
	v_cvt_u32_f32_e32 v7, v7
	v_mul_lo_u32 v2, v6, v7
	v_mul_hi_u32 v2, v7, v2
	v_add_u32_e32 v2, v7, v2
	v_mul_hi_u32 v2, v8, v2
	v_mul_lo_u32 v6, v2, v5
	v_sub_u32_e32 v6, v8, v6
	v_add_u32_e32 v7, 1, v2
	v_cmp_ge_u32_e32 vcc, v6, v5
	s_nop 1
	v_cndmask_b32_e32 v2, v2, v7, vcc
	v_sub_u32_e32 v7, v6, v5
	v_cndmask_b32_e32 v6, v6, v7, vcc
	v_add_u32_e32 v7, 1, v2
	v_cmp_ge_u32_e32 vcc, v6, v5
	v_add_u32_e32 v6, 1, v8
	s_nop 0
	v_cndmask_b32_e32 v2, v2, v7, vcc
	v_mul_lo_u32 v7, v5, v2
	v_add_u32_e32 v5, v7, v5
	v_cmp_ne_u32_e32 vcc, v6, v5
	s_and_saveexec_b64 s[2:3], vcc
	s_xor_b64 s[12:13], exec, s[2:3]
	s_cbranch_execz .LBB0_674
	buffer_inv sc1
	s_waitcnt lgkmcnt(0)
	s_load_dwordx2 s[18:19], s[90:91], 0xb0
	s_waitcnt lgkmcnt(0)
	s_add_u32 s18, s18, 0x1d79b500
	s_addc_u32 s19, s19, 0
	v_mov_b32_e32 v4, 0
	global_load_dword v4, v4, s[18:19] sc1
	s_waitcnt vmcnt(0)
	v_cmp_eq_u32_e32 vcc, v4, v2
	s_and_saveexec_b64 s[14:15], vcc
	s_cbranch_execz .LBB0_673
	s_add_u32 s16, s4, 0x1d798200
	s_addc_u32 s17, s5, 0
	s_mov_b32 s2, 1
	s_mov_b64 s[20:21], 0
	s_branch .LBB0_664

; __device__ __forceinline__ unsigned xb_ld(unsigned* p)              { return __hip_atomic_load(p, __ATOMIC_RELAXED, __HIP_MEMORY_SCOPE_AGENT); }
; __device__ __forceinline__ unsigned xb_add(unsigned* p, unsigned v) { return __hip_atomic_fetch_add(p, v, __ATOMIC_RELAXED, __HIP_MEMORY_SCOPE_AGENT); }
; #define XB_SPIN(cond, bar) do { unsigned _sp = 0; while (cond) { __builtin_amdgcn_s_sleep(1); \
;     if ((++_sp & 255u) == 0u) { if (xb_ld(&(bar)[XB_TMO])) break; if (_sp > XB_SPIN_CAP) { atomicAdd(&(bar)[XB_TMO], 1u); break; } } } } while (0)
; __device__ __forceinline__ void xcd_barrier(const XcdBarrier& b, const bool leader) {
;     ...
;         if (old + 1u == (gen + 1u) * nloc) {
;             __builtin_amdgcn_fence(__ATOMIC_RELEASE, "agent");
;             asm volatile("s_waitcnt vmcnt(0)" ::: "memory");
;             const unsigned og = xb_add(&bar[XB_TOP], 1u);
;             const unsigned tg = og / nx;
;             if (og + 1u == (tg + 1u) * nx) xb_add(&bar[XB_TOPGEN], 1u);
;             else XB_SPIN(xb_ld(&bar[XB_TOPGEN]) == tg, bar);
;             __builtin_amdgcn_fence(__ATOMIC_ACQUIRE, "agent");
;             xb_add(&bar[XB_XGEN(b.x)], 1u);
;             asm volatile("s_waitcnt vmcnt(0)" ::: "memory");
;         } else {
;             XB_SPIN(xb_ld(&bar[XB_XGEN(b.x)]) == gen, bar);
;             __builtin_amdgcn_fence(__ATOMIC_ACQUIRE, "agent");
;             asm volatile("s_waitcnt vmcnt(0)" ::: "memory");
.LBB0_674:
	s_andn2_saveexec_b64 s[2:3], s[12:13]
	s_cbranch_execz .LBB0_694
	s_mov_b64 s[12:13], exec
	buffer_wbl2 sc1
	buffer_inv sc1
	s_waitcnt lgkmcnt(0)
	s_waitcnt vmcnt(0)
	v_mbcnt_lo_u32_b32 v2, s12, 0
	v_mbcnt_hi_u32_b32 v2, s13, v2
	v_cmp_eq_u32_e32 vcc, 0, v2
	s_and_saveexec_b64 s[14:15], vcc
	s_cbranch_execz .LBB0_677
	s_bcnt1_i32_b64 s2, s[12:13]
	v_mov_b32_e32 v5, s2
	global_atomic_add v5, v203, v5, s[4:5] offset:1024 sc0

; __device__ __forceinline__ unsigned xb_add(unsigned* p, unsigned v) { return __hip_atomic_fetch_add(p, v, __ATOMIC_RELAXED, __HIP_MEMORY_SCOPE_AGENT); }
; __device__ __forceinline__ void xcd_barrier(const XcdBarrier& b, const bool leader) {
;     ...
;             __builtin_amdgcn_fence(__ATOMIC_ACQUIRE, "agent");
;             xb_add(&bar[XB_XGEN(b.x)], 1u);
;             asm volatile("s_waitcnt vmcnt(0)" ::: "memory");
.LBB0_691:
	s_or_b64 exec, exec, s[4:5]
	s_mov_b64 s[4:5], exec
	v_mbcnt_lo_u32_b32 v2, s4, 0
	v_mbcnt_hi_u32_b32 v2, s5, v2
	v_cmp_eq_u32_e32 vcc, 0, v2
	s_waitcnt vmcnt(0)
	s_and_saveexec_b64 s[6:7], vcc
	s_cbranch_execz .LBB0_693
	s_bcnt1_i32_b64 s2, s[4:5]
	v_mov_b32_e32 v2, s2
	global_atomic_add v202, v2, s[10:11] offset:1024
.LBB0_693:
	s_or_b64 exec, exec, s[6:7]
	s_waitcnt vmcnt(0)

; __device__ __forceinline__ unsigned xb_add(unsigned* p, unsigned v) { return __hip_atomic_fetch_add(p, v, __ATOMIC_RELAXED, __HIP_MEMORY_SCOPE_AGENT); }
; __device__ __forceinline__ void xcd_barrier(const XcdBarrier& b, const bool leader) {
;     ...
;             __builtin_amdgcn_fence(__ATOMIC_ACQUIRE, "agent");
;             xb_add(&bar[XB_XGEN(b.x)], 1u);
;             asm volatile("s_waitcnt vmcnt(0)" ::: "memory");
.LBB0_748:
	s_or_b64 exec, exec, s[4:5]
	s_mov_b64 s[4:5], exec
	v_mbcnt_lo_u32_b32 v2, s4, 0
	v_mbcnt_hi_u32_b32 v2, s5, v2
	v_cmp_eq_u32_e32 vcc, 0, v2
	s_waitcnt vmcnt(0)
	s_and_saveexec_b64 s[6:7], vcc
	s_cbranch_execz .LBB0_750
	s_bcnt1_i32_b64 s2, s[4:5]
	v_mov_b32_e32 v2, s2
	global_atomic_add v202, v2, s[10:11] offset:1024
.LBB0_750:
	s_or_b64 exec, exec, s[6:7]
	s_waitcnt vmcnt(0)

; #define PG8_STAGE(bufoff, gbase, voff) do { _Pragma("unroll") for (int _i = 0; _i < 2; ++_i) \
;         __builtin_amdgcn_global_load_lds((const unsigned*)((const char*)(gbase) + (voff)[_i]), (PG8_LAS unsigned*)(lds + (bufoff) + ldsw + _i * 8192), 16, 0, 0); } while (0)
; #define PG8_LDA(dst, b, h) do { _Pragma("unroll") for (int m = 0; m < 4; ++m) _Pragma("unroll") for (int k = 0; k < 2; ++k) dst[m][k] = *(const PG8_LAS bf16x8*)(lds + PG8_SA(b, h) + aoff + m * 2048 + k * 1024); } while (0)
; #define PG8_LDB(dst, b, h) do { _Pragma("unroll") for (int n = 0; n < 2; ++n) _Pragma("unroll") for (int k = 0; k < 2; ++k) dst[n][k] = *(const PG8_LAS bf16x8*)(lds + PG8_SB(b, h) + boff + n * 2048 + k * 1024); } while (0)
; #define PG8_MMA(ai, bj, At, Bt) do { __builtin_amdgcn_s_setprio(1); _Pragma("unroll") for (int m = 0; m < 4; ++m) _Pragma("unroll") for (int n = 0; n < 2; ++n) _Pragma("unroll") for (int k = 0; k < 2; ++k) \
;         acc[ai][bj][m][n] = __builtin_amdgcn_mfma_f32_16x16x32_bf16(Bt[n][k], At[m][k], acc[ai][bj][m][n], 0, 0, 0); __builtin_amdgcn_s_setprio(0); } while (0)
; #define PG8_WAIT_V(n) asm volatile("s_waitcnt vmcnt(" #n ")" ::: "memory")
; template <class Epi, class Sched, bool ALIGN_EPI = false, bool SP2 = false>
; __device__ __forceinline__ void gemm_phase(PG8_LAS unsigned char* lds, const Gemm g, const Sched& S, const Epi& E, const int tid_arg) {
;     ...
;         for (int t = 0; t < nt; t += 2) {
;             const bool last = (t == nt - 2);
;             const char* a1 = cA + (size_t)(t + 1) * kstep;
;             const char* a2 = last ? nA : cA + (size_t)(t + 2) * kstep; const char* b2 = last ? nB : cB + (size_t)(t + 2) * kstep;
;             const char* a3 = a2 + kstep; const char* b3 = b2 + kstep;
;             if (last && has_next) S.a_ready(nxt);
;             if constexpr (SP2) {
;             PG8_LDB(B0, 0, 0); PG8_LDB(B1, 0, 1); PG8_SCHED; PG8_LDA(At, 0, 0); PG8_STAGE(PG8_SA(1, 1), a1 + hstep, voffA);
;             PG8_WAIT_V(8); PG8_WAIT_L(0); PG8_BAR; PG8_MMA(0, 0, At, B0); PG8_MMA(0, 1, At, B1); PG8_BAR; PG8_SCHED;
;     ...
; #pragma unroll
;         for (int a = 0; a < 2; ++a)
; #pragma unroll
;             for (int b = 0; b < 2; ++b)
; #pragma unroll
;                 for (int m = 0; m < 4; ++m)
; #pragma unroll
;                     for (int n = 0; n < 2; ++n) acc[a][b][m][n] = (f32x4){0.f, 0.f, 0.f, 0.f};
.LBB0_763:
	s_ashr_i32 s27, s26, 31
	s_lshl_b64 s[28:29], s[26:27], 19
	s_add_u32 s28, s3, s28
	s_addc_u32 s29, s6, s29
	s_and_b64 s[30:31], s[10:11], exec
	s_cselect_b32 s27, s29, s5
	s_cselect_b32 s48, s28, s4
	s_ashr_i32 s25, s24, 31
	s_lshl_b64 s[30:31], s[24:25], 19
	s_add_u32 s30, s7, s30
	s_addc_u32 s31, s38, s31
	s_and_b64 s[36:37], s[10:11], exec
	s_cselect_b32 s25, s31, s35
	s_cselect_b32 s49, s30, s34
	s_add_u32 s4, s4, 0x40080
	s_addc_u32 s5, s5, 0
	s_add_u32 s50, s34, 0x100
	v_mov_b32_e32 v4, 0
	s_addc_u32 s51, s35, 0
	s_mov_b32 s52, -2
	v_mov_b32_e32 v5, v4
	v_mov_b32_e32 v6, v4
	v_mov_b32_e32 v7, v4
	v_mov_b32_e32 v8, v4
	v_mov_b32_e32 v9, v4
	v_mov_b32_e32 v10, v4
	v_mov_b32_e32 v11, v4
	v_mov_b32_e32 v20, v4
	v_mov_b32_e32 v21, v4
	v_mov_b32_e32 v22, v4
	v_mov_b32_e32 v23, v4
	v_mov_b32_e32 v24, v4
	v_mov_b32_e32 v25, v4
	v_mov_b32_e32 v26, v4
	v_mov_b32_e32 v27, v4
	v_mov_b32_e32 v36, v4
	v_mov_b32_e32 v37, v4
	v_mov_b32_e32 v38, v4
	v_mov_b32_e32 v39, v4
	v_mov_b32_e32 v40, v4
	v_mov_b32_e32 v41, v4
	v_mov_b32_e32 v42, v4
	v_mov_b32_e32 v43, v4
	v_mov_b32_e32 v52, v4
	v_mov_b32_e32 v53, v4
	v_mov_b32_e32 v54, v4
	v_mov_b32_e32 v55, v4
	v_mov_b32_e32 v56, v4
	v_mov_b32_e32 v57, v4
	v_mov_b32_e32 v58, v4
	v_mov_b32_e32 v59, v4
	v_mov_b32_e32 v12, v4
	v_mov_b32_e32 v13, v4
	v_mov_b32_e32 v14, v4
	v_mov_b32_e32 v15, v4
	v_mov_b32_e32 v16, v4
	v_mov_b32_e32 v17, v4
	v_mov_b32_e32 v18, v4
	v_mov_b32_e32 v19, v4
	v_mov_b32_e32 v28, v4
	v_mov_b32_e32 v29, v4
	v_mov_b32_e32 v30, v4
	v_mov_b32_e32 v31, v4
	v_mov_b32_e32 v32, v4
	v_mov_b32_e32 v33, v4
	v_mov_b32_e32 v34, v4
	v_mov_b32_e32 v35, v4
	v_mov_b32_e32 v44, v4
	v_mov_b32_e32 v45, v4
	v_mov_b32_e32 v46, v4
	v_mov_b32_e32 v47, v4
	v_mov_b32_e32 v48, v4
	v_mov_b32_e32 v49, v4
	v_mov_b32_e32 v50, v4
	v_mov_b32_e32 v51, v4
	v_mov_b32_e32 v60, v4
	v_mov_b32_e32 v61, v4
	v_mov_b32_e32 v62, v4
	v_mov_b32_e32 v63, v4
	v_mov_b32_e32 v64, v4
	v_mov_b32_e32 v65, v4
	v_mov_b32_e32 v66, v4
	v_mov_b32_e32 v67, v4
	v_mov_b32_e32 v68, v4
	v_mov_b32_e32 v69, v4
	v_mov_b32_e32 v70, v4
	v_mov_b32_e32 v71, v4
	v_mov_b32_e32 v72, v4
	v_mov_b32_e32 v73, v4
	v_mov_b32_e32 v74, v4
	v_mov_b32_e32 v75, v4
	v_mov_b32_e32 v84, v4
	v_mov_b32_e32 v85, v4
	v_mov_b32_e32 v86, v4
	v_mov_b32_e32 v87, v4
	v_mov_b32_e32 v88, v4
	v_mov_b32_e32 v89, v4
	v_mov_b32_e32 v90, v4
	v_mov_b32_e32 v91, v4
	v_mov_b32_e32 v100, v4
	v_mov_b32_e32 v101, v4
	v_mov_b32_e32 v102, v4
	v_mov_b32_e32 v103, v4
	v_mov_b32_e32 v104, v4
	v_mov_b32_e32 v105, v4
	v_mov_b32_e32 v106, v4
	v_mov_b32_e32 v107, v4
	v_mov_b32_e32 v116, v4
	v_mov_b32_e32 v117, v4
	v_mov_b32_e32 v118, v4
	v_mov_b32_e32 v119, v4
	s_waitcnt vmcnt(0)
	v_mov_b32_e32 v120, v4
	v_mov_b32_e32 v121, v4
	v_mov_b32_e32 v122, v4
	v_mov_b32_e32 v123, v4
	v_mov_b32_e32 v76, v4
	v_mov_b32_e32 v77, v4
	v_mov_b32_e32 v78, v4
	v_mov_b32_e32 v79, v4
	v_mov_b32_e32 v80, v4
	v_mov_b32_e32 v81, v4
	v_mov_b32_e32 v82, v4
	v_mov_b32_e32 v83, v4
	v_mov_b32_e32 v92, v4
	v_mov_b32_e32 v93, v4
	v_mov_b32_e32 v94, v4
	v_mov_b32_e32 v95, v4
	v_mov_b32_e32 v96, v4
	v_mov_b32_e32 v97, v4
	v_mov_b32_e32 v98, v4
	v_mov_b32_e32 v99, v4
	v_mov_b32_e32 v108, v4
	v_mov_b32_e32 v109, v4
	v_mov_b32_e32 v110, v4
	v_mov_b32_e32 v111, v4
	v_mov_b32_e32 v112, v4
	v_mov_b32_e32 v113, v4
	v_mov_b32_e32 v114, v4
	v_mov_b32_e32 v115, v4
	v_mov_b32_e32 v124, v4
	v_mov_b32_e32 v125, v4
	v_mov_b32_e32 v126, v4
	v_mov_b32_e32 v127, v4
	v_mov_b32_e32 v128, v4
	v_mov_b32_e32 v129, v4
	v_mov_b32_e32 v130, v4
	v_mov_b32_e32 v131, v4
	s_nop 0
	s_nop 0
	s_nop 0
	s_nop 0
	s_nop 0
	s_nop 0
	s_nop 0
	s_nop 0
	s_nop 0
	s_nop 0
	s_nop 0
	s_nop 0
.LBB0_764:
	s_add_u32 s34, s4, 0xfffc0080
	s_addc_u32 s35, s5, -1
	s_add_i32 s53, 0, 0x10000
	s_cmp_eq_u32 s52, 12
	s_cselect_b32 s37, s27, s35
	s_cselect_b32 s36, s48, s34
	s_cselect_b32 s35, s25, s51
	s_cselect_b32 s34, s49, s50
	s_add_i32 s56, 0, 0x14000
	v_add_u32_e32 v164, s53, v153
	v_add_u32_e32 v180, s56, v153
	ds_read_b128 v[148:151], v164
	ds_read_b128 v[156:159], v164 offset:1024
	ds_read_b128 v[160:163], v164 offset:2048
	ds_read_b128 v[164:167], v164 offset:3072
	ds_read_b128 v[168:171], v180
	ds_read_b128 v[172:175], v180 offset:1024
	ds_read_b128 v[176:179], v180 offset:2048
	ds_read_b128 v[182:185], v180 offset:3072
	v_lshl_add_u64 v[194:195], s[4:5], 0, v[138:139]
	s_add_i32 m0, s40, 0xc000
	ds_read_b128 v[186:189], v155
	ds_read_b128 v[190:193], v155 offset:1024
	ds_read_b128 v[210:213], v155 offset:2048
	ds_read_b128 v[214:217], v155 offset:3072
	ds_read_b128 v[218:221], v155 offset:4096
	ds_read_b128 v[222:225], v155 offset:5120
	ds_read_b128 v[226:229], v155 offset:6144
	ds_read_b128 v[230:233], v155 offset:7168
	global_load_lds_dwordx4 v[194:195], off
	v_lshl_add_u64 v[194:195], s[4:5], 0, v[146:147]
	s_add_i32 m0, s40, 0xe000
	s_nop 0
	global_load_lds_dwordx4 v[194:195], off
	s_waitcnt vmcnt(8)
	s_waitcnt lgkmcnt(0)
	s_barrier
; #define PG8_STAGE(bufoff, gbase, voff) do { _Pragma("unroll") for (int _i = 0; _i < 2; ++_i) \
;         __builtin_amdgcn_global_load_lds((const unsigned*)((const char*)(gbase) + (voff)[_i]), (PG8_LAS unsigned*)(lds + (bufoff) + ldsw + _i * 8192), 16, 0, 0); } while (0)
; #define PG8_LDA(dst, b, h) do { _Pragma("unroll") for (int m = 0; m < 4; ++m) _Pragma("unroll") for (int k = 0; k < 2; ++k) dst[m][k] = *(const PG8_LAS bf16x8*)(lds + PG8_SA(b, h) + aoff + m * 2048 + k * 1024); } while (0)
; #define PG8_MMA(ai, bj, At, Bt) do { __builtin_amdgcn_s_setprio(1); _Pragma("unroll") for (int m = 0; m < 4; ++m) _Pragma("unroll") for (int n = 0; n < 2; ++n) _Pragma("unroll") for (int k = 0; k < 2; ++k) \
;         acc[ai][bj][m][n] = __builtin_amdgcn_mfma_f32_16x16x32_bf16(Bt[n][k], At[m][k], acc[ai][bj][m][n], 0, 0, 0); __builtin_amdgcn_s_setprio(0); } while (0)
; #define PG8_WAIT_V(n) asm volatile("s_waitcnt vmcnt(" #n ")" ::: "memory")
; #define PG8_WAIT_L(n) asm volatile("s_waitcnt lgkmcnt(" #n ")" ::: "memory")
; #define PG8_BAR __builtin_amdgcn_s_barrier()
; #define PG8_SCHED __builtin_amdgcn_sched_barrier(0)
; template <class Epi, class Sched, bool ALIGN_EPI = false, bool SP2 = false>
; __device__ __forceinline__ void gemm_phase(PG8_LAS unsigned char* lds, const Gemm g, const Sched& S, const Epi& E, const int tid_arg) {
;     ...
;             PG8_WAIT_V(8); PG8_WAIT_L(0); PG8_BAR; PG8_MMA(0, 0, At, B0); PG8_MMA(0, 1, At, B1); PG8_BAR; PG8_SCHED;
;             PG8_LDA(At, 0, 1); PG8_STAGE(PG8_SB(0, 0), b2, voffB); PG8_STAGE(PG8_SB(0, 1), b2 + hstep, voffB); PG8_STAGE(PG8_SA(0, 0), a2, voffA);
;             PG8_WAIT_V(8); PG8_WAIT_L(0); PG8_BAR; PG8_MMA(1, 0, At, B0); PG8_MMA(1, 1, At, B1); PG8_BAR; PG8_SCHED;
	s_setprio 1
	s_waitcnt lgkmcnt(0)
	v_mfma_f32_16x16x32_bf16 v[128:131], v[148:151], v[186:189], v[128:131]
	v_mfma_f32_16x16x32_bf16 v[124:127], v[160:163], v[186:189], v[124:127]
	v_mfma_f32_16x16x32_bf16 v[112:115], v[148:151], v[210:213], v[112:115]
	v_mfma_f32_16x16x32_bf16 v[108:111], v[160:163], v[210:213], v[108:111]
	v_mfma_f32_16x16x32_bf16 v[96:99], v[148:151], v[218:221], v[96:99]
	v_mfma_f32_16x16x32_bf16 v[92:95], v[160:163], v[218:221], v[92:95]
	v_mfma_f32_16x16x32_bf16 v[80:83], v[148:151], v[226:229], v[80:83]
	v_mfma_f32_16x16x32_bf16 v[76:79], v[160:163], v[226:229], v[76:79]
	v_mfma_f32_16x16x32_bf16 v[128:131], v[156:159], v[190:193], v[128:131]
	v_mfma_f32_16x16x32_bf16 v[124:127], v[164:167], v[190:193], v[124:127]
	v_mfma_f32_16x16x32_bf16 v[112:115], v[156:159], v[214:217], v[112:115]
	v_mfma_f32_16x16x32_bf16 v[108:111], v[164:167], v[214:217], v[108:111]
	v_mfma_f32_16x16x32_bf16 v[96:99], v[156:159], v[222:225], v[96:99]
	v_mfma_f32_16x16x32_bf16 v[92:95], v[164:167], v[222:225], v[92:95]
	v_mfma_f32_16x16x32_bf16 v[80:83], v[156:159], v[230:233], v[80:83]
	v_mfma_f32_16x16x32_bf16 v[76:79], v[164:167], v[230:233], v[76:79]
	s_setprio 0
	s_setprio 1
	v_mfma_f32_16x16x32_bf16 v[120:123], v[168:171], v[186:189], v[120:123]
	v_mfma_f32_16x16x32_bf16 v[116:119], v[176:179], v[186:189], v[116:119]
	v_mfma_f32_16x16x32_bf16 v[104:107], v[168:171], v[210:213], v[104:107]
	v_mfma_f32_16x16x32_bf16 v[100:103], v[176:179], v[210:213], v[100:103]
	v_mfma_f32_16x16x32_bf16 v[88:91], v[168:171], v[218:221], v[88:91]
	v_mfma_f32_16x16x32_bf16 v[84:87], v[176:179], v[218:221], v[84:87]
	v_mfma_f32_16x16x32_bf16 v[72:75], v[168:171], v[226:229], v[72:75]
	v_mfma_f32_16x16x32_bf16 v[68:71], v[176:179], v[226:229], v[68:71]
	v_mfma_f32_16x16x32_bf16 v[120:123], v[172:175], v[190:193], v[120:123]
	v_mfma_f32_16x16x32_bf16 v[116:119], v[182:185], v[190:193], v[116:119]
	v_mfma_f32_16x16x32_bf16 v[104:107], v[172:175], v[214:217], v[104:107]
	v_mfma_f32_16x16x32_bf16 v[100:103], v[182:185], v[214:217], v[100:103]
	v_mfma_f32_16x16x32_bf16 v[88:91], v[172:175], v[222:225], v[88:91]
	v_mfma_f32_16x16x32_bf16 v[84:87], v[182:185], v[222:225], v[84:87]
	v_mfma_f32_16x16x32_bf16 v[72:75], v[172:175], v[230:233], v[72:75]
	v_mfma_f32_16x16x32_bf16 v[68:71], v[182:185], v[230:233], v[68:71]
	s_setprio 0
	s_barrier
	s_add_i32 s53, s53, s39
	v_lshl_add_u64 v[194:195], s[34:35], 0, v[2:3]
	s_mov_b32 m0, s53
	ds_read_b128 v[186:189], v155 offset:16384
	ds_read_b128 v[190:193], v155 offset:17408
	ds_read_b128 v[210:213], v155 offset:18432
	ds_read_b128 v[214:217], v155 offset:19456
	ds_read_b128 v[218:221], v155 offset:20480
	ds_read_b128 v[222:225], v155 offset:21504
	ds_read_b128 v[226:229], v155 offset:22528
	ds_read_b128 v[230:233], v155 offset:23552
	global_load_lds_dwordx4 v[194:195], off
	s_add_i32 m0, s53, 0x2000
	s_add_u32 s54, s34, 0x40000
	v_lshl_add_u64 v[234:235], s[34:35], 0, v[132:133]
	s_addc_u32 s55, s35, 0
	s_add_i32 s53, s56, s39
	global_load_lds_dwordx4 v[234:235], off
	v_lshl_add_u64 v[236:237], s[54:55], 0, v[2:3]
	s_mov_b32 m0, s53
	v_lshl_add_u64 v[238:239], s[36:37], 0, v[134:135]
	global_load_lds_dwordx4 v[236:237], off
	v_lshl_add_u64 v[236:237], s[54:55], 0, v[132:133]
	s_add_i32 m0, s53, 0x2000
	s_nop 0
	global_load_lds_dwordx4 v[236:237], off
	v_lshl_add_u64 v[236:237], s[36:37], 0, v[136:137]
	s_mov_b32 m0, s40
	s_nop 0
	global_load_lds_dwordx4 v[236:237], off
	s_mov_b32 m0, s41
	s_nop 0
	global_load_lds_dwordx4 v[238:239], off
	s_waitcnt vmcnt(8)
	s_waitcnt lgkmcnt(0)
	s_barrier
	s_setprio 1
	s_waitcnt lgkmcnt(0)
	v_mfma_f32_16x16x32_bf16 v[64:67], v[148:151], v[186:189], v[64:67]
	v_mfma_f32_16x16x32_bf16 v[60:63], v[160:163], v[186:189], v[60:63]
	v_mfma_f32_16x16x32_bf16 v[48:51], v[148:151], v[210:213], v[48:51]
	v_mfma_f32_16x16x32_bf16 v[44:47], v[160:163], v[210:213], v[44:47]
	v_mfma_f32_16x16x32_bf16 v[32:35], v[148:151], v[218:221], v[32:35]
	v_mfma_f32_16x16x32_bf16 v[28:31], v[160:163], v[218:221], v[28:31]
	v_mfma_f32_16x16x32_bf16 v[16:19], v[148:151], v[226:229], v[16:19]
	v_mfma_f32_16x16x32_bf16 v[12:15], v[160:163], v[226:229], v[12:15]
	v_mfma_f32_16x16x32_bf16 v[64:67], v[156:159], v[190:193], v[64:67]
	v_mfma_f32_16x16x32_bf16 v[60:63], v[164:167], v[190:193], v[60:63]
	v_mfma_f32_16x16x32_bf16 v[48:51], v[156:159], v[214:217], v[48:51]
	v_mfma_f32_16x16x32_bf16 v[44:47], v[164:167], v[214:217], v[44:47]
	v_mfma_f32_16x16x32_bf16 v[32:35], v[156:159], v[222:225], v[32:35]
	v_mfma_f32_16x16x32_bf16 v[28:31], v[164:167], v[222:225], v[28:31]
	v_mfma_f32_16x16x32_bf16 v[16:19], v[156:159], v[230:233], v[16:19]
	v_mfma_f32_16x16x32_bf16 v[12:15], v[164:167], v[230:233], v[12:15]
	s_setprio 0
	s_setprio 1
	v_mfma_f32_16x16x32_bf16 v[56:59], v[168:171], v[186:189], v[56:59]
	v_mfma_f32_16x16x32_bf16 v[52:55], v[176:179], v[186:189], v[52:55]
	v_mfma_f32_16x16x32_bf16 v[40:43], v[168:171], v[210:213], v[40:43]
	v_mfma_f32_16x16x32_bf16 v[36:39], v[176:179], v[210:213], v[36:39]
	v_mfma_f32_16x16x32_bf16 v[24:27], v[168:171], v[218:221], v[24:27]
	v_mfma_f32_16x16x32_bf16 v[20:23], v[176:179], v[218:221], v[20:23]
	v_mfma_f32_16x16x32_bf16 v[8:11], v[168:171], v[226:229], v[8:11]
	v_mfma_f32_16x16x32_bf16 v[4:7], v[176:179], v[226:229], v[4:7]
	v_mfma_f32_16x16x32_bf16 v[56:59], v[172:175], v[190:193], v[56:59]
	v_mfma_f32_16x16x32_bf16 v[52:55], v[182:185], v[190:193], v[52:55]
	v_mfma_f32_16x16x32_bf16 v[40:43], v[172:175], v[214:217], v[40:43]
	v_mfma_f32_16x16x32_bf16 v[36:39], v[182:185], v[214:217], v[36:39]
	v_mfma_f32_16x16x32_bf16 v[24:27], v[172:175], v[222:225], v[24:27]
	v_mfma_f32_16x16x32_bf16 v[20:23], v[182:185], v[222:225], v[20:23]
	v_mfma_f32_16x16x32_bf16 v[8:11], v[172:175], v[230:233], v[8:11]
	v_mfma_f32_16x16x32_bf16 v[4:7], v[182:185], v[230:233], v[4:7]
	s_setprio 0
	s_barrier
; #define PG8_STAGE(bufoff, gbase, voff) do { _Pragma("unroll") for (int _i = 0; _i < 2; ++_i) \
;         __builtin_amdgcn_global_load_lds((const unsigned*)((const char*)(gbase) + (voff)[_i]), (PG8_LAS unsigned*)(lds + (bufoff) + ldsw + _i * 8192), 16, 0, 0); } while (0)
; #define PG8_LDA(dst, b, h) do { _Pragma("unroll") for (int m = 0; m < 4; ++m) _Pragma("unroll") for (int k = 0; k < 2; ++k) dst[m][k] = *(const PG8_LAS bf16x8*)(lds + PG8_SA(b, h) + aoff + m * 2048 + k * 1024); } while (0)
; #define PG8_LDB(dst, b, h) do { _Pragma("unroll") for (int n = 0; n < 2; ++n) _Pragma("unroll") for (int k = 0; k < 2; ++k) dst[n][k] = *(const PG8_LAS bf16x8*)(lds + PG8_SB(b, h) + boff + n * 2048 + k * 1024); } while (0)
; #define PG8_MMA(ai, bj, At, Bt) do { __builtin_amdgcn_s_setprio(1); _Pragma("unroll") for (int m = 0; m < 4; ++m) _Pragma("unroll") for (int n = 0; n < 2; ++n) _Pragma("unroll") for (int k = 0; k < 2; ++k) \
;         acc[ai][bj][m][n] = __builtin_amdgcn_mfma_f32_16x16x32_bf16(Bt[n][k], At[m][k], acc[ai][bj][m][n], 0, 0, 0); __builtin_amdgcn_s_setprio(0); } while (0)
; #define PG8_WAIT_V(n) asm volatile("s_waitcnt vmcnt(" #n ")" ::: "memory")
; #define PG8_WAIT_L(n) asm volatile("s_waitcnt lgkmcnt(" #n ")" ::: "memory")
; #define PG8_BAR __builtin_amdgcn_s_barrier()
; #define PG8_SCHED __builtin_amdgcn_sched_barrier(0)
; template <class Epi, class Sched, bool ALIGN_EPI = false, bool SP2 = false>
; __device__ __forceinline__ void gemm_phase(PG8_LAS unsigned char* lds, const Gemm g, const Sched& S, const Epi& E, const int tid_arg) {
;     ...
;             PG8_LDB(B0, 1, 0); PG8_LDB(B1, 1, 1); PG8_SCHED; PG8_LDA(At, 1, 0); PG8_STAGE(PG8_SA(0, 1), a2 + hstep, voffA);
;             PG8_WAIT_V(8); PG8_WAIT_L(0); PG8_BAR; PG8_MMA(0, 0, At, B0); PG8_MMA(0, 1, At, B1); PG8_BAR; PG8_SCHED;
	s_add_i32 s53, 0, 0x18000
	s_add_i32 s54, 0, 0x1c000
	v_add_u32_e32 v164, s53, v153
	v_add_u32_e32 v180, s54, v153
	ds_read_b128 v[148:151], v164
	ds_read_b128 v[156:159], v164 offset:1024
	ds_read_b128 v[160:163], v164 offset:2048
	ds_read_b128 v[164:167], v164 offset:3072
	ds_read_b128 v[168:171], v180
	ds_read_b128 v[172:175], v180 offset:1024
	ds_read_b128 v[176:179], v180 offset:2048
	ds_read_b128 v[182:185], v180 offset:3072
	s_add_u32 s36, s36, 0x40000
	s_addc_u32 s37, s37, 0
	s_mov_b32 m0, s42
	v_lshl_add_u64 v[240:241], s[36:37], 0, v[136:137]
	ds_read_b128 v[186:189], v155 offset:32768
	ds_read_b128 v[190:193], v155 offset:33792
	ds_read_b128 v[210:213], v155 offset:34816
	ds_read_b128 v[214:217], v155 offset:35840
	ds_read_b128 v[218:221], v155 offset:36864
	ds_read_b128 v[222:225], v155 offset:37888
	ds_read_b128 v[226:229], v155 offset:38912
	ds_read_b128 v[230:233], v155 offset:39936
	global_load_lds_dwordx4 v[240:241], off
	v_lshl_add_u64 v[240:241], s[36:37], 0, v[134:135]
	s_mov_b32 m0, s43
	s_nop 0
	global_load_lds_dwordx4 v[240:241], off
	s_waitcnt vmcnt(8)
	s_waitcnt lgkmcnt(0)
	s_barrier
	s_setprio 1
	s_waitcnt lgkmcnt(0)
	v_mfma_f32_16x16x32_bf16 v[128:131], v[148:151], v[186:189], v[128:131]
	v_mfma_f32_16x16x32_bf16 v[124:127], v[160:163], v[186:189], v[124:127]
	v_mfma_f32_16x16x32_bf16 v[112:115], v[148:151], v[210:213], v[112:115]
	v_mfma_f32_16x16x32_bf16 v[108:111], v[160:163], v[210:213], v[108:111]
	v_mfma_f32_16x16x32_bf16 v[96:99], v[148:151], v[218:221], v[96:99]
	v_mfma_f32_16x16x32_bf16 v[92:95], v[160:163], v[218:221], v[92:95]
	v_mfma_f32_16x16x32_bf16 v[80:83], v[148:151], v[226:229], v[80:83]
	v_mfma_f32_16x16x32_bf16 v[76:79], v[160:163], v[226:229], v[76:79]
	v_mfma_f32_16x16x32_bf16 v[128:131], v[156:159], v[190:193], v[128:131]
	v_mfma_f32_16x16x32_bf16 v[124:127], v[164:167], v[190:193], v[124:127]
	v_mfma_f32_16x16x32_bf16 v[112:115], v[156:159], v[214:217], v[112:115]
	v_mfma_f32_16x16x32_bf16 v[108:111], v[164:167], v[214:217], v[108:111]
	v_mfma_f32_16x16x32_bf16 v[96:99], v[156:159], v[222:225], v[96:99]
	v_mfma_f32_16x16x32_bf16 v[92:95], v[164:167], v[222:225], v[92:95]
	v_mfma_f32_16x16x32_bf16 v[80:83], v[156:159], v[230:233], v[80:83]
	v_mfma_f32_16x16x32_bf16 v[76:79], v[164:167], v[230:233], v[76:79]
	s_setprio 0
	s_setprio 1
	v_mfma_f32_16x16x32_bf16 v[120:123], v[168:171], v[186:189], v[120:123]
	v_mfma_f32_16x16x32_bf16 v[116:119], v[176:179], v[186:189], v[116:119]
	v_mfma_f32_16x16x32_bf16 v[104:107], v[168:171], v[210:213], v[104:107]
	v_mfma_f32_16x16x32_bf16 v[100:103], v[176:179], v[210:213], v[100:103]
	v_mfma_f32_16x16x32_bf16 v[88:91], v[168:171], v[218:221], v[88:91]
	v_mfma_f32_16x16x32_bf16 v[84:87], v[176:179], v[218:221], v[84:87]
	v_mfma_f32_16x16x32_bf16 v[72:75], v[168:171], v[226:229], v[72:75]
	v_mfma_f32_16x16x32_bf16 v[68:71], v[176:179], v[226:229], v[68:71]
	v_mfma_f32_16x16x32_bf16 v[120:123], v[172:175], v[190:193], v[120:123]
	v_mfma_f32_16x16x32_bf16 v[116:119], v[182:185], v[190:193], v[116:119]
	v_mfma_f32_16x16x32_bf16 v[104:107], v[172:175], v[214:217], v[104:107]
	v_mfma_f32_16x16x32_bf16 v[100:103], v[182:185], v[214:217], v[100:103]
	v_mfma_f32_16x16x32_bf16 v[88:91], v[172:175], v[222:225], v[88:91]
	v_mfma_f32_16x16x32_bf16 v[84:87], v[182:185], v[222:225], v[84:87]
	v_mfma_f32_16x16x32_bf16 v[72:75], v[172:175], v[230:233], v[72:75]
	v_mfma_f32_16x16x32_bf16 v[68:71], v[182:185], v[230:233], v[68:71]
	s_setprio 0
	s_barrier
; #define PG8_STAGE(bufoff, gbase, voff) do { _Pragma("unroll") for (int _i = 0; _i < 2; ++_i) \
;         __builtin_amdgcn_global_load_lds((const unsigned*)((const char*)(gbase) + (voff)[_i]), (PG8_LAS unsigned*)(lds + (bufoff) + ldsw + _i * 8192), 16, 0, 0); } while (0)
; #define PG8_LDA(dst, b, h) do { _Pragma("unroll") for (int m = 0; m < 4; ++m) _Pragma("unroll") for (int k = 0; k < 2; ++k) dst[m][k] = *(const PG8_LAS bf16x8*)(lds + PG8_SA(b, h) + aoff + m * 2048 + k * 1024); } while (0)
; #define PG8_WAIT_V(n) asm volatile("s_waitcnt vmcnt(" #n ")" ::: "memory")
; #define PG8_WAIT_L(n) asm volatile("s_waitcnt lgkmcnt(" #n ")" ::: "memory")
; template <class Epi, class Sched, bool ALIGN_EPI = false, bool SP2 = false>
; __device__ __forceinline__ void gemm_phase(PG8_LAS unsigned char* lds, const Gemm g, const Sched& S, const Epi& E, const int tid_arg) {
;     ...
;         for (int t = 0; t < nt; t += 2) {
;             const bool last = (t == nt - 2);
;             const char* a1 = cA + (size_t)(t + 1) * kstep;
;             const char* a2 = last ? nA : cA + (size_t)(t + 2) * kstep; const char* b2 = last ? nB : cB + (size_t)(t + 2) * kstep;
;             const char* a3 = a2 + kstep; const char* b3 = b2 + kstep;
;             if (last && has_next) S.a_ready(nxt);
;             if constexpr (SP2) {
;             PG8_LDB(B0, 0, 0); PG8_LDB(B1, 0, 1); PG8_SCHED; PG8_LDA(At, 0, 0); PG8_STAGE(PG8_SA(1, 1), a1 + hstep, voffA);
;             PG8_WAIT_V(8); PG8_WAIT_L(0); PG8_BAR; PG8_MMA(0, 0, At, B0); PG8_MMA(0, 1, At, B1); PG8_BAR; PG8_SCHED;
;             PG8_LDA(At, 0, 1); PG8_STAGE(PG8_SB(0, 0), b2, voffB); PG8_STAGE(PG8_SB(0, 1), b2 + hstep, voffB); PG8_STAGE(PG8_SA(0, 0), a2, voffA);
;             PG8_WAIT_V(8); PG8_WAIT_L(0); PG8_BAR; PG8_MMA(1, 0, At, B0); PG8_MMA(1, 1, At, B1); PG8_BAR; PG8_SCHED;
;             PG8_LDB(B0, 1, 0); PG8_LDB(B1, 1, 1); PG8_SCHED; PG8_LDA(At, 1, 0); PG8_STAGE(PG8_SA(0, 1), a2 + hstep, voffA);
;             PG8_WAIT_V(8); PG8_WAIT_L(0); PG8_BAR; PG8_MMA(0, 0, At, B0); PG8_MMA(0, 1, At, B1); PG8_BAR; PG8_SCHED;
;             PG8_LDA(At, 1, 1); PG8_STAGE(PG8_SB(1, 0), b3, voffB); PG8_STAGE(PG8_SB(1, 1), b3 + hstep, voffB); PG8_STAGE(PG8_SA(1, 0), a3, voffA);
;             PG8_WAIT_V(8); PG8_WAIT_L(0); PG8_BAR; PG8_MMA(1, 0, At, B0); PG8_MMA(1, 1, At, B1); PG8_BAR; PG8_SCHED;
;     ...
;         if constexpr (ALIGN_EPI) { if (wr == 0) PG8_BAR; }
	s_add_i32 s36, s53, s39
	v_lshl_add_u64 v[194:195], v[194:195], 0, s[76:77]
	s_mov_b32 m0, s36
	ds_read_b128 v[186:189], v155 offset:49152
	ds_read_b128 v[190:193], v155 offset:50176
	ds_read_b128 v[210:213], v155 offset:51200
	ds_read_b128 v[214:217], v155 offset:52224
	ds_read_b128 v[218:221], v155 offset:53248
	ds_read_b128 v[222:225], v155 offset:54272
	ds_read_b128 v[226:229], v155 offset:55296
	ds_read_b128 v[230:233], v155 offset:56320
	global_load_lds_dwordx4 v[194:195], off
	s_add_i32 m0, s36, 0x2000
	s_add_u32 s34, s34, 0x40080
	v_lshl_add_u64 v[194:195], v[234:235], 0, s[76:77]
	s_addc_u32 s35, s35, 0
	s_add_i32 s36, s54, s39
	global_load_lds_dwordx4 v[194:195], off
	v_lshl_add_u64 v[194:195], s[34:35], 0, v[2:3]
	s_mov_b32 m0, s36
	s_nop 0
	global_load_lds_dwordx4 v[194:195], off
	v_lshl_add_u64 v[194:195], s[34:35], 0, v[132:133]
	s_add_i32 m0, s36, 0x2000
	s_nop 0
	global_load_lds_dwordx4 v[194:195], off
	v_lshl_add_u64 v[194:195], v[236:237], 0, s[76:77]
	s_mov_b32 m0, s44
	s_nop 0
	global_load_lds_dwordx4 v[194:195], off
	v_lshl_add_u64 v[194:195], v[238:239], 0, s[76:77]
	s_mov_b32 m0, s45
	s_nop 0
	global_load_lds_dwordx4 v[194:195], off
	s_waitcnt vmcnt(8)
	s_waitcnt lgkmcnt(0)
	s_barrier
	s_setprio 1
	s_waitcnt lgkmcnt(0)
	v_mfma_f32_16x16x32_bf16 v[64:67], v[148:151], v[186:189], v[64:67]
	v_mfma_f32_16x16x32_bf16 v[60:63], v[160:163], v[186:189], v[60:63]
	v_mfma_f32_16x16x32_bf16 v[48:51], v[148:151], v[210:213], v[48:51]
	v_mfma_f32_16x16x32_bf16 v[44:47], v[160:163], v[210:213], v[44:47]
	v_mfma_f32_16x16x32_bf16 v[32:35], v[148:151], v[218:221], v[32:35]
	v_mfma_f32_16x16x32_bf16 v[28:31], v[160:163], v[218:221], v[28:31]
	v_mfma_f32_16x16x32_bf16 v[16:19], v[148:151], v[226:229], v[16:19]
	v_mfma_f32_16x16x32_bf16 v[12:15], v[160:163], v[226:229], v[12:15]
	v_mfma_f32_16x16x32_bf16 v[64:67], v[156:159], v[190:193], v[64:67]
	v_mfma_f32_16x16x32_bf16 v[60:63], v[164:167], v[190:193], v[60:63]
	v_mfma_f32_16x16x32_bf16 v[48:51], v[156:159], v[214:217], v[48:51]
	v_mfma_f32_16x16x32_bf16 v[44:47], v[164:167], v[214:217], v[44:47]
	v_mfma_f32_16x16x32_bf16 v[32:35], v[156:159], v[222:225], v[32:35]
	v_mfma_f32_16x16x32_bf16 v[28:31], v[164:167], v[222:225], v[28:31]
	v_mfma_f32_16x16x32_bf16 v[16:19], v[156:159], v[230:233], v[16:19]
	v_mfma_f32_16x16x32_bf16 v[12:15], v[164:167], v[230:233], v[12:15]
	s_setprio 0
	s_setprio 1
	v_mfma_f32_16x16x32_bf16 v[56:59], v[168:171], v[186:189], v[56:59]
	v_mfma_f32_16x16x32_bf16 v[52:55], v[176:179], v[186:189], v[52:55]
	v_mfma_f32_16x16x32_bf16 v[40:43], v[168:171], v[210:213], v[40:43]
	v_mfma_f32_16x16x32_bf16 v[36:39], v[176:179], v[210:213], v[36:39]
	v_mfma_f32_16x16x32_bf16 v[24:27], v[168:171], v[218:221], v[24:27]
	v_mfma_f32_16x16x32_bf16 v[20:23], v[176:179], v[218:221], v[20:23]
	v_mfma_f32_16x16x32_bf16 v[8:11], v[168:171], v[226:229], v[8:11]
	v_mfma_f32_16x16x32_bf16 v[4:7], v[176:179], v[226:229], v[4:7]
	v_mfma_f32_16x16x32_bf16 v[56:59], v[172:175], v[190:193], v[56:59]
	v_mfma_f32_16x16x32_bf16 v[52:55], v[182:185], v[190:193], v[52:55]
	v_mfma_f32_16x16x32_bf16 v[40:43], v[172:175], v[214:217], v[40:43]
	v_mfma_f32_16x16x32_bf16 v[36:39], v[182:185], v[214:217], v[36:39]
	v_mfma_f32_16x16x32_bf16 v[24:27], v[172:175], v[222:225], v[24:27]
	v_mfma_f32_16x16x32_bf16 v[20:23], v[182:185], v[222:225], v[20:23]
	v_mfma_f32_16x16x32_bf16 v[8:11], v[172:175], v[230:233], v[8:11]
	v_mfma_f32_16x16x32_bf16 v[4:7], v[182:185], v[230:233], v[4:7]
	s_setprio 0
	s_barrier
	s_add_i32 s52, s52, 2
	s_add_u32 s4, s4, 0x100
	s_addc_u32 s5, s5, 0
	s_add_u32 s50, s50, 0x100
	s_addc_u32 s51, s51, 0
	s_cmp_gt_u32 s52, 13
	s_cbranch_scc0 .LBB0_764
	s_and_b64 vcc, exec, s[22:23]
	s_cbranch_vccz .LBB0_767
	s_barrier

; __device__ __forceinline__ unsigned xb_ld(unsigned* p)              { return __hip_atomic_load(p, __ATOMIC_RELAXED, __HIP_MEMORY_SCOPE_AGENT); }
; __device__ __forceinline__ unsigned xb_add(unsigned* p, unsigned v) { return __hip_atomic_fetch_add(p, v, __ATOMIC_RELAXED, __HIP_MEMORY_SCOPE_AGENT); }
; #define XB_SPIN(cond, bar) do { unsigned _sp = 0; while (cond) { __builtin_amdgcn_s_sleep(1); \
;     if ((++_sp & 255u) == 0u) { if (xb_ld(&(bar)[XB_TMO])) break; if (_sp > XB_SPIN_CAP) { atomicAdd(&(bar)[XB_TMO], 1u); break; } } } } while (0)
; __device__ __forceinline__ void xcd_barrier(const XcdBarrier& b, const bool leader) {
;     ...
;         const unsigned old = xb_add(&bar[XB_XSUB(b.x)], 1u);
;         const unsigned gen = old / nloc;
;         if (old + 1u == (gen + 1u) * nloc) {
;             __builtin_amdgcn_fence(__ATOMIC_RELEASE, "agent");
;             asm volatile("s_waitcnt vmcnt(0)" ::: "memory");
;             const unsigned og = xb_add(&bar[XB_TOP], 1u);
;             const unsigned tg = og / nx;
;             if (og + 1u == (tg + 1u) * nx) xb_add(&bar[XB_TOPGEN], 1u);
;             else XB_SPIN(xb_ld(&bar[XB_TOPGEN]) == tg, bar);
;             __builtin_amdgcn_fence(__ATOMIC_ACQUIRE, "agent");
;             xb_add(&bar[XB_XGEN(b.x)], 1u);
;             asm volatile("s_waitcnt vmcnt(0)" ::: "memory");
;         } else {
;             XB_SPIN(xb_ld(&bar[XB_XGEN(b.x)]) == gen, bar);
.LBB0_821:
	s_or_b64 exec, exec, s[6:7]
	v_cvt_f32_u32_e32 v7, v5
	s_waitcnt vmcnt(0)
	v_readfirstlane_b32 s2, v6
	v_sub_u32_e32 v6, 0, v5
	v_rcp_iflag_f32_e32 v7, v7
	v_add_u32_e32 v8, s2, v2
	v_mul_f32_e32 v7, 0x4f7ffffe, v7
	v_cvt_u32_f32_e32 v7, v7
	v_mul_lo_u32 v2, v6, v7
	v_mul_hi_u32 v2, v7, v2
	v_add_u32_e32 v2, v7, v2
	v_mul_hi_u32 v2, v8, v2
	v_mul_lo_u32 v6, v2, v5
	v_sub_u32_e32 v6, v8, v6
	v_add_u32_e32 v7, 1, v2
	v_cmp_ge_u32_e32 vcc, v6, v5
	s_nop 1
	v_cndmask_b32_e32 v2, v2, v7, vcc
	v_sub_u32_e32 v7, v6, v5
	v_cndmask_b32_e32 v6, v6, v7, vcc
	v_add_u32_e32 v7, 1, v2
	v_cmp_ge_u32_e32 vcc, v6, v5
	v_add_u32_e32 v6, 1, v8
	s_nop 0
	v_cndmask_b32_e32 v2, v2, v7, vcc
	v_mul_lo_u32 v7, v5, v2
	v_add_u32_e32 v5, v7, v5
	v_cmp_ne_u32_e32 vcc, v6, v5
	s_and_saveexec_b64 s[2:3], vcc
	s_xor_b64 s[16:17], exec, s[2:3]
	s_cbranch_execz .LBB0_835
	buffer_inv sc1
	s_waitcnt lgkmcnt(0)
	s_load_dwordx2 s[22:23], s[90:91], 0xb0
	s_waitcnt lgkmcnt(0)
	s_add_u32 s22, s22, 0x1d79b500
	s_addc_u32 s23, s23, 0
	v_mov_b32_e32 v4, 0
	global_load_dword v4, v4, s[22:23] sc1
	s_waitcnt vmcnt(0)
	v_cmp_eq_u32_e32 vcc, v4, v2
	s_and_saveexec_b64 s[18:19], vcc
	s_cbranch_execz .LBB0_834
	s_add_u32 s20, s12, 0x1d798200
	s_addc_u32 s21, s13, 0
	s_mov_b32 s2, 1
	s_mov_b64 s[24:25], 0
	s_branch .LBB0_825

; __device__ __forceinline__ unsigned xb_add(unsigned* p, unsigned v) { return __hip_atomic_fetch_add(p, v, __ATOMIC_RELAXED, __HIP_MEMORY_SCOPE_AGENT); }
; __device__ __forceinline__ void xcd_barrier(const XcdBarrier& b, const bool leader) {
;     ...
;         if (old + 1u == (gen + 1u) * nloc) {
;             __builtin_amdgcn_fence(__ATOMIC_RELEASE, "agent");
;             asm volatile("s_waitcnt vmcnt(0)" ::: "memory");
;             const unsigned og = xb_add(&bar[XB_TOP], 1u);
;             const unsigned tg = og / nx;
;             if (og + 1u == (tg + 1u) * nx) xb_add(&bar[XB_TOPGEN], 1u);
.LBB0_835:
	s_andn2_saveexec_b64 s[2:3], s[16:17]
	s_cbranch_execz .LBB0_855
	s_mov_b64 s[16:17], exec
	buffer_wbl2 sc1
	buffer_inv sc1
	s_waitcnt lgkmcnt(0)
	s_waitcnt vmcnt(0)
	v_mbcnt_lo_u32_b32 v2, s16, 0
	v_mbcnt_hi_u32_b32 v2, s17, v2
	v_cmp_eq_u32_e32 vcc, 0, v2
	s_and_saveexec_b64 s[18:19], vcc
	s_cbranch_execz .LBB0_838
	s_bcnt1_i32_b64 s2, s[16:17]
	v_mov_b32_e32 v5, s2
	global_atomic_add v5, v203, v5, s[12:13] offset:1024 sc0

; __device__ __forceinline__ unsigned xb_ld(unsigned* p)              { return __hip_atomic_load(p, __ATOMIC_RELAXED, __HIP_MEMORY_SCOPE_AGENT); }
; __device__ __forceinline__ unsigned xb_add(unsigned* p, unsigned v) { return __hip_atomic_fetch_add(p, v, __ATOMIC_RELAXED, __HIP_MEMORY_SCOPE_AGENT); }
; #define XB_SPIN(cond, bar) do { unsigned _sp = 0; while (cond) { __builtin_amdgcn_s_sleep(1); \
;     if ((++_sp & 255u) == 0u) { if (xb_ld(&(bar)[XB_TMO])) break; if (_sp > XB_SPIN_CAP) { atomicAdd(&(bar)[XB_TMO], 1u); break; } } } } while (0)
; __device__ __forceinline__ void xcd_barrier(const XcdBarrier& b, const bool leader) {
;     ...
;             if (og + 1u == (tg + 1u) * nx) xb_add(&bar[XB_TOPGEN], 1u);
;             else XB_SPIN(xb_ld(&bar[XB_TOPGEN]) == tg, bar);
;             __builtin_amdgcn_fence(__ATOMIC_ACQUIRE, "agent");
;             xb_add(&bar[XB_XGEN(b.x)], 1u);
;             asm volatile("s_waitcnt vmcnt(0)" ::: "memory");
;         } else {
;             XB_SPIN(xb_ld(&bar[XB_XGEN(b.x)]) == gen, bar);
;             __builtin_amdgcn_fence(__ATOMIC_ACQUIRE, "agent");
;             asm volatile("s_waitcnt vmcnt(0)" ::: "memory");
.LBB0_852:
	s_or_b64 exec, exec, s[6:7]
	s_mov_b64 s[12:13], exec
	v_mbcnt_lo_u32_b32 v2, s12, 0
	v_mbcnt_hi_u32_b32 v2, s13, v2
	v_cmp_eq_u32_e32 vcc, 0, v2
	s_waitcnt vmcnt(0)
	s_and_saveexec_b64 s[6:7], vcc
	s_cbranch_execz .LBB0_854
	s_bcnt1_i32_b64 s2, s[12:13]
	v_mov_b32_e32 v2, s2
	global_atomic_add v202, v2, s[14:15] offset:1024
.LBB0_854:
	s_or_b64 exec, exec, s[6:7]
	s_waitcnt vmcnt(0)

; #define PG8_STAGE(bufoff, gbase, voff) do { _Pragma("unroll") for (int _i = 0; _i < 2; ++_i) \
;         __builtin_amdgcn_global_load_lds((const unsigned*)((const char*)(gbase) + (voff)[_i]), (PG8_LAS unsigned*)(lds + (bufoff) + ldsw + _i * 8192), 16, 0, 0); } while (0)
; #define PG8_LDA(dst, b, h) do { _Pragma("unroll") for (int m = 0; m < 4; ++m) _Pragma("unroll") for (int k = 0; k < 2; ++k) dst[m][k] = *(const PG8_LAS bf16x8*)(lds + PG8_SA(b, h) + aoff + m * 2048 + k * 1024); } while (0)
; #define PG8_LDB(dst, b, h) do { _Pragma("unroll") for (int n = 0; n < 2; ++n) _Pragma("unroll") for (int k = 0; k < 2; ++k) dst[n][k] = *(const PG8_LAS bf16x8*)(lds + PG8_SB(b, h) + boff + n * 2048 + k * 1024); } while (0)
; #define PG8_WAIT_V(n) asm volatile("s_waitcnt vmcnt(" #n ")" ::: "memory")
; #define PG8_WAIT_L(n) asm volatile("s_waitcnt lgkmcnt(" #n ")" ::: "memory")
; #define PG8_BAR __builtin_amdgcn_s_barrier()
; template <class Epi, class Sched, bool ALIGN_EPI = false, bool SP2 = false>
; __device__ __forceinline__ void gemm_phase(PG8_LAS unsigned char* lds, const Gemm g, const Sched& S, const Epi& E, const int tid_arg) {
;     ...
;         const bool has_next = S.next(ui + 1, nxt);
;         const char* nA = has_next ? (const char*)g.A + (size_t)nxt.pm * tstep : cA; const char* nB = has_next ? (const char*)g.Bt + (size_t)nxt.pn * tstep : cB;
;         for (int t = 0; t < nt; t += 2) {
;             const bool last = (t == nt - 2);
;             const char* a1 = cA + (size_t)(t + 1) * kstep;
;             const char* a2 = last ? nA : cA + (size_t)(t + 2) * kstep; const char* b2 = last ? nB : cB + (size_t)(t + 2) * kstep;
;             const char* a3 = a2 + kstep; const char* b3 = b2 + kstep;
;             if (last && has_next) S.a_ready(nxt);
;             if constexpr (SP2) {
;             PG8_LDB(B0, 0, 0); PG8_LDB(B1, 0, 1); PG8_SCHED; PG8_LDA(At, 0, 0); PG8_STAGE(PG8_SA(1, 1), a1 + hstep, voffA);
;             PG8_WAIT_V(8); PG8_WAIT_L(0); PG8_BAR; PG8_MMA(0, 0, At, B0); PG8_MMA(0, 1, At, B1); PG8_BAR; PG8_SCHED;
;     ...
; #pragma unroll
;         for (int a = 0; a < 2; ++a)
; #pragma unroll
;             for (int b = 0; b < 2; ++b)
; #pragma unroll
;                 for (int m = 0; m < 4; ++m)
; #pragma unroll
;                     for (int n = 0; n < 2; ++n) acc[a][b][m][n] = (f32x4){0.f, 0.f, 0.f, 0.f};
;         cur = nxt; cA = nA; cB = nB; ++ui;
.LBB0_867:
	s_ashr_i32 s35, s34, 31
	s_lshl_b64 s[36:37], s[34:35], 19
	s_add_u32 s36, s2, s36
	s_addc_u32 s37, s47, s37
	s_and_b64 s[38:39], s[14:15], exec
	s_cselect_b32 s7, s37, s17
	s_cselect_b32 s35, s36, s16
	s_ashr_i32 s31, s30, 31
	s_lshl_b64 s[38:39], s[30:31], 19
	s_add_u32 s38, s48, s38
	s_addc_u32 s39, s49, s39
	s_and_b64 s[44:45], s[14:15], exec
	s_cselect_b32 s31, s39, s43
	s_cselect_b32 s41, s38, s42
	s_add_u32 s16, s16, 0x40080
	s_addc_u32 s17, s17, 0
	s_add_u32 s59, s42, 0x100
	v_mov_b32_e32 v4, 0
	s_addc_u32 s60, s43, 0
	s_mov_b32 s61, -2
	s_waitcnt lgkmcnt(0)
	v_mov_b32_e32 v5, v4
	v_mov_b32_e32 v6, v4
	v_mov_b32_e32 v7, v4
	v_mov_b32_e32 v8, v4
	v_mov_b32_e32 v9, v4
	v_mov_b32_e32 v10, v4
	v_mov_b32_e32 v11, v4
	v_mov_b32_e32 v20, v4
	v_mov_b32_e32 v21, v4
	v_mov_b32_e32 v22, v4
	v_mov_b32_e32 v23, v4
	v_mov_b32_e32 v24, v4
	v_mov_b32_e32 v25, v4
	v_mov_b32_e32 v26, v4
	v_mov_b32_e32 v27, v4
	v_mov_b32_e32 v36, v4
	v_mov_b32_e32 v37, v4
	v_mov_b32_e32 v38, v4
	v_mov_b32_e32 v39, v4
	v_mov_b32_e32 v40, v4
	v_mov_b32_e32 v41, v4
	v_mov_b32_e32 v42, v4
	v_mov_b32_e32 v43, v4
	v_mov_b32_e32 v52, v4
	v_mov_b32_e32 v53, v4
	v_mov_b32_e32 v54, v4
	v_mov_b32_e32 v55, v4
	v_mov_b32_e32 v56, v4
	v_mov_b32_e32 v57, v4
	v_mov_b32_e32 v58, v4
	v_mov_b32_e32 v59, v4
	v_mov_b32_e32 v12, v4
	v_mov_b32_e32 v13, v4
	v_mov_b32_e32 v14, v4
	v_mov_b32_e32 v15, v4
	v_mov_b32_e32 v16, v4
	v_mov_b32_e32 v17, v4
	v_mov_b32_e32 v18, v4
	v_mov_b32_e32 v19, v4
	v_mov_b32_e32 v28, v4
	v_mov_b32_e32 v29, v4
	v_mov_b32_e32 v30, v4
	v_mov_b32_e32 v31, v4
	v_mov_b32_e32 v32, v4
	v_mov_b32_e32 v33, v4
	v_mov_b32_e32 v34, v4
	v_mov_b32_e32 v35, v4
	v_mov_b32_e32 v44, v4
	v_mov_b32_e32 v45, v4
	v_mov_b32_e32 v46, v4
	v_mov_b32_e32 v47, v4
	v_mov_b32_e32 v48, v4
	v_mov_b32_e32 v49, v4
	v_mov_b32_e32 v50, v4
	v_mov_b32_e32 v51, v4
	v_mov_b32_e32 v60, v4
	v_mov_b32_e32 v61, v4
	v_mov_b32_e32 v62, v4
	v_mov_b32_e32 v63, v4
	v_mov_b32_e32 v64, v4
	v_mov_b32_e32 v65, v4
	v_mov_b32_e32 v66, v4
	v_mov_b32_e32 v67, v4
	v_mov_b32_e32 v68, v4
	v_mov_b32_e32 v69, v4
	v_mov_b32_e32 v70, v4
	v_mov_b32_e32 v71, v4
	v_mov_b32_e32 v72, v4
	v_mov_b32_e32 v73, v4
	v_mov_b32_e32 v74, v4
	v_mov_b32_e32 v75, v4
	v_mov_b32_e32 v84, v4
	v_mov_b32_e32 v85, v4
	v_mov_b32_e32 v86, v4
	v_mov_b32_e32 v87, v4
	v_mov_b32_e32 v88, v4
	v_mov_b32_e32 v89, v4
	v_mov_b32_e32 v90, v4
	v_mov_b32_e32 v91, v4
	v_mov_b32_e32 v100, v4
	v_mov_b32_e32 v101, v4
	v_mov_b32_e32 v102, v4
	v_mov_b32_e32 v103, v4
	v_mov_b32_e32 v104, v4
	v_mov_b32_e32 v105, v4
	v_mov_b32_e32 v106, v4
	v_mov_b32_e32 v107, v4
	v_mov_b32_e32 v116, v4
	v_mov_b32_e32 v117, v4
	v_mov_b32_e32 v118, v4
	v_mov_b32_e32 v119, v4
	s_waitcnt vmcnt(0)
	v_mov_b32_e32 v120, v4
	v_mov_b32_e32 v121, v4
	v_mov_b32_e32 v122, v4
	v_mov_b32_e32 v123, v4
	v_mov_b32_e32 v76, v4
	v_mov_b32_e32 v77, v4
	v_mov_b32_e32 v78, v4
	v_mov_b32_e32 v79, v4
	v_mov_b32_e32 v80, v4
	v_mov_b32_e32 v81, v4
	v_mov_b32_e32 v82, v4
	v_mov_b32_e32 v83, v4
	v_mov_b32_e32 v92, v4
	v_mov_b32_e32 v93, v4
	v_mov_b32_e32 v94, v4
	v_mov_b32_e32 v95, v4
	v_mov_b32_e32 v96, v4
	v_mov_b32_e32 v97, v4
	v_mov_b32_e32 v98, v4
	v_mov_b32_e32 v99, v4
	v_mov_b32_e32 v108, v4
	v_mov_b32_e32 v109, v4
	v_mov_b32_e32 v110, v4
	v_mov_b32_e32 v111, v4
	v_mov_b32_e32 v112, v4
	v_mov_b32_e32 v113, v4
	v_mov_b32_e32 v114, v4
	v_mov_b32_e32 v115, v4
	v_mov_b32_e32 v124, v4
	v_mov_b32_e32 v125, v4
	v_mov_b32_e32 v126, v4
	v_mov_b32_e32 v127, v4
	v_mov_b32_e32 v128, v4
	v_mov_b32_e32 v129, v4
	v_mov_b32_e32 v130, v4
	v_mov_b32_e32 v131, v4
	s_nop 0
.LBB0_868:
	s_add_u32 s42, s16, 0xfffc0080
	s_addc_u32 s43, s17, -1
	s_add_i32 s62, 0, 0x10000
	s_cmp_eq_u32 s61, 12
	s_cselect_b32 s45, s7, s43
	s_cselect_b32 s44, s35, s42
	s_cselect_b32 s43, s31, s60
	s_cselect_b32 s42, s41, s59
	s_add_i32 s64, 0, 0x14000
	v_add_u32_e32 v160, s62, v169
	v_add_u32_e32 v179, s64, v169
	ds_read_b128 v[132:135], v160
	ds_read_b128 v[136:139], v160 offset:1024
	ds_read_b128 v[156:159], v160 offset:2048
	ds_read_b128 v[160:163], v160 offset:3072
	ds_read_b128 v[164:167], v179
	ds_read_b128 v[182:185], v179 offset:1024
	ds_read_b128 v[186:189], v179 offset:2048
	ds_read_b128 v[190:193], v179 offset:3072
	v_lshl_add_u64 v[194:195], s[16:17], 0, v[152:153]
	s_add_i32 m0, s51, 0xc000
	ds_read_b128 v[210:213], v178
	ds_read_b128 v[214:217], v178 offset:1024
	ds_read_b128 v[218:221], v178 offset:2048
	ds_read_b128 v[222:225], v178 offset:3072
	ds_read_b128 v[226:229], v178 offset:4096
	ds_read_b128 v[230:233], v178 offset:5120
	ds_read_b128 v[234:237], v178 offset:6144
	ds_read_b128 v[238:241], v178 offset:7168
	global_load_lds_dwordx4 v[194:195], off
	v_lshl_add_u64 v[194:195], s[16:17], 0, v[154:155]
	s_add_i32 m0, s51, 0xe000
	s_nop 0
	global_load_lds_dwordx4 v[194:195], off
	s_waitcnt vmcnt(8)
	s_waitcnt lgkmcnt(0)
	s_barrier
; #define PG8_STAGE(bufoff, gbase, voff) do { _Pragma("unroll") for (int _i = 0; _i < 2; ++_i) \
;         __builtin_amdgcn_global_load_lds((const unsigned*)((const char*)(gbase) + (voff)[_i]), (PG8_LAS unsigned*)(lds + (bufoff) + ldsw + _i * 8192), 16, 0, 0); } while (0)
; #define PG8_LDA(dst, b, h) do { _Pragma("unroll") for (int m = 0; m < 4; ++m) _Pragma("unroll") for (int k = 0; k < 2; ++k) dst[m][k] = *(const PG8_LAS bf16x8*)(lds + PG8_SA(b, h) + aoff + m * 2048 + k * 1024); } while (0)
; #define PG8_LDB(dst, b, h) do { _Pragma("unroll") for (int n = 0; n < 2; ++n) _Pragma("unroll") for (int k = 0; k < 2; ++k) dst[n][k] = *(const PG8_LAS bf16x8*)(lds + PG8_SB(b, h) + boff + n * 2048 + k * 1024); } while (0)
; #define PG8_MMA(ai, bj, At, Bt) do { __builtin_amdgcn_s_setprio(1); _Pragma("unroll") for (int m = 0; m < 4; ++m) _Pragma("unroll") for (int n = 0; n < 2; ++n) _Pragma("unroll") for (int k = 0; k < 2; ++k) \
;         acc[ai][bj][m][n] = __builtin_amdgcn_mfma_f32_16x16x32_bf16(Bt[n][k], At[m][k], acc[ai][bj][m][n], 0, 0, 0); __builtin_amdgcn_s_setprio(0); } while (0)
; #define PG8_WAIT_V(n) asm volatile("s_waitcnt vmcnt(" #n ")" ::: "memory")
; #define PG8_WAIT_L(n) asm volatile("s_waitcnt lgkmcnt(" #n ")" ::: "memory")
; #define PG8_BAR __builtin_amdgcn_s_barrier()
; #define PG8_SCHED __builtin_amdgcn_sched_barrier(0)
; template <class Epi, class Sched, bool ALIGN_EPI = false, bool SP2 = false>
; __device__ __forceinline__ void gemm_phase(PG8_LAS unsigned char* lds, const Gemm g, const Sched& S, const Epi& E, const int tid_arg) {
;     ...
;             PG8_WAIT_V(8); PG8_WAIT_L(0); PG8_BAR; PG8_MMA(0, 0, At, B0); PG8_MMA(0, 1, At, B1); PG8_BAR; PG8_SCHED;
;             PG8_LDA(At, 0, 1); PG8_STAGE(PG8_SB(0, 0), b2, voffB); PG8_STAGE(PG8_SB(0, 1), b2 + hstep, voffB); PG8_STAGE(PG8_SA(0, 0), a2, voffA);
;             PG8_WAIT_V(8); PG8_WAIT_L(0); PG8_BAR; PG8_MMA(1, 0, At, B0); PG8_MMA(1, 1, At, B1); PG8_BAR; PG8_SCHED;
;             PG8_LDB(B0, 1, 0); PG8_LDB(B1, 1, 1); PG8_SCHED; PG8_LDA(At, 1, 0); PG8_STAGE(PG8_SA(0, 1), a2 + hstep, voffA);
;             PG8_WAIT_V(8); PG8_WAIT_L(0); PG8_BAR; PG8_MMA(0, 0, At, B0); PG8_MMA(0, 1, At, B1); PG8_BAR; PG8_SCHED;
	s_setprio 1
	s_waitcnt lgkmcnt(0)
	v_mfma_f32_16x16x32_bf16 v[128:131], v[132:135], v[210:213], v[128:131]
	v_mfma_f32_16x16x32_bf16 v[124:127], v[156:159], v[210:213], v[124:127]
	v_mfma_f32_16x16x32_bf16 v[112:115], v[132:135], v[218:221], v[112:115]
	v_mfma_f32_16x16x32_bf16 v[108:111], v[156:159], v[218:221], v[108:111]
	v_mfma_f32_16x16x32_bf16 v[96:99], v[132:135], v[226:229], v[96:99]
	v_mfma_f32_16x16x32_bf16 v[92:95], v[156:159], v[226:229], v[92:95]
	v_mfma_f32_16x16x32_bf16 v[80:83], v[132:135], v[234:237], v[80:83]
	v_mfma_f32_16x16x32_bf16 v[76:79], v[156:159], v[234:237], v[76:79]
	v_mfma_f32_16x16x32_bf16 v[128:131], v[136:139], v[214:217], v[128:131]
	v_mfma_f32_16x16x32_bf16 v[124:127], v[160:163], v[214:217], v[124:127]
	v_mfma_f32_16x16x32_bf16 v[112:115], v[136:139], v[222:225], v[112:115]
	v_mfma_f32_16x16x32_bf16 v[108:111], v[160:163], v[222:225], v[108:111]
	v_mfma_f32_16x16x32_bf16 v[96:99], v[136:139], v[230:233], v[96:99]
	v_mfma_f32_16x16x32_bf16 v[92:95], v[160:163], v[230:233], v[92:95]
	v_mfma_f32_16x16x32_bf16 v[80:83], v[136:139], v[238:241], v[80:83]
	v_mfma_f32_16x16x32_bf16 v[76:79], v[160:163], v[238:241], v[76:79]
	s_setprio 0
	s_setprio 1
	v_mfma_f32_16x16x32_bf16 v[120:123], v[164:167], v[210:213], v[120:123]
	v_mfma_f32_16x16x32_bf16 v[116:119], v[186:189], v[210:213], v[116:119]
	v_mfma_f32_16x16x32_bf16 v[104:107], v[164:167], v[218:221], v[104:107]
	v_mfma_f32_16x16x32_bf16 v[100:103], v[186:189], v[218:221], v[100:103]
	v_mfma_f32_16x16x32_bf16 v[88:91], v[164:167], v[226:229], v[88:91]
	v_mfma_f32_16x16x32_bf16 v[84:87], v[186:189], v[226:229], v[84:87]
	v_mfma_f32_16x16x32_bf16 v[72:75], v[164:167], v[234:237], v[72:75]
	v_mfma_f32_16x16x32_bf16 v[68:71], v[186:189], v[234:237], v[68:71]
	v_mfma_f32_16x16x32_bf16 v[120:123], v[182:185], v[214:217], v[120:123]
	v_mfma_f32_16x16x32_bf16 v[116:119], v[190:193], v[214:217], v[116:119]
	v_mfma_f32_16x16x32_bf16 v[104:107], v[182:185], v[222:225], v[104:107]
	v_mfma_f32_16x16x32_bf16 v[100:103], v[190:193], v[222:225], v[100:103]
	v_mfma_f32_16x16x32_bf16 v[88:91], v[182:185], v[230:233], v[88:91]
	v_mfma_f32_16x16x32_bf16 v[84:87], v[190:193], v[230:233], v[84:87]
	v_mfma_f32_16x16x32_bf16 v[72:75], v[182:185], v[238:241], v[72:75]
	v_mfma_f32_16x16x32_bf16 v[68:71], v[190:193], v[238:241], v[68:71]
	s_setprio 0
	s_barrier
	s_add_i32 s62, s62, s50
	v_lshl_add_u64 v[194:195], s[42:43], 0, v[2:3]
	s_mov_b32 m0, s62
	ds_read_b128 v[210:213], v178 offset:16384
	ds_read_b128 v[214:217], v178 offset:17408
	ds_read_b128 v[218:221], v178 offset:18432
	ds_read_b128 v[222:225], v178 offset:19456
	ds_read_b128 v[226:229], v178 offset:20480
	ds_read_b128 v[230:233], v178 offset:21504
	ds_read_b128 v[234:237], v178 offset:22528
	ds_read_b128 v[238:241], v178 offset:23552
	global_load_lds_dwordx4 v[194:195], off
	s_add_i32 m0, s62, 0x2000
	s_add_u32 s62, s42, 0x40000
	v_lshl_add_u64 v[242:243], s[42:43], 0, v[146:147]
	s_addc_u32 s63, s43, 0
	s_add_i32 s64, s64, s50
	global_load_lds_dwordx4 v[242:243], off
	v_lshl_add_u64 v[244:245], s[62:63], 0, v[2:3]
	s_mov_b32 m0, s64
	v_lshl_add_u64 v[246:247], s[44:45], 0, v[148:149]
	global_load_lds_dwordx4 v[244:245], off
	v_lshl_add_u64 v[244:245], s[62:63], 0, v[146:147]
	s_add_i32 m0, s64, 0x2000
	s_nop 0
	global_load_lds_dwordx4 v[244:245], off
	v_lshl_add_u64 v[244:245], s[44:45], 0, v[150:151]
	s_mov_b32 m0, s51
	s_nop 0
	global_load_lds_dwordx4 v[244:245], off
	s_mov_b32 m0, s52
	s_nop 0
	global_load_lds_dwordx4 v[246:247], off
	s_waitcnt vmcnt(8)
	s_waitcnt lgkmcnt(0)
	s_barrier
	s_setprio 1
	s_waitcnt lgkmcnt(0)
	v_mfma_f32_16x16x32_bf16 v[64:67], v[132:135], v[210:213], v[64:67]
	v_mfma_f32_16x16x32_bf16 v[60:63], v[156:159], v[210:213], v[60:63]
	v_mfma_f32_16x16x32_bf16 v[48:51], v[132:135], v[218:221], v[48:51]
	v_mfma_f32_16x16x32_bf16 v[44:47], v[156:159], v[218:221], v[44:47]
	v_mfma_f32_16x16x32_bf16 v[32:35], v[132:135], v[226:229], v[32:35]
	v_mfma_f32_16x16x32_bf16 v[28:31], v[156:159], v[226:229], v[28:31]
	v_mfma_f32_16x16x32_bf16 v[16:19], v[132:135], v[234:237], v[16:19]
	v_mfma_f32_16x16x32_bf16 v[12:15], v[156:159], v[234:237], v[12:15]
	v_mfma_f32_16x16x32_bf16 v[64:67], v[136:139], v[214:217], v[64:67]
	v_mfma_f32_16x16x32_bf16 v[60:63], v[160:163], v[214:217], v[60:63]
	v_mfma_f32_16x16x32_bf16 v[48:51], v[136:139], v[222:225], v[48:51]
	v_mfma_f32_16x16x32_bf16 v[44:47], v[160:163], v[222:225], v[44:47]
	v_mfma_f32_16x16x32_bf16 v[32:35], v[136:139], v[230:233], v[32:35]
	v_mfma_f32_16x16x32_bf16 v[28:31], v[160:163], v[230:233], v[28:31]
	v_mfma_f32_16x16x32_bf16 v[16:19], v[136:139], v[238:241], v[16:19]
	v_mfma_f32_16x16x32_bf16 v[12:15], v[160:163], v[238:241], v[12:15]
	s_setprio 0
	s_setprio 1
	v_mfma_f32_16x16x32_bf16 v[56:59], v[164:167], v[210:213], v[56:59]
	v_mfma_f32_16x16x32_bf16 v[52:55], v[186:189], v[210:213], v[52:55]
	v_mfma_f32_16x16x32_bf16 v[40:43], v[164:167], v[218:221], v[40:43]
	v_mfma_f32_16x16x32_bf16 v[36:39], v[186:189], v[218:221], v[36:39]
	v_mfma_f32_16x16x32_bf16 v[24:27], v[164:167], v[226:229], v[24:27]
	v_mfma_f32_16x16x32_bf16 v[20:23], v[186:189], v[226:229], v[20:23]
	v_mfma_f32_16x16x32_bf16 v[8:11], v[164:167], v[234:237], v[8:11]
	v_mfma_f32_16x16x32_bf16 v[4:7], v[186:189], v[234:237], v[4:7]
	v_mfma_f32_16x16x32_bf16 v[56:59], v[182:185], v[214:217], v[56:59]
	v_mfma_f32_16x16x32_bf16 v[52:55], v[190:193], v[214:217], v[52:55]
	v_mfma_f32_16x16x32_bf16 v[40:43], v[182:185], v[222:225], v[40:43]
	v_mfma_f32_16x16x32_bf16 v[36:39], v[190:193], v[222:225], v[36:39]
	v_mfma_f32_16x16x32_bf16 v[24:27], v[182:185], v[230:233], v[24:27]
	v_mfma_f32_16x16x32_bf16 v[20:23], v[190:193], v[230:233], v[20:23]
	v_mfma_f32_16x16x32_bf16 v[8:11], v[182:185], v[238:241], v[8:11]
	v_mfma_f32_16x16x32_bf16 v[4:7], v[190:193], v[238:241], v[4:7]
	s_setprio 0
	s_barrier
; #define PG8_STAGE(bufoff, gbase, voff) do { _Pragma("unroll") for (int _i = 0; _i < 2; ++_i) \
;         __builtin_amdgcn_global_load_lds((const unsigned*)((const char*)(gbase) + (voff)[_i]), (PG8_LAS unsigned*)(lds + (bufoff) + ldsw + _i * 8192), 16, 0, 0); } while (0)
; #define PG8_LDA(dst, b, h) do { _Pragma("unroll") for (int m = 0; m < 4; ++m) _Pragma("unroll") for (int k = 0; k < 2; ++k) dst[m][k] = *(const PG8_LAS bf16x8*)(lds + PG8_SA(b, h) + aoff + m * 2048 + k * 1024); } while (0)
; #define PG8_LDB(dst, b, h) do { _Pragma("unroll") for (int n = 0; n < 2; ++n) _Pragma("unroll") for (int k = 0; k < 2; ++k) dst[n][k] = *(const PG8_LAS bf16x8*)(lds + PG8_SB(b, h) + boff + n * 2048 + k * 1024); } while (0)
; #define PG8_MMA(ai, bj, At, Bt) do { __builtin_amdgcn_s_setprio(1); _Pragma("unroll") for (int m = 0; m < 4; ++m) _Pragma("unroll") for (int n = 0; n < 2; ++n) _Pragma("unroll") for (int k = 0; k < 2; ++k) \
;         acc[ai][bj][m][n] = __builtin_amdgcn_mfma_f32_16x16x32_bf16(Bt[n][k], At[m][k], acc[ai][bj][m][n], 0, 0, 0); __builtin_amdgcn_s_setprio(0); } while (0)
; #define PG8_WAIT_V(n) asm volatile("s_waitcnt vmcnt(" #n ")" ::: "memory")
; #define PG8_WAIT_L(n) asm volatile("s_waitcnt lgkmcnt(" #n ")" ::: "memory")
; #define PG8_BAR __builtin_amdgcn_s_barrier()
; #define PG8_SCHED __builtin_amdgcn_sched_barrier(0)
; template <class Epi, class Sched, bool ALIGN_EPI = false, bool SP2 = false>
; __device__ __forceinline__ void gemm_phase(PG8_LAS unsigned char* lds, const Gemm g, const Sched& S, const Epi& E, const int tid_arg) {
;     ...
;             PG8_LDB(B0, 1, 0); PG8_LDB(B1, 1, 1); PG8_SCHED; PG8_LDA(At, 1, 0); PG8_STAGE(PG8_SA(0, 1), a2 + hstep, voffA);
;             PG8_WAIT_V(8); PG8_WAIT_L(0); PG8_BAR; PG8_MMA(0, 0, At, B0); PG8_MMA(0, 1, At, B1); PG8_BAR; PG8_SCHED;
	s_add_i32 s62, 0, 0x18000
	s_add_i32 s63, 0, 0x1c000
	v_add_u32_e32 v160, s62, v169
	v_add_u32_e32 v179, s63, v169
	ds_read_b128 v[132:135], v160
	ds_read_b128 v[136:139], v160 offset:1024
	ds_read_b128 v[156:159], v160 offset:2048
	ds_read_b128 v[160:163], v160 offset:3072
	ds_read_b128 v[164:167], v179
	ds_read_b128 v[182:185], v179 offset:1024
	ds_read_b128 v[186:189], v179 offset:2048
	ds_read_b128 v[190:193], v179 offset:3072
	s_add_u32 s44, s44, 0x40000
	s_addc_u32 s45, s45, 0
	s_mov_b32 m0, s53
	v_lshl_add_u64 v[248:249], s[44:45], 0, v[150:151]
	ds_read_b128 v[210:213], v178 offset:32768
	ds_read_b128 v[214:217], v178 offset:33792
	ds_read_b128 v[218:221], v178 offset:34816
	ds_read_b128 v[222:225], v178 offset:35840
	ds_read_b128 v[226:229], v178 offset:36864
	ds_read_b128 v[230:233], v178 offset:37888
	ds_read_b128 v[234:237], v178 offset:38912
	ds_read_b128 v[238:241], v178 offset:39936
	global_load_lds_dwordx4 v[248:249], off
	v_lshl_add_u64 v[248:249], s[44:45], 0, v[148:149]
	s_mov_b32 m0, s54
	s_nop 0
	global_load_lds_dwordx4 v[248:249], off
	s_waitcnt vmcnt(8)
	s_waitcnt lgkmcnt(0)
	s_barrier
	s_setprio 1
	s_waitcnt lgkmcnt(0)
	v_mfma_f32_16x16x32_bf16 v[128:131], v[132:135], v[210:213], v[128:131]
	v_mfma_f32_16x16x32_bf16 v[124:127], v[156:159], v[210:213], v[124:127]
	v_mfma_f32_16x16x32_bf16 v[112:115], v[132:135], v[218:221], v[112:115]
	v_mfma_f32_16x16x32_bf16 v[108:111], v[156:159], v[218:221], v[108:111]
	v_mfma_f32_16x16x32_bf16 v[96:99], v[132:135], v[226:229], v[96:99]
	v_mfma_f32_16x16x32_bf16 v[92:95], v[156:159], v[226:229], v[92:95]
	v_mfma_f32_16x16x32_bf16 v[80:83], v[132:135], v[234:237], v[80:83]
	v_mfma_f32_16x16x32_bf16 v[76:79], v[156:159], v[234:237], v[76:79]
	v_mfma_f32_16x16x32_bf16 v[128:131], v[136:139], v[214:217], v[128:131]
	v_mfma_f32_16x16x32_bf16 v[124:127], v[160:163], v[214:217], v[124:127]
	v_mfma_f32_16x16x32_bf16 v[112:115], v[136:139], v[222:225], v[112:115]
	v_mfma_f32_16x16x32_bf16 v[108:111], v[160:163], v[222:225], v[108:111]
	v_mfma_f32_16x16x32_bf16 v[96:99], v[136:139], v[230:233], v[96:99]
	v_mfma_f32_16x16x32_bf16 v[92:95], v[160:163], v[230:233], v[92:95]
	v_mfma_f32_16x16x32_bf16 v[80:83], v[136:139], v[238:241], v[80:83]
	v_mfma_f32_16x16x32_bf16 v[76:79], v[160:163], v[238:241], v[76:79]
	s_setprio 0
	s_setprio 1
	v_mfma_f32_16x16x32_bf16 v[120:123], v[164:167], v[210:213], v[120:123]
	v_mfma_f32_16x16x32_bf16 v[116:119], v[186:189], v[210:213], v[116:119]
	v_mfma_f32_16x16x32_bf16 v[104:107], v[164:167], v[218:221], v[104:107]
	v_mfma_f32_16x16x32_bf16 v[100:103], v[186:189], v[218:221], v[100:103]
	v_mfma_f32_16x16x32_bf16 v[88:91], v[164:167], v[226:229], v[88:91]
	v_mfma_f32_16x16x32_bf16 v[84:87], v[186:189], v[226:229], v[84:87]
	v_mfma_f32_16x16x32_bf16 v[72:75], v[164:167], v[234:237], v[72:75]
	v_mfma_f32_16x16x32_bf16 v[68:71], v[186:189], v[234:237], v[68:71]
	v_mfma_f32_16x16x32_bf16 v[120:123], v[182:185], v[214:217], v[120:123]
	v_mfma_f32_16x16x32_bf16 v[116:119], v[190:193], v[214:217], v[116:119]
	v_mfma_f32_16x16x32_bf16 v[104:107], v[182:185], v[222:225], v[104:107]
	v_mfma_f32_16x16x32_bf16 v[100:103], v[190:193], v[222:225], v[100:103]
	v_mfma_f32_16x16x32_bf16 v[88:91], v[182:185], v[230:233], v[88:91]
	v_mfma_f32_16x16x32_bf16 v[84:87], v[190:193], v[230:233], v[84:87]
	v_mfma_f32_16x16x32_bf16 v[72:75], v[182:185], v[238:241], v[72:75]
	v_mfma_f32_16x16x32_bf16 v[68:71], v[190:193], v[238:241], v[68:71]
	s_setprio 0
	s_barrier
; #define PG8_STAGE(bufoff, gbase, voff) do { _Pragma("unroll") for (int _i = 0; _i < 2; ++_i) \
;         __builtin_amdgcn_global_load_lds((const unsigned*)((const char*)(gbase) + (voff)[_i]), (PG8_LAS unsigned*)(lds + (bufoff) + ldsw + _i * 8192), 16, 0, 0); } while (0)
; #define PG8_LDA(dst, b, h) do { _Pragma("unroll") for (int m = 0; m < 4; ++m) _Pragma("unroll") for (int k = 0; k < 2; ++k) dst[m][k] = *(const PG8_LAS bf16x8*)(lds + PG8_SA(b, h) + aoff + m * 2048 + k * 1024); } while (0)
; #define PG8_MMA(ai, bj, At, Bt) do { __builtin_amdgcn_s_setprio(1); _Pragma("unroll") for (int m = 0; m < 4; ++m) _Pragma("unroll") for (int n = 0; n < 2; ++n) _Pragma("unroll") for (int k = 0; k < 2; ++k) \
;         acc[ai][bj][m][n] = __builtin_amdgcn_mfma_f32_16x16x32_bf16(Bt[n][k], At[m][k], acc[ai][bj][m][n], 0, 0, 0); __builtin_amdgcn_s_setprio(0); } while (0)
; #define PG8_WAIT_V(n) asm volatile("s_waitcnt vmcnt(" #n ")" ::: "memory")
; #define PG8_WAIT_L(n) asm volatile("s_waitcnt lgkmcnt(" #n ")" ::: "memory")
; #define PG8_BAR __builtin_amdgcn_s_barrier()
; #define PG8_SCHED __builtin_amdgcn_sched_barrier(0)
; template <class Epi, class Sched, bool ALIGN_EPI = false, bool SP2 = false>
; __device__ __forceinline__ void gemm_phase(PG8_LAS unsigned char* lds, const Gemm g, const Sched& S, const Epi& E, const int tid_arg) {
;     ...
;             PG8_LDA(At, 1, 1); PG8_STAGE(PG8_SB(1, 0), b3, voffB); PG8_STAGE(PG8_SB(1, 1), b3 + hstep, voffB); PG8_STAGE(PG8_SA(1, 0), a3, voffA);
;             PG8_WAIT_V(8); PG8_WAIT_L(0); PG8_BAR; PG8_MMA(1, 0, At, B0); PG8_MMA(1, 1, At, B1); PG8_BAR; PG8_SCHED;
;     ...
;         if constexpr (ALIGN_EPI) { if (wr == 0) PG8_BAR; }
	s_add_i32 s44, s62, s50
	v_lshl_add_u64 v[194:195], v[194:195], 0, s[76:77]
	s_mov_b32 m0, s44
	ds_read_b128 v[210:213], v178 offset:49152
	ds_read_b128 v[214:217], v178 offset:50176
	ds_read_b128 v[218:221], v178 offset:51200
	ds_read_b128 v[222:225], v178 offset:52224
	ds_read_b128 v[226:229], v178 offset:53248
	ds_read_b128 v[230:233], v178 offset:54272
	ds_read_b128 v[234:237], v178 offset:55296
	ds_read_b128 v[238:241], v178 offset:56320
	global_load_lds_dwordx4 v[194:195], off
	s_add_i32 m0, s44, 0x2000
	s_add_u32 s42, s42, 0x40080
	v_lshl_add_u64 v[194:195], v[242:243], 0, s[76:77]
	s_addc_u32 s43, s43, 0
	s_add_i32 s44, s63, s50
	global_load_lds_dwordx4 v[194:195], off
	v_lshl_add_u64 v[194:195], s[42:43], 0, v[2:3]
	s_mov_b32 m0, s44
	s_nop 0
	global_load_lds_dwordx4 v[194:195], off
	v_lshl_add_u64 v[194:195], s[42:43], 0, v[146:147]
	s_add_i32 m0, s44, 0x2000
	s_nop 0
	global_load_lds_dwordx4 v[194:195], off
	v_lshl_add_u64 v[194:195], v[244:245], 0, s[76:77]
	s_mov_b32 m0, s56
	s_nop 0
	global_load_lds_dwordx4 v[194:195], off
	v_lshl_add_u64 v[194:195], v[246:247], 0, s[76:77]
	s_mov_b32 m0, s57
	s_nop 0
	global_load_lds_dwordx4 v[194:195], off
	s_waitcnt vmcnt(8)
	s_waitcnt lgkmcnt(0)
	s_barrier
	s_setprio 1
	s_waitcnt lgkmcnt(0)
	v_mfma_f32_16x16x32_bf16 v[64:67], v[132:135], v[210:213], v[64:67]
	v_mfma_f32_16x16x32_bf16 v[60:63], v[156:159], v[210:213], v[60:63]
	v_mfma_f32_16x16x32_bf16 v[48:51], v[132:135], v[218:221], v[48:51]
	v_mfma_f32_16x16x32_bf16 v[44:47], v[156:159], v[218:221], v[44:47]
	v_mfma_f32_16x16x32_bf16 v[32:35], v[132:135], v[226:229], v[32:35]
	v_mfma_f32_16x16x32_bf16 v[28:31], v[156:159], v[226:229], v[28:31]
	v_mfma_f32_16x16x32_bf16 v[16:19], v[132:135], v[234:237], v[16:19]
	v_mfma_f32_16x16x32_bf16 v[12:15], v[156:159], v[234:237], v[12:15]
	v_mfma_f32_16x16x32_bf16 v[64:67], v[136:139], v[214:217], v[64:67]
	v_mfma_f32_16x16x32_bf16 v[60:63], v[160:163], v[214:217], v[60:63]
	v_mfma_f32_16x16x32_bf16 v[48:51], v[136:139], v[222:225], v[48:51]
	v_mfma_f32_16x16x32_bf16 v[44:47], v[160:163], v[222:225], v[44:47]
	v_mfma_f32_16x16x32_bf16 v[32:35], v[136:139], v[230:233], v[32:35]
	v_mfma_f32_16x16x32_bf16 v[28:31], v[160:163], v[230:233], v[28:31]
	v_mfma_f32_16x16x32_bf16 v[16:19], v[136:139], v[238:241], v[16:19]
	v_mfma_f32_16x16x32_bf16 v[12:15], v[160:163], v[238:241], v[12:15]
	s_setprio 0
	s_setprio 1
	v_mfma_f32_16x16x32_bf16 v[56:59], v[164:167], v[210:213], v[56:59]
	v_mfma_f32_16x16x32_bf16 v[52:55], v[186:189], v[210:213], v[52:55]
	v_mfma_f32_16x16x32_bf16 v[40:43], v[164:167], v[218:221], v[40:43]
	v_mfma_f32_16x16x32_bf16 v[36:39], v[186:189], v[218:221], v[36:39]
	v_mfma_f32_16x16x32_bf16 v[24:27], v[164:167], v[226:229], v[24:27]
	v_mfma_f32_16x16x32_bf16 v[20:23], v[186:189], v[226:229], v[20:23]
	v_mfma_f32_16x16x32_bf16 v[8:11], v[164:167], v[234:237], v[8:11]
	v_mfma_f32_16x16x32_bf16 v[4:7], v[186:189], v[234:237], v[4:7]
	v_mfma_f32_16x16x32_bf16 v[56:59], v[182:185], v[214:217], v[56:59]
	v_mfma_f32_16x16x32_bf16 v[52:55], v[190:193], v[214:217], v[52:55]
	v_mfma_f32_16x16x32_bf16 v[40:43], v[182:185], v[222:225], v[40:43]
	v_mfma_f32_16x16x32_bf16 v[36:39], v[190:193], v[222:225], v[36:39]
	v_mfma_f32_16x16x32_bf16 v[24:27], v[182:185], v[230:233], v[24:27]
	v_mfma_f32_16x16x32_bf16 v[20:23], v[190:193], v[230:233], v[20:23]
	v_mfma_f32_16x16x32_bf16 v[8:11], v[182:185], v[238:241], v[8:11]
	v_mfma_f32_16x16x32_bf16 v[4:7], v[190:193], v[238:241], v[4:7]
	s_setprio 0
	s_barrier
	s_add_i32 s61, s61, 2
	s_add_u32 s16, s16, 0x100
	s_addc_u32 s17, s17, 0
	s_add_u32 s59, s59, 0x100
	s_addc_u32 s60, s60, 0
	s_cmp_gt_u32 s61, 13
	s_cbranch_scc0 .LBB0_868
	s_and_b64 vcc, exec, s[28:29]
	s_cbranch_vccz .LBB0_871
	s_barrier

; __device__ __forceinline__ unsigned xb_ld(unsigned* p)              { return __hip_atomic_load(p, __ATOMIC_RELAXED, __HIP_MEMORY_SCOPE_AGENT); }
; __device__ __forceinline__ unsigned xb_add(unsigned* p, unsigned v) { return __hip_atomic_fetch_add(p, v, __ATOMIC_RELAXED, __HIP_MEMORY_SCOPE_AGENT); }
; #define XB_SPIN(cond, bar) do { unsigned _sp = 0; while (cond) { __builtin_amdgcn_s_sleep(1); \
;     if ((++_sp & 255u) == 0u) { if (xb_ld(&(bar)[XB_TMO])) break; if (_sp > XB_SPIN_CAP) { atomicAdd(&(bar)[XB_TMO], 1u); break; } } } } while (0)
; __device__ __forceinline__ void xcd_barrier(const XcdBarrier& b, const bool leader) {
;     ...
;         const unsigned old = xb_add(&bar[XB_XSUB(b.x)], 1u);
;         const unsigned gen = old / nloc;
;         if (old + 1u == (gen + 1u) * nloc) {
;             __builtin_amdgcn_fence(__ATOMIC_RELEASE, "agent");
;             asm volatile("s_waitcnt vmcnt(0)" ::: "memory");
;             const unsigned og = xb_add(&bar[XB_TOP], 1u);
;             const unsigned tg = og / nx;
;             if (og + 1u == (tg + 1u) * nx) xb_add(&bar[XB_TOPGEN], 1u);
;             else XB_SPIN(xb_ld(&bar[XB_TOPGEN]) == tg, bar);
;             __builtin_amdgcn_fence(__ATOMIC_ACQUIRE, "agent");
;             xb_add(&bar[XB_XGEN(b.x)], 1u);
;             asm volatile("s_waitcnt vmcnt(0)" ::: "memory");
;         } else {
;             XB_SPIN(xb_ld(&bar[XB_XGEN(b.x)]) == gen, bar);
.LBB0_1030:
	s_or_b64 exec, exec, s[6:7]
	v_cvt_f32_u32_e32 v7, v5
	s_waitcnt vmcnt(0)
	v_readfirstlane_b32 s2, v6
	v_sub_u32_e32 v6, 0, v5
	v_rcp_iflag_f32_e32 v7, v7
	v_add_u32_e32 v8, s2, v2
	v_mul_f32_e32 v7, 0x4f7ffffe, v7
	v_cvt_u32_f32_e32 v7, v7
	v_mul_lo_u32 v2, v6, v7
	v_mul_hi_u32 v2, v7, v2
	v_add_u32_e32 v2, v7, v2
	v_mul_hi_u32 v2, v8, v2
	v_mul_lo_u32 v6, v2, v5
	v_sub_u32_e32 v6, v8, v6
	v_add_u32_e32 v7, 1, v2
	v_cmp_ge_u32_e32 vcc, v6, v5
	s_nop 1
	v_cndmask_b32_e32 v2, v2, v7, vcc
	v_sub_u32_e32 v7, v6, v5
	v_cndmask_b32_e32 v6, v6, v7, vcc
	v_add_u32_e32 v7, 1, v2
	v_cmp_ge_u32_e32 vcc, v6, v5
	v_add_u32_e32 v6, 1, v8
	s_nop 0
	v_cndmask_b32_e32 v2, v2, v7, vcc
	v_mul_lo_u32 v7, v5, v2
	v_add_u32_e32 v5, v7, v5
	v_cmp_ne_u32_e32 vcc, v6, v5
	s_and_saveexec_b64 s[2:3], vcc
	s_xor_b64 s[12:13], exec, s[2:3]
	s_cbranch_execz .LBB0_1044
	buffer_inv sc1
	s_waitcnt lgkmcnt(0)
	s_load_dwordx2 s[20:21], s[90:91], 0xb0
	s_waitcnt lgkmcnt(0)
	s_add_u32 s20, s20, 0x1d79b500
	s_addc_u32 s21, s21, 0
	v_mov_b32_e32 v4, 0
	global_load_dword v4, v4, s[20:21] sc1
	s_waitcnt vmcnt(0)
	v_cmp_eq_u32_e32 vcc, v4, v2
	s_and_saveexec_b64 s[14:15], vcc
	s_cbranch_execz .LBB0_1043
	s_add_u32 s16, s18, 0x1d798200
	s_addc_u32 s17, s19, 0
	s_mov_b32 s2, 1
	s_mov_b64 s[22:23], 0
	s_branch .LBB0_1034

; __device__ __forceinline__ unsigned xb_add(unsigned* p, unsigned v) { return __hip_atomic_fetch_add(p, v, __ATOMIC_RELAXED, __HIP_MEMORY_SCOPE_AGENT); }
; __device__ __forceinline__ void xcd_barrier(const XcdBarrier& b, const bool leader) {
;     ...
;         if (old + 1u == (gen + 1u) * nloc) {
;             __builtin_amdgcn_fence(__ATOMIC_RELEASE, "agent");
;             asm volatile("s_waitcnt vmcnt(0)" ::: "memory");
;             const unsigned og = xb_add(&bar[XB_TOP], 1u);
;             const unsigned tg = og / nx;
;             if (og + 1u == (tg + 1u) * nx) xb_add(&bar[XB_TOPGEN], 1u);
.LBB0_1044:
	s_andn2_saveexec_b64 s[2:3], s[12:13]
	s_cbranch_execz .LBB0_346
	s_mov_b64 s[12:13], exec
	buffer_wbl2 sc1
	buffer_inv sc1
	s_waitcnt lgkmcnt(0)
	s_waitcnt vmcnt(0)
	v_mbcnt_lo_u32_b32 v2, s12, 0
	v_mbcnt_hi_u32_b32 v2, s13, v2
	v_cmp_eq_u32_e32 vcc, 0, v2
	s_and_saveexec_b64 s[14:15], vcc
	s_cbranch_execz .LBB0_1047
	s_bcnt1_i32_b64 s2, s[12:13]
	v_mov_b32_e32 v5, s2
	global_atomic_add v5, v203, v5, s[18:19] offset:1024 sc0

; __device__ __forceinline__ unsigned xb_ld(unsigned* p)              { return __hip_atomic_load(p, __ATOMIC_RELAXED, __HIP_MEMORY_SCOPE_AGENT); }
; __device__ __forceinline__ unsigned xb_add(unsigned* p, unsigned v) { return __hip_atomic_fetch_add(p, v, __ATOMIC_RELAXED, __HIP_MEMORY_SCOPE_AGENT); }
; #define XB_SPIN(cond, bar) do { unsigned _sp = 0; while (cond) { __builtin_amdgcn_s_sleep(1); \
;     if ((++_sp & 255u) == 0u) { if (xb_ld(&(bar)[XB_TMO])) break; if (_sp > XB_SPIN_CAP) { atomicAdd(&(bar)[XB_TMO], 1u); break; } } } } while (0)
; __device__ __forceinline__ void xcd_barrier(const XcdBarrier& b, const bool leader) {
;     ...
;             xb_add(&bar[XB_XGEN(b.x)], 1u);
;             asm volatile("s_waitcnt vmcnt(0)" ::: "memory");
;         } else {
;             XB_SPIN(xb_ld(&bar[XB_XGEN(b.x)]) == gen, bar);
;             __builtin_amdgcn_fence(__ATOMIC_ACQUIRE, "agent");
;             asm volatile("s_waitcnt vmcnt(0)" ::: "memory");
.LBB0_1061:
	s_or_b64 exec, exec, s[6:7]
	s_mov_b64 s[12:13], exec
	v_mbcnt_lo_u32_b32 v2, s12, 0
	v_mbcnt_hi_u32_b32 v2, s13, v2
	v_cmp_eq_u32_e32 vcc, 0, v2
	s_waitcnt vmcnt(0)
	s_and_saveexec_b64 s[6:7], vcc
	s_cbranch_execz .LBB0_345
	s_bcnt1_i32_b64 s2, s[12:13]
	v_mov_b32_e32 v2, s2
	global_atomic_add v202, v2, s[10:11] offset:1024
	s_branch .LBB0_345

; #define PG8_STAGE(bufoff, gbase, voff) do { _Pragma("unroll") for (int _i = 0; _i < 2; ++_i) \
;         __builtin_amdgcn_global_load_lds((const unsigned*)((const char*)(gbase) + (voff)[_i]), (PG8_LAS unsigned*)(lds + (bufoff) + ldsw + _i * 8192), 16, 0, 0); } while (0)
; #define PG8_LDA(dst, b, h) do { _Pragma("unroll") for (int m = 0; m < 4; ++m) _Pragma("unroll") for (int k = 0; k < 2; ++k) dst[m][k] = *(const PG8_LAS bf16x8*)(lds + PG8_SA(b, h) + aoff + m * 2048 + k * 1024); } while (0)
; #define PG8_LDB(dst, b, h) do { _Pragma("unroll") for (int n = 0; n < 2; ++n) _Pragma("unroll") for (int k = 0; k < 2; ++k) dst[n][k] = *(const PG8_LAS bf16x8*)(lds + PG8_SB(b, h) + boff + n * 2048 + k * 1024); } while (0)
; #define PG8_WAIT_V(n) asm volatile("s_waitcnt vmcnt(" #n ")" ::: "memory")
; #define PG8_WAIT_L(n) asm volatile("s_waitcnt lgkmcnt(" #n ")" ::: "memory")
; #define PG8_BAR __builtin_amdgcn_s_barrier()
; template <class Epi, class Sched, bool ALIGN_EPI = false, bool SP2 = false>
; __device__ __forceinline__ void gemm_phase(PG8_LAS unsigned char* lds, const Gemm g, const Sched& S, const Epi& E, const int tid_arg) {
;     ...
;         const bool has_next = S.next(ui + 1, nxt);
;         const char* nA = has_next ? (const char*)g.A + (size_t)nxt.pm * tstep : cA; const char* nB = has_next ? (const char*)g.Bt + (size_t)nxt.pn * tstep : cB;
;         for (int t = 0; t < nt; t += 2) {
;             const bool last = (t == nt - 2);
;             const char* a1 = cA + (size_t)(t + 1) * kstep;
;             const char* a2 = last ? nA : cA + (size_t)(t + 2) * kstep; const char* b2 = last ? nB : cB + (size_t)(t + 2) * kstep;
;             const char* a3 = a2 + kstep; const char* b3 = b2 + kstep;
;             if (last && has_next) S.a_ready(nxt);
;             if constexpr (SP2) {
;             PG8_LDB(B0, 0, 0); PG8_LDB(B1, 0, 1); PG8_SCHED; PG8_LDA(At, 0, 0); PG8_STAGE(PG8_SA(1, 1), a1 + hstep, voffA);
;             PG8_WAIT_V(8); PG8_WAIT_L(0); PG8_BAR; PG8_MMA(0, 0, At, B0); PG8_MMA(0, 1, At, B1); PG8_BAR; PG8_SCHED;
;     ...
; #pragma unroll
;         for (int a = 0; a < 2; ++a)
; #pragma unroll
;             for (int b = 0; b < 2; ++b)
; #pragma unroll
;                 for (int m = 0; m < 4; ++m)
; #pragma unroll
;                     for (int n = 0; n < 2; ++n) acc[a][b][m][n] = (f32x4){0.f, 0.f, 0.f, 0.f};
;         cur = nxt; cA = nA; cB = nB; ++ui;
.LBB0_1079:
	s_ashr_i32 s21, s20, 31
	s_lshl_b64 s[22:23], s[20:21], 19
	s_add_u32 s22, s0, s22
	s_addc_u32 s23, s1, s23
	s_and_b64 s[24:25], s[10:11], exec
	s_cselect_b32 s21, s23, s29
	s_cselect_b32 s47, s22, s28
	s_ashr_i32 s17, s16, 31
	s_lshl_b64 s[24:25], s[16:17], 19
	s_add_u32 s24, s2, s24
	s_addc_u32 s25, s3, s25
	s_and_b64 s[34:35], s[10:11], exec
	s_cselect_b32 s17, s25, s31
	s_cselect_b32 s48, s24, s30
	s_add_u32 s28, s28, 0x40080
	s_addc_u32 s29, s29, 0
	s_add_u32 s49, s30, 0x100
	v_mov_b32_e32 v2, 0
	s_addc_u32 s50, s31, 0
	s_mov_b32 s51, -2
	v_mov_b32_e32 v3, v2
	v_mov_b32_e32 v4, v2
	v_mov_b32_e32 v5, v2
	v_mov_b32_e32 v6, v2
	v_mov_b32_e32 v7, v2
	v_mov_b32_e32 v8, v2
	v_mov_b32_e32 v9, v2
	v_mov_b32_e32 v18, v2
	v_mov_b32_e32 v19, v2
	v_mov_b32_e32 v20, v2
	v_mov_b32_e32 v21, v2
	v_mov_b32_e32 v22, v2
	v_mov_b32_e32 v23, v2
	v_mov_b32_e32 v24, v2
	v_mov_b32_e32 v25, v2
	v_mov_b32_e32 v34, v2
	v_mov_b32_e32 v35, v2
	v_mov_b32_e32 v36, v2
	v_mov_b32_e32 v37, v2
	v_mov_b32_e32 v38, v2
	v_mov_b32_e32 v39, v2
	v_mov_b32_e32 v40, v2
	v_mov_b32_e32 v41, v2
	v_mov_b32_e32 v50, v2
	v_mov_b32_e32 v51, v2
	v_mov_b32_e32 v52, v2
	v_mov_b32_e32 v53, v2
	v_mov_b32_e32 v54, v2
	v_mov_b32_e32 v55, v2
	v_mov_b32_e32 v56, v2
	v_mov_b32_e32 v57, v2
	v_mov_b32_e32 v10, v2
	v_mov_b32_e32 v11, v2
	v_mov_b32_e32 v12, v2
	v_mov_b32_e32 v13, v2
	v_mov_b32_e32 v14, v2
	v_mov_b32_e32 v15, v2
	v_mov_b32_e32 v16, v2
	v_mov_b32_e32 v17, v2
	v_mov_b32_e32 v26, v2
	v_mov_b32_e32 v27, v2
	v_mov_b32_e32 v28, v2
	v_mov_b32_e32 v29, v2
	v_mov_b32_e32 v30, v2
	v_mov_b32_e32 v31, v2
	v_mov_b32_e32 v32, v2
	v_mov_b32_e32 v33, v2
	v_mov_b32_e32 v42, v2
	v_mov_b32_e32 v43, v2
	v_mov_b32_e32 v44, v2
	v_mov_b32_e32 v45, v2
	v_mov_b32_e32 v46, v2
	v_mov_b32_e32 v47, v2
	v_mov_b32_e32 v48, v2
	v_mov_b32_e32 v49, v2
	v_mov_b32_e32 v58, v2
	v_mov_b32_e32 v59, v2
	v_mov_b32_e32 v60, v2
	v_mov_b32_e32 v61, v2
	v_mov_b32_e32 v62, v2
	v_mov_b32_e32 v63, v2
	v_mov_b32_e32 v64, v2
	v_mov_b32_e32 v65, v2
	v_mov_b32_e32 v66, v2
	v_mov_b32_e32 v67, v2
	v_mov_b32_e32 v68, v2
	v_mov_b32_e32 v69, v2
	v_mov_b32_e32 v70, v2
	v_mov_b32_e32 v71, v2
	v_mov_b32_e32 v72, v2
	v_mov_b32_e32 v73, v2
	v_mov_b32_e32 v82, v2
	v_mov_b32_e32 v83, v2
	v_mov_b32_e32 v84, v2
	v_mov_b32_e32 v85, v2
	v_mov_b32_e32 v86, v2
	v_mov_b32_e32 v87, v2
	v_mov_b32_e32 v88, v2
	v_mov_b32_e32 v89, v2
	v_mov_b32_e32 v98, v2
	v_mov_b32_e32 v99, v2
	v_mov_b32_e32 v100, v2
	v_mov_b32_e32 v101, v2
	v_mov_b32_e32 v102, v2
	v_mov_b32_e32 v103, v2
	v_mov_b32_e32 v104, v2
	v_mov_b32_e32 v105, v2
	v_mov_b32_e32 v114, v2
	v_mov_b32_e32 v115, v2
	v_mov_b32_e32 v116, v2
	v_mov_b32_e32 v117, v2
	v_mov_b32_e32 v118, v2
	v_mov_b32_e32 v119, v2
	v_mov_b32_e32 v120, v2
	v_mov_b32_e32 v121, v2
	v_mov_b32_e32 v74, v2
	v_mov_b32_e32 v75, v2
	v_mov_b32_e32 v76, v2
	v_mov_b32_e32 v77, v2
	v_mov_b32_e32 v78, v2
	v_mov_b32_e32 v79, v2
	v_mov_b32_e32 v80, v2
	v_mov_b32_e32 v81, v2
	v_mov_b32_e32 v90, v2
	v_mov_b32_e32 v91, v2
	v_mov_b32_e32 v92, v2
	v_mov_b32_e32 v93, v2
	v_mov_b32_e32 v94, v2
	v_mov_b32_e32 v95, v2
	v_mov_b32_e32 v96, v2
	v_mov_b32_e32 v97, v2
	v_mov_b32_e32 v106, v2
	v_mov_b32_e32 v107, v2
	v_mov_b32_e32 v108, v2
	v_mov_b32_e32 v109, v2
	v_mov_b32_e32 v110, v2
	v_mov_b32_e32 v111, v2
	v_mov_b32_e32 v112, v2
	v_mov_b32_e32 v113, v2
	v_mov_b32_e32 v122, v2
	v_mov_b32_e32 v123, v2
	v_mov_b32_e32 v124, v2
	v_mov_b32_e32 v125, v2
	v_mov_b32_e32 v126, v2
	v_mov_b32_e32 v127, v2
	v_mov_b32_e32 v128, v2
	v_mov_b32_e32 v129, v2
	s_nop 0
.LBB0_1080:
	ds_read_b128 v[148:151], v155
	ds_read_b128 v[160:163], v155 offset:1024
	ds_read_b128 v[164:167], v155 offset:2048
	ds_read_b128 v[168:171], v155 offset:3072
	ds_read_b128 v[172:175], v156
	ds_read_b128 v[176:179], v156 offset:1024
	ds_read_b128 v[182:185], v156 offset:2048
	ds_read_b128 v[186:189], v156 offset:3072
	s_add_u32 s30, s28, 0xfffc0080
	s_addc_u32 s31, s29, -1
	s_cmp_eq_u32 s51, 12
	s_cselect_b32 s35, s21, s31
	s_cselect_b32 s34, s47, s30
	s_cselect_b32 s31, s17, s50
	s_cselect_b32 s30, s48, s49
	v_lshl_add_u64 v[194:195], s[28:29], 0, v[140:141]
	s_add_i32 m0, s27, 0xc000
	ds_read_b128 v[190:193], v157
	ds_read_b128 v[202:205], v157 offset:1024
	ds_read_b128 v[206:209], v157 offset:2048
	ds_read_b128 v[210:213], v157 offset:3072
	ds_read_b128 v[214:217], v157 offset:4096
	ds_read_b128 v[218:221], v157 offset:5120
	ds_read_b128 v[222:225], v157 offset:6144
	ds_read_b128 v[226:229], v157 offset:7168
	global_load_lds_dwordx4 v[194:195], off
	v_lshl_add_u64 v[194:195], s[28:29], 0, v[142:143]
	s_add_i32 m0, s27, 0xe000
	s_nop 0
	global_load_lds_dwordx4 v[194:195], off
	s_waitcnt vmcnt(8)
	s_waitcnt lgkmcnt(0)
	s_barrier
; #define PG8_STAGE(bufoff, gbase, voff) do { _Pragma("unroll") for (int _i = 0; _i < 2; ++_i) \
;         __builtin_amdgcn_global_load_lds((const unsigned*)((const char*)(gbase) + (voff)[_i]), (PG8_LAS unsigned*)(lds + (bufoff) + ldsw + _i * 8192), 16, 0, 0); } while (0)
; #define PG8_LDA(dst, b, h) do { _Pragma("unroll") for (int m = 0; m < 4; ++m) _Pragma("unroll") for (int k = 0; k < 2; ++k) dst[m][k] = *(const PG8_LAS bf16x8*)(lds + PG8_SA(b, h) + aoff + m * 2048 + k * 1024); } while (0)
; #define PG8_LDB(dst, b, h) do { _Pragma("unroll") for (int n = 0; n < 2; ++n) _Pragma("unroll") for (int k = 0; k < 2; ++k) dst[n][k] = *(const PG8_LAS bf16x8*)(lds + PG8_SB(b, h) + boff + n * 2048 + k * 1024); } while (0)
; #define PG8_MMA(ai, bj, At, Bt) do { __builtin_amdgcn_s_setprio(1); _Pragma("unroll") for (int m = 0; m < 4; ++m) _Pragma("unroll") for (int n = 0; n < 2; ++n) _Pragma("unroll") for (int k = 0; k < 2; ++k) \
;         acc[ai][bj][m][n] = __builtin_amdgcn_mfma_f32_16x16x32_bf16(Bt[n][k], At[m][k], acc[ai][bj][m][n], 0, 0, 0); __builtin_amdgcn_s_setprio(0); } while (0)
; #define PG8_WAIT_V(n) asm volatile("s_waitcnt vmcnt(" #n ")" ::: "memory")
; #define PG8_WAIT_L(n) asm volatile("s_waitcnt lgkmcnt(" #n ")" ::: "memory")
; #define PG8_BAR __builtin_amdgcn_s_barrier()
; #define PG8_SCHED __builtin_amdgcn_sched_barrier(0)
; template <class Epi, class Sched, bool ALIGN_EPI = false, bool SP2 = false>
; __device__ __forceinline__ void gemm_phase(PG8_LAS unsigned char* lds, const Gemm g, const Sched& S, const Epi& E, const int tid_arg) {
;     ...
;             PG8_WAIT_V(8); PG8_WAIT_L(0); PG8_BAR; PG8_MMA(0, 0, At, B0); PG8_MMA(0, 1, At, B1); PG8_BAR; PG8_SCHED;
;             PG8_LDA(At, 0, 1); PG8_STAGE(PG8_SB(0, 0), b2, voffB); PG8_STAGE(PG8_SB(0, 1), b2 + hstep, voffB); PG8_STAGE(PG8_SA(0, 0), a2, voffA);
;             PG8_WAIT_V(8); PG8_WAIT_L(0); PG8_BAR; PG8_MMA(1, 0, At, B0); PG8_MMA(1, 1, At, B1); PG8_BAR; PG8_SCHED;
;             PG8_LDB(B0, 1, 0); PG8_LDB(B1, 1, 1); PG8_SCHED; PG8_LDA(At, 1, 0); PG8_STAGE(PG8_SA(0, 1), a2 + hstep, voffA);
;             PG8_WAIT_V(8); PG8_WAIT_L(0); PG8_BAR; PG8_MMA(0, 0, At, B0); PG8_MMA(0, 1, At, B1); PG8_BAR; PG8_SCHED;
	s_setprio 1
	s_waitcnt lgkmcnt(0)
	v_mfma_f32_16x16x32_bf16 v[126:129], v[148:151], v[190:193], v[126:129]
	v_mfma_f32_16x16x32_bf16 v[122:125], v[164:167], v[190:193], v[122:125]
	v_mfma_f32_16x16x32_bf16 v[110:113], v[148:151], v[206:209], v[110:113]
	v_mfma_f32_16x16x32_bf16 v[106:109], v[164:167], v[206:209], v[106:109]
	v_mfma_f32_16x16x32_bf16 v[94:97], v[148:151], v[214:217], v[94:97]
	v_mfma_f32_16x16x32_bf16 v[90:93], v[164:167], v[214:217], v[90:93]
	v_mfma_f32_16x16x32_bf16 v[78:81], v[148:151], v[222:225], v[78:81]
	v_mfma_f32_16x16x32_bf16 v[74:77], v[164:167], v[222:225], v[74:77]
	v_mfma_f32_16x16x32_bf16 v[126:129], v[160:163], v[202:205], v[126:129]
	v_mfma_f32_16x16x32_bf16 v[122:125], v[168:171], v[202:205], v[122:125]
	v_mfma_f32_16x16x32_bf16 v[110:113], v[160:163], v[210:213], v[110:113]
	v_mfma_f32_16x16x32_bf16 v[106:109], v[168:171], v[210:213], v[106:109]
	v_mfma_f32_16x16x32_bf16 v[94:97], v[160:163], v[218:221], v[94:97]
	v_mfma_f32_16x16x32_bf16 v[90:93], v[168:171], v[218:221], v[90:93]
	v_mfma_f32_16x16x32_bf16 v[78:81], v[160:163], v[226:229], v[78:81]
	v_mfma_f32_16x16x32_bf16 v[74:77], v[168:171], v[226:229], v[74:77]
	s_setprio 0
	s_setprio 1
	v_mfma_f32_16x16x32_bf16 v[118:121], v[172:175], v[190:193], v[118:121]
	v_mfma_f32_16x16x32_bf16 v[114:117], v[182:185], v[190:193], v[114:117]
	v_mfma_f32_16x16x32_bf16 v[102:105], v[172:175], v[206:209], v[102:105]
	v_mfma_f32_16x16x32_bf16 v[98:101], v[182:185], v[206:209], v[98:101]
	v_mfma_f32_16x16x32_bf16 v[86:89], v[172:175], v[214:217], v[86:89]
	v_mfma_f32_16x16x32_bf16 v[82:85], v[182:185], v[214:217], v[82:85]
	v_mfma_f32_16x16x32_bf16 v[70:73], v[172:175], v[222:225], v[70:73]
	v_mfma_f32_16x16x32_bf16 v[66:69], v[182:185], v[222:225], v[66:69]
	v_mfma_f32_16x16x32_bf16 v[118:121], v[176:179], v[202:205], v[118:121]
	v_mfma_f32_16x16x32_bf16 v[114:117], v[186:189], v[202:205], v[114:117]
	v_mfma_f32_16x16x32_bf16 v[102:105], v[176:179], v[210:213], v[102:105]
	v_mfma_f32_16x16x32_bf16 v[98:101], v[186:189], v[210:213], v[98:101]
	v_mfma_f32_16x16x32_bf16 v[86:89], v[176:179], v[218:221], v[86:89]
	v_mfma_f32_16x16x32_bf16 v[82:85], v[186:189], v[218:221], v[82:85]
	v_mfma_f32_16x16x32_bf16 v[70:73], v[176:179], v[226:229], v[70:73]
	v_mfma_f32_16x16x32_bf16 v[66:69], v[186:189], v[226:229], v[66:69]
	s_setprio 0
	s_barrier
	s_add_i32 s52, s42, s33
	v_lshl_add_u64 v[194:195], s[30:31], 0, v[132:133]
	s_mov_b32 m0, s52
	ds_read_b128 v[190:193], v157 offset:16384
	ds_read_b128 v[202:205], v157 offset:17408
	ds_read_b128 v[206:209], v157 offset:18432
	ds_read_b128 v[210:213], v157 offset:19456
	ds_read_b128 v[214:217], v157 offset:20480
	ds_read_b128 v[218:221], v157 offset:21504
	ds_read_b128 v[222:225], v157 offset:22528
	ds_read_b128 v[226:229], v157 offset:23552
	global_load_lds_dwordx4 v[194:195], off
	s_add_i32 m0, s52, 0x2000
	s_add_u32 s52, s30, 0x40000
	v_lshl_add_u64 v[230:231], s[30:31], 0, v[136:137]
	s_addc_u32 s53, s31, 0
	s_add_i32 s54, s43, s33
	global_load_lds_dwordx4 v[230:231], off
	v_lshl_add_u64 v[232:233], s[52:53], 0, v[132:133]
	s_mov_b32 m0, s54
	v_lshl_add_u64 v[234:235], s[34:35], 0, v[134:135]
	global_load_lds_dwordx4 v[232:233], off
	v_lshl_add_u64 v[232:233], s[52:53], 0, v[136:137]
	s_add_i32 m0, s54, 0x2000
	s_nop 0
	global_load_lds_dwordx4 v[232:233], off
	v_lshl_add_u64 v[232:233], s[34:35], 0, v[130:131]
	s_mov_b32 m0, s27
	s_nop 0
	global_load_lds_dwordx4 v[232:233], off
	s_mov_b32 m0, s36
	s_nop 0
	global_load_lds_dwordx4 v[234:235], off
	s_waitcnt vmcnt(8)
	s_waitcnt lgkmcnt(0)
	s_barrier
	s_setprio 1
	s_waitcnt lgkmcnt(0)
	v_mfma_f32_16x16x32_bf16 v[62:65], v[148:151], v[190:193], v[62:65]
	v_mfma_f32_16x16x32_bf16 v[58:61], v[164:167], v[190:193], v[58:61]
	v_mfma_f32_16x16x32_bf16 v[46:49], v[148:151], v[206:209], v[46:49]
	v_mfma_f32_16x16x32_bf16 v[42:45], v[164:167], v[206:209], v[42:45]
	v_mfma_f32_16x16x32_bf16 v[30:33], v[148:151], v[214:217], v[30:33]
	v_mfma_f32_16x16x32_bf16 v[26:29], v[164:167], v[214:217], v[26:29]
	v_mfma_f32_16x16x32_bf16 v[14:17], v[148:151], v[222:225], v[14:17]
	v_mfma_f32_16x16x32_bf16 v[10:13], v[164:167], v[222:225], v[10:13]
	v_mfma_f32_16x16x32_bf16 v[62:65], v[160:163], v[202:205], v[62:65]
	v_mfma_f32_16x16x32_bf16 v[58:61], v[168:171], v[202:205], v[58:61]
	v_mfma_f32_16x16x32_bf16 v[46:49], v[160:163], v[210:213], v[46:49]
	v_mfma_f32_16x16x32_bf16 v[42:45], v[168:171], v[210:213], v[42:45]
	v_mfma_f32_16x16x32_bf16 v[30:33], v[160:163], v[218:221], v[30:33]
	v_mfma_f32_16x16x32_bf16 v[26:29], v[168:171], v[218:221], v[26:29]
	v_mfma_f32_16x16x32_bf16 v[14:17], v[160:163], v[226:229], v[14:17]
	v_mfma_f32_16x16x32_bf16 v[10:13], v[168:171], v[226:229], v[10:13]
	s_setprio 0
	s_setprio 1
	v_mfma_f32_16x16x32_bf16 v[54:57], v[172:175], v[190:193], v[54:57]
	v_mfma_f32_16x16x32_bf16 v[50:53], v[182:185], v[190:193], v[50:53]
	v_mfma_f32_16x16x32_bf16 v[38:41], v[172:175], v[206:209], v[38:41]
	v_mfma_f32_16x16x32_bf16 v[34:37], v[182:185], v[206:209], v[34:37]
	v_mfma_f32_16x16x32_bf16 v[22:25], v[172:175], v[214:217], v[22:25]
	v_mfma_f32_16x16x32_bf16 v[18:21], v[182:185], v[214:217], v[18:21]
	v_mfma_f32_16x16x32_bf16 v[6:9], v[172:175], v[222:225], v[6:9]
	v_mfma_f32_16x16x32_bf16 v[2:5], v[182:185], v[222:225], v[2:5]
	v_mfma_f32_16x16x32_bf16 v[54:57], v[176:179], v[202:205], v[54:57]
	v_mfma_f32_16x16x32_bf16 v[50:53], v[186:189], v[202:205], v[50:53]
	v_mfma_f32_16x16x32_bf16 v[38:41], v[176:179], v[210:213], v[38:41]
	v_mfma_f32_16x16x32_bf16 v[34:37], v[186:189], v[210:213], v[34:37]
	v_mfma_f32_16x16x32_bf16 v[22:25], v[176:179], v[218:221], v[22:25]
	v_mfma_f32_16x16x32_bf16 v[18:21], v[186:189], v[218:221], v[18:21]
	v_mfma_f32_16x16x32_bf16 v[6:9], v[176:179], v[226:229], v[6:9]
	v_mfma_f32_16x16x32_bf16 v[2:5], v[186:189], v[226:229], v[2:5]
	s_setprio 0
	s_barrier
; #define PG8_STAGE(bufoff, gbase, voff) do { _Pragma("unroll") for (int _i = 0; _i < 2; ++_i) \
;         __builtin_amdgcn_global_load_lds((const unsigned*)((const char*)(gbase) + (voff)[_i]), (PG8_LAS unsigned*)(lds + (bufoff) + ldsw + _i * 8192), 16, 0, 0); } while (0)
; #define PG8_LDA(dst, b, h) do { _Pragma("unroll") for (int m = 0; m < 4; ++m) _Pragma("unroll") for (int k = 0; k < 2; ++k) dst[m][k] = *(const PG8_LAS bf16x8*)(lds + PG8_SA(b, h) + aoff + m * 2048 + k * 1024); } while (0)
; #define PG8_LDB(dst, b, h) do { _Pragma("unroll") for (int n = 0; n < 2; ++n) _Pragma("unroll") for (int k = 0; k < 2; ++k) dst[n][k] = *(const PG8_LAS bf16x8*)(lds + PG8_SB(b, h) + boff + n * 2048 + k * 1024); } while (0)
; #define PG8_MMA(ai, bj, At, Bt) do { __builtin_amdgcn_s_setprio(1); _Pragma("unroll") for (int m = 0; m < 4; ++m) _Pragma("unroll") for (int n = 0; n < 2; ++n) _Pragma("unroll") for (int k = 0; k < 2; ++k) \
;         acc[ai][bj][m][n] = __builtin_amdgcn_mfma_f32_16x16x32_bf16(Bt[n][k], At[m][k], acc[ai][bj][m][n], 0, 0, 0); __builtin_amdgcn_s_setprio(0); } while (0)
; #define PG8_WAIT_V(n) asm volatile("s_waitcnt vmcnt(" #n ")" ::: "memory")
; #define PG8_WAIT_L(n) asm volatile("s_waitcnt lgkmcnt(" #n ")" ::: "memory")
; #define PG8_BAR __builtin_amdgcn_s_barrier()
; #define PG8_SCHED __builtin_amdgcn_sched_barrier(0)
; template <class Epi, class Sched, bool ALIGN_EPI = false, bool SP2 = false>
; __device__ __forceinline__ void gemm_phase(PG8_LAS unsigned char* lds, const Gemm g, const Sched& S, const Epi& E, const int tid_arg) {
;     ...
;             PG8_LDB(B0, 1, 0); PG8_LDB(B1, 1, 1); PG8_SCHED; PG8_LDA(At, 1, 0); PG8_STAGE(PG8_SA(0, 1), a2 + hstep, voffA);
;             PG8_WAIT_V(8); PG8_WAIT_L(0); PG8_BAR; PG8_MMA(0, 0, At, B0); PG8_MMA(0, 1, At, B1); PG8_BAR; PG8_SCHED;
	s_add_i32 s52, 0, 0x18000
	v_add_u32_e32 v159, s52, v153
	s_add_i32 s53, 0, 0x1c000
	ds_read_b128 v[148:151], v159
	ds_read_b128 v[160:163], v159 offset:1024
	ds_read_b128 v[164:167], v159 offset:2048
	ds_read_b128 v[168:171], v159 offset:3072
	v_add_u32_e32 v159, s53, v153
	ds_read_b128 v[172:175], v159
	ds_read_b128 v[176:179], v159 offset:1024
	ds_read_b128 v[182:185], v159 offset:2048
	ds_read_b128 v[186:189], v159 offset:3072
	s_add_u32 s34, s34, 0x40000
	s_addc_u32 s35, s35, 0
	s_mov_b32 m0, s37
	v_lshl_add_u64 v[236:237], s[34:35], 0, v[130:131]
	ds_read_b128 v[190:193], v157 offset:32768
	ds_read_b128 v[202:205], v157 offset:33792
	ds_read_b128 v[206:209], v157 offset:34816
	ds_read_b128 v[210:213], v157 offset:35840
	ds_read_b128 v[214:217], v157 offset:36864
	ds_read_b128 v[218:221], v157 offset:37888
	ds_read_b128 v[222:225], v157 offset:38912
	ds_read_b128 v[226:229], v157 offset:39936
	global_load_lds_dwordx4 v[236:237], off
	v_lshl_add_u64 v[236:237], s[34:35], 0, v[134:135]
	s_mov_b32 m0, s38
	s_nop 0
	global_load_lds_dwordx4 v[236:237], off
	s_waitcnt vmcnt(8)
	s_waitcnt lgkmcnt(0)
	s_barrier
	s_setprio 1
	s_waitcnt lgkmcnt(0)
	v_mfma_f32_16x16x32_bf16 v[126:129], v[148:151], v[190:193], v[126:129]
	v_mfma_f32_16x16x32_bf16 v[122:125], v[164:167], v[190:193], v[122:125]
	v_mfma_f32_16x16x32_bf16 v[110:113], v[148:151], v[206:209], v[110:113]
	v_mfma_f32_16x16x32_bf16 v[106:109], v[164:167], v[206:209], v[106:109]
	v_mfma_f32_16x16x32_bf16 v[94:97], v[148:151], v[214:217], v[94:97]
	v_mfma_f32_16x16x32_bf16 v[90:93], v[164:167], v[214:217], v[90:93]
	v_mfma_f32_16x16x32_bf16 v[78:81], v[148:151], v[222:225], v[78:81]
	v_mfma_f32_16x16x32_bf16 v[74:77], v[164:167], v[222:225], v[74:77]
	v_mfma_f32_16x16x32_bf16 v[126:129], v[160:163], v[202:205], v[126:129]
	v_mfma_f32_16x16x32_bf16 v[122:125], v[168:171], v[202:205], v[122:125]
	v_mfma_f32_16x16x32_bf16 v[110:113], v[160:163], v[210:213], v[110:113]
	v_mfma_f32_16x16x32_bf16 v[106:109], v[168:171], v[210:213], v[106:109]
	v_mfma_f32_16x16x32_bf16 v[94:97], v[160:163], v[218:221], v[94:97]
	v_mfma_f32_16x16x32_bf16 v[90:93], v[168:171], v[218:221], v[90:93]
	v_mfma_f32_16x16x32_bf16 v[78:81], v[160:163], v[226:229], v[78:81]
	v_mfma_f32_16x16x32_bf16 v[74:77], v[168:171], v[226:229], v[74:77]
	s_setprio 0
	s_setprio 1
	v_mfma_f32_16x16x32_bf16 v[118:121], v[172:175], v[190:193], v[118:121]
	v_mfma_f32_16x16x32_bf16 v[114:117], v[182:185], v[190:193], v[114:117]
	v_mfma_f32_16x16x32_bf16 v[102:105], v[172:175], v[206:209], v[102:105]
	v_mfma_f32_16x16x32_bf16 v[98:101], v[182:185], v[206:209], v[98:101]
	v_mfma_f32_16x16x32_bf16 v[86:89], v[172:175], v[214:217], v[86:89]
	v_mfma_f32_16x16x32_bf16 v[82:85], v[182:185], v[214:217], v[82:85]
	v_mfma_f32_16x16x32_bf16 v[70:73], v[172:175], v[222:225], v[70:73]
	v_mfma_f32_16x16x32_bf16 v[66:69], v[182:185], v[222:225], v[66:69]
	v_mfma_f32_16x16x32_bf16 v[118:121], v[176:179], v[202:205], v[118:121]
	v_mfma_f32_16x16x32_bf16 v[114:117], v[186:189], v[202:205], v[114:117]
	v_mfma_f32_16x16x32_bf16 v[102:105], v[176:179], v[210:213], v[102:105]
	v_mfma_f32_16x16x32_bf16 v[98:101], v[186:189], v[210:213], v[98:101]
	v_mfma_f32_16x16x32_bf16 v[86:89], v[176:179], v[218:221], v[86:89]
	v_mfma_f32_16x16x32_bf16 v[82:85], v[186:189], v[218:221], v[82:85]
	v_mfma_f32_16x16x32_bf16 v[70:73], v[176:179], v[226:229], v[70:73]
	v_mfma_f32_16x16x32_bf16 v[66:69], v[186:189], v[226:229], v[66:69]
	s_setprio 0
	s_barrier
; #define PG8_STAGE(bufoff, gbase, voff) do { _Pragma("unroll") for (int _i = 0; _i < 2; ++_i) \
;         __builtin_amdgcn_global_load_lds((const unsigned*)((const char*)(gbase) + (voff)[_i]), (PG8_LAS unsigned*)(lds + (bufoff) + ldsw + _i * 8192), 16, 0, 0); } while (0)
; #define PG8_LDA(dst, b, h) do { _Pragma("unroll") for (int m = 0; m < 4; ++m) _Pragma("unroll") for (int k = 0; k < 2; ++k) dst[m][k] = *(const PG8_LAS bf16x8*)(lds + PG8_SA(b, h) + aoff + m * 2048 + k * 1024); } while (0)
; #define PG8_MMA(ai, bj, At, Bt) do { __builtin_amdgcn_s_setprio(1); _Pragma("unroll") for (int m = 0; m < 4; ++m) _Pragma("unroll") for (int n = 0; n < 2; ++n) _Pragma("unroll") for (int k = 0; k < 2; ++k) \
;         acc[ai][bj][m][n] = __builtin_amdgcn_mfma_f32_16x16x32_bf16(Bt[n][k], At[m][k], acc[ai][bj][m][n], 0, 0, 0); __builtin_amdgcn_s_setprio(0); } while (0)
; #define PG8_WAIT_V(n) asm volatile("s_waitcnt vmcnt(" #n ")" ::: "memory")
; #define PG8_WAIT_L(n) asm volatile("s_waitcnt lgkmcnt(" #n ")" ::: "memory")
; #define PG8_BAR __builtin_amdgcn_s_barrier()
; #define PG8_SCHED __builtin_amdgcn_sched_barrier(0)
;     __device__ __forceinline__ void operator()(const f32x4 (&acc)[2][2][4][2], const Unit& u, int wr, int wc, int fr, int fq) const {
;         const int row0 = u.pm * BM + wr * 64 + fr, col0 = u.pn * 128 + wc * 32 + 8 * fq;
; #pragma unroll
;         for (int ai = 0; ai < 2; ++ai)
; #pragma unroll
;             for (int m = 0; m < 4; ++m) {
;                 int row = row0 + ai * HALF + m * 16; asm volatile("" : "+v"(row));
;                 const float rs = SS ? rstd_from_ss(SS + (size_t)row * 16, fq) : 1.0f;
; template <class Epi, class Sched, bool ALIGN_EPI = false, bool SP2 = false>
; __device__ __forceinline__ void gemm_phase(PG8_LAS unsigned char* lds, const Gemm g, const Sched& S, const Epi& E, const int tid_arg) {
;     ...
;             PG8_LDA(At, 1, 1); PG8_STAGE(PG8_SB(1, 0), b3, voffB); PG8_STAGE(PG8_SB(1, 1), b3 + hstep, voffB); PG8_STAGE(PG8_SA(1, 0), a3, voffA);
;             PG8_WAIT_V(8); PG8_WAIT_L(0); PG8_BAR; PG8_MMA(1, 0, At, B0); PG8_MMA(1, 1, At, B1); PG8_BAR; PG8_SCHED;
	s_add_i32 s34, s52, s33
	v_lshl_add_u64 v[194:195], v[194:195], 0, s[12:13]
	s_mov_b32 m0, s34
	ds_read_b128 v[190:193], v157 offset:49152
	ds_read_b128 v[202:205], v157 offset:50176
	ds_read_b128 v[206:209], v157 offset:51200
	ds_read_b128 v[210:213], v157 offset:52224
	ds_read_b128 v[214:217], v157 offset:53248
	ds_read_b128 v[218:221], v157 offset:54272
	ds_read_b128 v[222:225], v157 offset:55296
	ds_read_b128 v[226:229], v157 offset:56320
	global_load_lds_dwordx4 v[194:195], off
	s_add_i32 m0, s34, 0x2000
	s_add_u32 s30, s30, 0x40080
	v_lshl_add_u64 v[194:195], v[230:231], 0, s[12:13]
	s_addc_u32 s31, s31, 0
	s_add_i32 s34, s53, s33
	global_load_lds_dwordx4 v[194:195], off
	v_lshl_add_u64 v[194:195], s[30:31], 0, v[132:133]
	s_mov_b32 m0, s34
	s_nop 0
	global_load_lds_dwordx4 v[194:195], off
	v_lshl_add_u64 v[194:195], s[30:31], 0, v[136:137]
	s_add_i32 m0, s34, 0x2000
	s_nop 0
	global_load_lds_dwordx4 v[194:195], off
	v_lshl_add_u64 v[194:195], v[232:233], 0, s[12:13]
	s_mov_b32 m0, s40
	s_nop 0
	global_load_lds_dwordx4 v[194:195], off
	v_lshl_add_u64 v[194:195], v[234:235], 0, s[12:13]
	s_mov_b32 m0, s41
	s_nop 0
	global_load_lds_dwordx4 v[194:195], off
	s_waitcnt vmcnt(8)
	s_waitcnt lgkmcnt(0)
	s_barrier
	s_setprio 1
	s_waitcnt lgkmcnt(0)
	v_mfma_f32_16x16x32_bf16 v[62:65], v[148:151], v[190:193], v[62:65]
	v_mfma_f32_16x16x32_bf16 v[58:61], v[164:167], v[190:193], v[58:61]
	v_mfma_f32_16x16x32_bf16 v[46:49], v[148:151], v[206:209], v[46:49]
	v_mfma_f32_16x16x32_bf16 v[42:45], v[164:167], v[206:209], v[42:45]
	v_mfma_f32_16x16x32_bf16 v[30:33], v[148:151], v[214:217], v[30:33]
	v_mfma_f32_16x16x32_bf16 v[26:29], v[164:167], v[214:217], v[26:29]
	v_mfma_f32_16x16x32_bf16 v[14:17], v[148:151], v[222:225], v[14:17]
	v_mfma_f32_16x16x32_bf16 v[10:13], v[164:167], v[222:225], v[10:13]
	v_mfma_f32_16x16x32_bf16 v[62:65], v[160:163], v[202:205], v[62:65]
	v_mfma_f32_16x16x32_bf16 v[58:61], v[168:171], v[202:205], v[58:61]
	v_mfma_f32_16x16x32_bf16 v[46:49], v[160:163], v[210:213], v[46:49]
	v_mfma_f32_16x16x32_bf16 v[42:45], v[168:171], v[210:213], v[42:45]
	v_mfma_f32_16x16x32_bf16 v[30:33], v[160:163], v[218:221], v[30:33]
	v_mfma_f32_16x16x32_bf16 v[26:29], v[168:171], v[218:221], v[26:29]
	v_mfma_f32_16x16x32_bf16 v[14:17], v[160:163], v[226:229], v[14:17]
	v_mfma_f32_16x16x32_bf16 v[10:13], v[168:171], v[226:229], v[10:13]
	s_setprio 0
	s_setprio 1
	v_mfma_f32_16x16x32_bf16 v[54:57], v[172:175], v[190:193], v[54:57]
	v_mfma_f32_16x16x32_bf16 v[50:53], v[182:185], v[190:193], v[50:53]
	v_mfma_f32_16x16x32_bf16 v[38:41], v[172:175], v[206:209], v[38:41]
	v_mfma_f32_16x16x32_bf16 v[34:37], v[182:185], v[206:209], v[34:37]
	v_mfma_f32_16x16x32_bf16 v[22:25], v[172:175], v[214:217], v[22:25]
	v_mfma_f32_16x16x32_bf16 v[18:21], v[182:185], v[214:217], v[18:21]
	v_mfma_f32_16x16x32_bf16 v[6:9], v[172:175], v[222:225], v[6:9]
	v_mfma_f32_16x16x32_bf16 v[2:5], v[182:185], v[222:225], v[2:5]
	v_mfma_f32_16x16x32_bf16 v[54:57], v[176:179], v[202:205], v[54:57]
	v_mfma_f32_16x16x32_bf16 v[50:53], v[186:189], v[202:205], v[50:53]
	v_mfma_f32_16x16x32_bf16 v[38:41], v[176:179], v[210:213], v[38:41]
	v_mfma_f32_16x16x32_bf16 v[34:37], v[186:189], v[210:213], v[34:37]
	v_mfma_f32_16x16x32_bf16 v[22:25], v[176:179], v[218:221], v[22:25]
	v_mfma_f32_16x16x32_bf16 v[18:21], v[186:189], v[218:221], v[18:21]
	v_mfma_f32_16x16x32_bf16 v[6:9], v[176:179], v[226:229], v[6:9]
	v_mfma_f32_16x16x32_bf16 v[2:5], v[186:189], v[226:229], v[2:5]
	s_setprio 0
	s_barrier
	s_add_i32 s51, s51, 2
	s_add_u32 s28, s28, 0x100
	s_addc_u32 s29, s29, 0
	s_add_u32 s49, s49, 0x100
	s_addc_u32 s50, s50, 0
	s_cmp_gt_u32 s51, 13
	s_cbranch_scc0 .LBB0_1080
	v_lshl_add_u32 v159, s26, 8, v152
	v_mov_b32_e32 v231, 0
	v_mov_b32_e32 v230, v159
	v_add_u32_e32 v232, 0x80, v159
	v_mov_b32_e32 v233, 0
	v_lshlrev_b64 v[230:231], 6, v[230:231]
	v_lshlrev_b64 v[232:233], 6, v[232:233]
	v_lshl_add_u64 v[230:231], v[138:139], 0, v[230:231]
	v_lshl_add_u64 v[232:233], v[138:139], 0, v[232:233]
	global_load_dwordx4 v[190:193], v[230:231], off
	global_load_dwordx4 v[202:205], v[230:231], off offset:1024
	global_load_dwordx4 v[206:209], v[230:231], off offset:2048
	global_load_dwordx4 v[210:213], v[230:231], off offset:3072
	global_load_dwordx4 v[214:217], v[232:233], off
	global_load_dwordx4 v[218:221], v[232:233], off offset:1024
	global_load_dwordx4 v[222:225], v[232:233], off offset:2048
	global_load_dwordx4 v[226:229], v[232:233], off offset:3072
	s_and_b64 vcc, exec, s[14:15]
	s_cbranch_vccz .LBB0_1083
	s_barrier

; __device__ __forceinline__ unsigned xb_ld(unsigned* p)              { return __hip_atomic_load(p, __ATOMIC_RELAXED, __HIP_MEMORY_SCOPE_AGENT); }
; __device__ __forceinline__ unsigned xb_add(unsigned* p, unsigned v) { return __hip_atomic_fetch_add(p, v, __ATOMIC_RELAXED, __HIP_MEMORY_SCOPE_AGENT); }
; #define XB_SPIN(cond, bar) do { unsigned _sp = 0; while (cond) { __builtin_amdgcn_s_sleep(1); \
;     if ((++_sp & 255u) == 0u) { if (xb_ld(&(bar)[XB_TMO])) break; if (_sp > XB_SPIN_CAP) { atomicAdd(&(bar)[XB_TMO], 1u); break; } } } } while (0)
; __device__ __forceinline__ void xcd_barrier(const XcdBarrier& b, const bool leader) {
;     ...
;         const unsigned old = xb_add(&bar[XB_XSUB(b.x)], 1u);
;         const unsigned gen = old / nloc;
;         if (old + 1u == (gen + 1u) * nloc) {
;             __builtin_amdgcn_fence(__ATOMIC_RELEASE, "agent");
;             asm volatile("s_waitcnt vmcnt(0)" ::: "memory");
;             const unsigned og = xb_add(&bar[XB_TOP], 1u);
;             const unsigned tg = og / nx;
;             if (og + 1u == (tg + 1u) * nx) xb_add(&bar[XB_TOPGEN], 1u);
;             else XB_SPIN(xb_ld(&bar[XB_TOPGEN]) == tg, bar);
;             __builtin_amdgcn_fence(__ATOMIC_ACQUIRE, "agent");
;             xb_add(&bar[XB_XGEN(b.x)], 1u);
;             asm volatile("s_waitcnt vmcnt(0)" ::: "memory");
;         } else {
;             XB_SPIN(xb_ld(&bar[XB_XGEN(b.x)]) == gen, bar);
.LBB0_1115:
	s_or_b64 exec, exec, s[12:13]
	v_cvt_f32_u32_e32 v4, v2
	s_waitcnt vmcnt(0)
	v_readfirstlane_b32 s0, v3
	v_sub_u32_e32 v3, 0, v2
	v_rcp_iflag_f32_e32 v4, v4
	v_add_u32_e32 v5, s0, v1
	v_mul_f32_e32 v4, 0x4f7ffffe, v4
	v_cvt_u32_f32_e32 v4, v4
	v_mul_lo_u32 v1, v3, v4
	v_mul_hi_u32 v1, v4, v1
	v_add_u32_e32 v1, v4, v1
	v_mul_hi_u32 v1, v5, v1
	v_mul_lo_u32 v3, v1, v2
	v_sub_u32_e32 v3, v5, v3
	v_add_u32_e32 v4, 1, v1
	v_cmp_ge_u32_e32 vcc, v3, v2
	s_nop 1
	v_cndmask_b32_e32 v1, v1, v4, vcc
	v_sub_u32_e32 v4, v3, v2
	v_cndmask_b32_e32 v3, v3, v4, vcc
	v_add_u32_e32 v4, 1, v1
	v_cmp_ge_u32_e32 vcc, v3, v2
	v_add_u32_e32 v3, 1, v5
	s_nop 0
	v_cndmask_b32_e32 v1, v1, v4, vcc
	v_mul_lo_u32 v4, v2, v1
	v_add_u32_e32 v2, v4, v2
	v_cmp_ne_u32_e32 vcc, v3, v2
	s_and_saveexec_b64 s[0:1], vcc
	s_xor_b64 s[10:11], exec, s[0:1]
	s_cbranch_execz .LBB0_1129
	buffer_inv sc1
	s_waitcnt lgkmcnt(0)
	v_mov_b32_e32 v0, 0x2000
	s_load_dwordx2 s[16:17], s[90:91], 0xb0
	s_waitcnt lgkmcnt(0)
	s_add_u32 s16, s16, 0x1d79b500
	s_addc_u32 s17, s17, 0
	v_mov_b32_e32 v0, 0
	global_load_dword v0, v0, s[16:17] sc1
	s_waitcnt vmcnt(0)
	v_cmp_eq_u32_e32 vcc, v0, v1
	s_and_saveexec_b64 s[12:13], vcc
	s_cbranch_execz .LBB0_1128
	s_add_u32 s14, s18, 0x1d798200
	s_addc_u32 s15, s19, 0
	s_mov_b32 s0, 1
	s_mov_b64 s[20:21], 0
	v_mov_b32_e32 v0, 0
	s_branch .LBB0_1119

; __device__ __forceinline__ unsigned xb_add(unsigned* p, unsigned v) { return __hip_atomic_fetch_add(p, v, __ATOMIC_RELAXED, __HIP_MEMORY_SCOPE_AGENT); }
; __device__ __forceinline__ void xcd_barrier(const XcdBarrier& b, const bool leader) {
;     ...
;         if (old + 1u == (gen + 1u) * nloc) {
;             __builtin_amdgcn_fence(__ATOMIC_RELEASE, "agent");
;             asm volatile("s_waitcnt vmcnt(0)" ::: "memory");
;             const unsigned og = xb_add(&bar[XB_TOP], 1u);
;             const unsigned tg = og / nx;
;             if (og + 1u == (tg + 1u) * nx) xb_add(&bar[XB_TOPGEN], 1u);
.LBB0_1129:
	s_andn2_saveexec_b64 s[0:1], s[10:11]
	s_cbranch_execz .LBB0_1149
	s_mov_b64 s[10:11], exec
	buffer_wbl2 sc1
	buffer_inv sc1
	s_waitcnt lgkmcnt(0)
	s_waitcnt vmcnt(0)
	v_mbcnt_lo_u32_b32 v1, s10, 0
	v_mbcnt_hi_u32_b32 v1, s11, v1
	v_cmp_eq_u32_e32 vcc, 0, v1
	s_and_saveexec_b64 s[12:13], vcc
	s_cbranch_execz .LBB0_1132
	s_bcnt1_i32_b64 s0, s[10:11]
	v_mov_b32_e32 v2, 0x1d79b000
	v_mov_b32_e32 v3, s0
	global_atomic_add v2, v2, v3, s[18:19] offset:1024 sc0

; __device__ __forceinline__ unsigned xb_ld(unsigned* p)              { return __hip_atomic_load(p, __ATOMIC_RELAXED, __HIP_MEMORY_SCOPE_AGENT); }
; __device__ __forceinline__ unsigned xb_add(unsigned* p, unsigned v) { return __hip_atomic_fetch_add(p, v, __ATOMIC_RELAXED, __HIP_MEMORY_SCOPE_AGENT); }
; #define XB_SPIN(cond, bar) do { unsigned _sp = 0; while (cond) { __builtin_amdgcn_s_sleep(1); \
;     if ((++_sp & 255u) == 0u) { if (xb_ld(&(bar)[XB_TMO])) break; if (_sp > XB_SPIN_CAP) { atomicAdd(&(bar)[XB_TMO], 1u); break; } } } } while (0)
; __device__ __forceinline__ void xcd_barrier(const XcdBarrier& b, const bool leader) {
;     ...
;             if (og + 1u == (tg + 1u) * nx) xb_add(&bar[XB_TOPGEN], 1u);
;             else XB_SPIN(xb_ld(&bar[XB_TOPGEN]) == tg, bar);
;             __builtin_amdgcn_fence(__ATOMIC_ACQUIRE, "agent");
;             xb_add(&bar[XB_XGEN(b.x)], 1u);
;             asm volatile("s_waitcnt vmcnt(0)" ::: "memory");
;         } else {
;             XB_SPIN(xb_ld(&bar[XB_XGEN(b.x)]) == gen, bar);
;             __builtin_amdgcn_fence(__ATOMIC_ACQUIRE, "agent");
;             asm volatile("s_waitcnt vmcnt(0)" ::: "memory");
.LBB0_1146:
	s_or_b64 exec, exec, s[10:11]
	s_mov_b64 s[10:11], exec
	v_mbcnt_lo_u32_b32 v0, s10, 0
	v_mbcnt_hi_u32_b32 v0, s11, v0
	v_cmp_eq_u32_e32 vcc, 0, v0
	s_waitcnt vmcnt(0)
	s_and_saveexec_b64 s[12:13], vcc
	s_cbranch_execz .LBB0_1148
	s_bcnt1_i32_b64 s0, s[10:11]
	v_mov_b32_e32 v0, 0x2000
	v_mov_b32_e32 v1, s0
	global_atomic_add v0, v1, s[6:7] offset:1024
.LBB0_1148:
	s_or_b64 exec, exec, s[12:13]
	s_waitcnt vmcnt(0)

; #define PG8_STAGE(bufoff, gbase, voff) do { _Pragma("unroll") for (int _i = 0; _i < 2; ++_i) \
;         __builtin_amdgcn_global_load_lds((const unsigned*)((const char*)(gbase) + (voff)[_i]), (PG8_LAS unsigned*)(lds + (bufoff) + ldsw + _i * 8192), 16, 0, 0); } while (0)
; #define PG8_LDA(dst, b, h) do { _Pragma("unroll") for (int m = 0; m < 4; ++m) _Pragma("unroll") for (int k = 0; k < 2; ++k) dst[m][k] = *(const PG8_LAS bf16x8*)(lds + PG8_SA(b, h) + aoff + m * 2048 + k * 1024); } while (0)
; #define PG8_LDB(dst, b, h) do { _Pragma("unroll") for (int n = 0; n < 2; ++n) _Pragma("unroll") for (int k = 0; k < 2; ++k) dst[n][k] = *(const PG8_LAS bf16x8*)(lds + PG8_SB(b, h) + boff + n * 2048 + k * 1024); } while (0)
; #define PG8_MMA(ai, bj, At, Bt) do { __builtin_amdgcn_s_setprio(1); _Pragma("unroll") for (int m = 0; m < 4; ++m) _Pragma("unroll") for (int n = 0; n < 2; ++n) _Pragma("unroll") for (int k = 0; k < 2; ++k) \
;         acc[ai][bj][m][n] = __builtin_amdgcn_mfma_f32_16x16x32_bf16(Bt[n][k], At[m][k], acc[ai][bj][m][n], 0, 0, 0); __builtin_amdgcn_s_setprio(0); } while (0)
; #define PG8_WAIT_V(n) asm volatile("s_waitcnt vmcnt(" #n ")" ::: "memory")
; #define PG8_WAIT_L(n) asm volatile("s_waitcnt lgkmcnt(" #n ")" ::: "memory")
; #define PG8_BAR __builtin_amdgcn_s_barrier()
; #define PG8_SCHED __builtin_amdgcn_sched_barrier(0)
; template <class Epi, class Sched, bool ALIGN_EPI = false, bool SP2 = false>
; __device__ __forceinline__ void gemm_phase(PG8_LAS unsigned char* lds, const Gemm g, const Sched& S, const Epi& E, const int tid_arg) {
;     ...
;             PG8_LDB(B0, 0, 0); PG8_LDB(B1, 0, 1); PG8_SCHED; PG8_LDA(At, 0, 0); PG8_STAGE(PG8_SA(1, 1), a1 + hstep, voffA);
;             PG8_WAIT_V(8); PG8_WAIT_L(0); PG8_BAR; PG8_MMA(0, 0, At, B0); PG8_MMA(0, 1, At, B1); PG8_BAR; PG8_SCHED;
;     ...
; #pragma unroll
;         for (int a = 0; a < 2; ++a)
; #pragma unroll
;             for (int b = 0; b < 2; ++b)
; #pragma unroll
;                 for (int m = 0; m < 4; ++m)
; #pragma unroll
;                     for (int n = 0; n < 2; ++n) acc[a][b][m][n] = (f32x4){0.f, 0.f, 0.f, 0.f};
;         cur = nxt; cA = nA; cB = nB; ++ui;
.LBB0_1169:
	s_add_u32 s23, s26, 0x100
	v_mov_b32_e32 v0, 0
	s_addc_u32 s46, s27, 0
	s_mov_b32 s47, -2
	v_mov_b32_e32 v1, v0
	v_mov_b32_e32 v2, v0
	v_mov_b32_e32 v3, v0
	v_mov_b32_e32 v4, v0
	v_mov_b32_e32 v5, v0
	v_mov_b32_e32 v6, v0
	v_mov_b32_e32 v7, v0
	v_mov_b32_e32 v16, v0
	v_mov_b32_e32 v17, v0
	v_mov_b32_e32 v18, v0
	v_mov_b32_e32 v19, v0
	v_mov_b32_e32 v20, v0
	v_mov_b32_e32 v21, v0
	v_mov_b32_e32 v22, v0
	v_mov_b32_e32 v23, v0
	v_mov_b32_e32 v32, v0
	v_mov_b32_e32 v33, v0
	v_mov_b32_e32 v34, v0
	v_mov_b32_e32 v35, v0
	v_mov_b32_e32 v36, v0
	v_mov_b32_e32 v37, v0
	v_mov_b32_e32 v38, v0
	v_mov_b32_e32 v39, v0
	v_mov_b32_e32 v48, v0
	v_mov_b32_e32 v49, v0
	v_mov_b32_e32 v50, v0
	v_mov_b32_e32 v51, v0
	v_mov_b32_e32 v52, v0
	v_mov_b32_e32 v53, v0
	v_mov_b32_e32 v54, v0
	v_mov_b32_e32 v55, v0
	v_mov_b32_e32 v8, v0
	v_mov_b32_e32 v9, v0
	v_mov_b32_e32 v10, v0
	v_mov_b32_e32 v11, v0
	v_mov_b32_e32 v12, v0
	v_mov_b32_e32 v13, v0
	v_mov_b32_e32 v14, v0
	v_mov_b32_e32 v15, v0
	v_mov_b32_e32 v24, v0
	v_mov_b32_e32 v25, v0
	v_mov_b32_e32 v26, v0
	v_mov_b32_e32 v27, v0
	v_mov_b32_e32 v28, v0
	v_mov_b32_e32 v29, v0
	v_mov_b32_e32 v30, v0
	v_mov_b32_e32 v31, v0
	v_mov_b32_e32 v40, v0
	v_mov_b32_e32 v41, v0
	v_mov_b32_e32 v42, v0
	v_mov_b32_e32 v43, v0
	v_mov_b32_e32 v44, v0
	v_mov_b32_e32 v45, v0
	v_mov_b32_e32 v46, v0
	v_mov_b32_e32 v47, v0
	v_mov_b32_e32 v56, v0
	v_mov_b32_e32 v57, v0
	v_mov_b32_e32 v58, v0
	v_mov_b32_e32 v59, v0
	v_mov_b32_e32 v60, v0
	v_mov_b32_e32 v61, v0
	v_mov_b32_e32 v62, v0
	v_mov_b32_e32 v63, v0
	v_mov_b32_e32 v64, v0
	v_mov_b32_e32 v65, v0
	v_mov_b32_e32 v66, v0
	v_mov_b32_e32 v67, v0
	v_mov_b32_e32 v68, v0
	v_mov_b32_e32 v69, v0
	v_mov_b32_e32 v70, v0
	v_mov_b32_e32 v71, v0
	v_mov_b32_e32 v80, v0
	v_mov_b32_e32 v81, v0
	v_mov_b32_e32 v82, v0
	v_mov_b32_e32 v83, v0
	v_mov_b32_e32 v84, v0
	v_mov_b32_e32 v85, v0
	v_mov_b32_e32 v86, v0
	v_mov_b32_e32 v87, v0
	v_mov_b32_e32 v96, v0
	v_mov_b32_e32 v97, v0
	v_mov_b32_e32 v98, v0
	v_mov_b32_e32 v99, v0
	v_mov_b32_e32 v100, v0
	v_mov_b32_e32 v101, v0
	v_mov_b32_e32 v102, v0
	v_mov_b32_e32 v103, v0
	v_mov_b32_e32 v112, v0
	v_mov_b32_e32 v113, v0
	v_mov_b32_e32 v114, v0
	v_mov_b32_e32 v115, v0
	v_mov_b32_e32 v116, v0
	v_mov_b32_e32 v117, v0
	v_mov_b32_e32 v118, v0
	v_mov_b32_e32 v119, v0
	v_mov_b32_e32 v72, v0
	v_mov_b32_e32 v73, v0
	v_mov_b32_e32 v74, v0
	v_mov_b32_e32 v75, v0
	v_mov_b32_e32 v76, v0
	v_mov_b32_e32 v77, v0
	v_mov_b32_e32 v78, v0
	v_mov_b32_e32 v79, v0
	v_mov_b32_e32 v88, v0
	v_mov_b32_e32 v89, v0
	v_mov_b32_e32 v90, v0
	v_mov_b32_e32 v91, v0
	v_mov_b32_e32 v92, v0
	v_mov_b32_e32 v93, v0
	v_mov_b32_e32 v94, v0
	v_mov_b32_e32 v95, v0
	v_mov_b32_e32 v104, v0
	v_mov_b32_e32 v105, v0
	v_mov_b32_e32 v106, v0
	v_mov_b32_e32 v107, v0
	v_mov_b32_e32 v108, v0
	v_mov_b32_e32 v109, v0
	v_mov_b32_e32 v110, v0
	v_mov_b32_e32 v111, v0
	v_mov_b32_e32 v120, v0
	v_mov_b32_e32 v121, v0
	v_mov_b32_e32 v122, v0
	v_mov_b32_e32 v123, v0
	v_mov_b32_e32 v124, v0
	v_mov_b32_e32 v125, v0
	v_mov_b32_e32 v126, v0
	v_mov_b32_e32 v127, v0
	s_nop 0
	s_nop 0
	s_nop 0
	s_nop 0
	s_nop 0
	s_nop 0
	s_nop 0
	s_nop 0
	s_nop 0
	s_nop 0
	s_nop 0
.LBB0_1170:
	ds_read_b128 v[160:163], v156
	ds_read_b128 v[164:167], v156 offset:1024
	ds_read_b128 v[168:171], v156 offset:2048
	ds_read_b128 v[172:175], v156 offset:3072
	ds_read_b128 v[176:179], v157
	ds_read_b128 v[182:185], v157 offset:1024
	ds_read_b128 v[186:189], v157 offset:2048
	ds_read_b128 v[190:193], v157 offset:3072
	s_add_u32 s26, s24, 0x100
	s_addc_u32 s27, s25, 0
	s_cmp_eq_u32 s47, 40
	s_cselect_b32 s31, s11, s27
	s_cselect_b32 s30, s10, s26
	s_cselect_b32 s29, s21, s46
	s_cselect_b32 s28, s20, s23
	v_lshl_add_u64 v[144:145], s[24:25], 0, v[136:137]
	s_add_i32 m0, s34, 0xc000
	ds_read_b128 v[202:205], v158
	ds_read_b128 v[206:209], v158 offset:1024
	ds_read_b128 v[210:213], v158 offset:2048
	ds_read_b128 v[214:217], v158 offset:3072
	ds_read_b128 v[218:221], v158 offset:4096
	ds_read_b128 v[222:225], v158 offset:5120
	ds_read_b128 v[226:229], v158 offset:6144
	ds_read_b128 v[230:233], v158 offset:7168
	global_load_lds_dwordx4 v[144:145], off
	v_lshl_add_u64 v[144:145], s[24:25], 0, v[138:139]
	s_add_i32 m0, s34, 0xe000
	s_nop 0
	global_load_lds_dwordx4 v[144:145], off
	s_waitcnt vmcnt(8)
	s_waitcnt lgkmcnt(0)
	s_barrier
	s_setprio 1
	s_waitcnt lgkmcnt(0)
	v_mfma_f32_16x16x32_bf16 v[124:127], v[160:163], v[202:205], v[124:127]
	v_mfma_f32_16x16x32_bf16 v[120:123], v[168:171], v[202:205], v[120:123]
	v_mfma_f32_16x16x32_bf16 v[108:111], v[160:163], v[210:213], v[108:111]
	v_mfma_f32_16x16x32_bf16 v[104:107], v[168:171], v[210:213], v[104:107]
	v_mfma_f32_16x16x32_bf16 v[92:95], v[160:163], v[218:221], v[92:95]
	v_mfma_f32_16x16x32_bf16 v[88:91], v[168:171], v[218:221], v[88:91]
	v_mfma_f32_16x16x32_bf16 v[76:79], v[160:163], v[226:229], v[76:79]
	v_mfma_f32_16x16x32_bf16 v[72:75], v[168:171], v[226:229], v[72:75]
	v_mfma_f32_16x16x32_bf16 v[124:127], v[164:167], v[206:209], v[124:127]
	v_mfma_f32_16x16x32_bf16 v[120:123], v[172:175], v[206:209], v[120:123]
	v_mfma_f32_16x16x32_bf16 v[108:111], v[164:167], v[214:217], v[108:111]
	v_mfma_f32_16x16x32_bf16 v[104:107], v[172:175], v[214:217], v[104:107]
	v_mfma_f32_16x16x32_bf16 v[92:95], v[164:167], v[222:225], v[92:95]
	v_mfma_f32_16x16x32_bf16 v[88:91], v[172:175], v[222:225], v[88:91]
	v_mfma_f32_16x16x32_bf16 v[76:79], v[164:167], v[230:233], v[76:79]
	v_mfma_f32_16x16x32_bf16 v[72:75], v[172:175], v[230:233], v[72:75]
	s_setprio 0
	s_setprio 1
	v_mfma_f32_16x16x32_bf16 v[116:119], v[176:179], v[202:205], v[116:119]
	v_mfma_f32_16x16x32_bf16 v[112:115], v[186:189], v[202:205], v[112:115]
	v_mfma_f32_16x16x32_bf16 v[100:103], v[176:179], v[210:213], v[100:103]
	v_mfma_f32_16x16x32_bf16 v[96:99], v[186:189], v[210:213], v[96:99]
	v_mfma_f32_16x16x32_bf16 v[84:87], v[176:179], v[218:221], v[84:87]
	v_mfma_f32_16x16x32_bf16 v[80:83], v[186:189], v[218:221], v[80:83]
	v_mfma_f32_16x16x32_bf16 v[68:71], v[176:179], v[226:229], v[68:71]
	v_mfma_f32_16x16x32_bf16 v[64:67], v[186:189], v[226:229], v[64:67]
	v_mfma_f32_16x16x32_bf16 v[116:119], v[182:185], v[206:209], v[116:119]
	v_mfma_f32_16x16x32_bf16 v[112:115], v[190:193], v[206:209], v[112:115]
	v_mfma_f32_16x16x32_bf16 v[100:103], v[182:185], v[214:217], v[100:103]
	v_mfma_f32_16x16x32_bf16 v[96:99], v[190:193], v[214:217], v[96:99]
	v_mfma_f32_16x16x32_bf16 v[84:87], v[182:185], v[222:225], v[84:87]
	v_mfma_f32_16x16x32_bf16 v[80:83], v[190:193], v[222:225], v[80:83]
	v_mfma_f32_16x16x32_bf16 v[68:71], v[182:185], v[230:233], v[68:71]
	v_mfma_f32_16x16x32_bf16 v[64:67], v[190:193], v[230:233], v[64:67]
	s_setprio 0
	s_barrier
; #define PG8_STAGE(bufoff, gbase, voff) do { _Pragma("unroll") for (int _i = 0; _i < 2; ++_i) \
;         __builtin_amdgcn_global_load_lds((const unsigned*)((const char*)(gbase) + (voff)[_i]), (PG8_LAS unsigned*)(lds + (bufoff) + ldsw + _i * 8192), 16, 0, 0); } while (0)
; #define PG8_LDA(dst, b, h) do { _Pragma("unroll") for (int m = 0; m < 4; ++m) _Pragma("unroll") for (int k = 0; k < 2; ++k) dst[m][k] = *(const PG8_LAS bf16x8*)(lds + PG8_SA(b, h) + aoff + m * 2048 + k * 1024); } while (0)
; #define PG8_LDB(dst, b, h) do { _Pragma("unroll") for (int n = 0; n < 2; ++n) _Pragma("unroll") for (int k = 0; k < 2; ++k) dst[n][k] = *(const PG8_LAS bf16x8*)(lds + PG8_SB(b, h) + boff + n * 2048 + k * 1024); } while (0)
; #define PG8_MMA(ai, bj, At, Bt) do { __builtin_amdgcn_s_setprio(1); _Pragma("unroll") for (int m = 0; m < 4; ++m) _Pragma("unroll") for (int n = 0; n < 2; ++n) _Pragma("unroll") for (int k = 0; k < 2; ++k) \
;         acc[ai][bj][m][n] = __builtin_amdgcn_mfma_f32_16x16x32_bf16(Bt[n][k], At[m][k], acc[ai][bj][m][n], 0, 0, 0); __builtin_amdgcn_s_setprio(0); } while (0)
; #define PG8_WAIT_V(n) asm volatile("s_waitcnt vmcnt(" #n ")" ::: "memory")
; #define PG8_WAIT_L(n) asm volatile("s_waitcnt lgkmcnt(" #n ")" ::: "memory")
; #define PG8_BAR __builtin_amdgcn_s_barrier()
; #define PG8_SCHED __builtin_amdgcn_sched_barrier(0)
; template <class Epi, class Sched, bool ALIGN_EPI = false, bool SP2 = false>
; __device__ __forceinline__ void gemm_phase(PG8_LAS unsigned char* lds, const Gemm g, const Sched& S, const Epi& E, const int tid_arg) {
;     ...
;             PG8_LDA(At, 0, 1); PG8_STAGE(PG8_SB(0, 0), b2, voffB); PG8_STAGE(PG8_SB(0, 1), b2 + hstep, voffB); PG8_STAGE(PG8_SA(0, 0), a2, voffA);
;             PG8_WAIT_V(8); PG8_WAIT_L(0); PG8_BAR; PG8_MMA(1, 0, At, B0); PG8_MMA(1, 1, At, B1); PG8_BAR; PG8_SCHED;
;             PG8_LDB(B0, 1, 0); PG8_LDB(B1, 1, 1); PG8_SCHED; PG8_LDA(At, 1, 0); PG8_STAGE(PG8_SA(0, 1), a2 + hstep, voffA);
	s_add_i32 s24, s41, s33
	v_lshl_add_u64 v[144:145], s[28:29], 0, v[130:131]
	s_mov_b32 m0, s24
	ds_read_b128 v[202:205], v158 offset:16384
	ds_read_b128 v[206:209], v158 offset:17408
	ds_read_b128 v[210:213], v158 offset:18432
	ds_read_b128 v[214:217], v158 offset:19456
	ds_read_b128 v[218:221], v158 offset:20480
	ds_read_b128 v[222:225], v158 offset:21504
	ds_read_b128 v[226:229], v158 offset:22528
	ds_read_b128 v[230:233], v158 offset:23552
	global_load_lds_dwordx4 v[144:145], off
	s_add_i32 m0, s24, 0x2000
	s_add_u32 s24, s28, 0xb0000
	v_lshl_add_u64 v[194:195], s[28:29], 0, v[134:135]
	s_addc_u32 s25, s29, 0
	s_add_i32 s48, s42, s33
	global_load_lds_dwordx4 v[194:195], off
	v_lshl_add_u64 v[234:235], s[24:25], 0, v[130:131]
	s_mov_b32 m0, s48
	v_lshl_add_u64 v[236:237], s[30:31], 0, v[132:133]
	global_load_lds_dwordx4 v[234:235], off
	v_lshl_add_u64 v[234:235], s[24:25], 0, v[134:135]
	s_add_i32 m0, s48, 0x2000
	s_nop 0
	global_load_lds_dwordx4 v[234:235], off
	v_lshl_add_u64 v[234:235], s[30:31], 0, v[128:129]
	s_mov_b32 m0, s34
	s_nop 0
	global_load_lds_dwordx4 v[234:235], off
	s_mov_b32 m0, s35
	s_nop 0
	global_load_lds_dwordx4 v[236:237], off
	s_waitcnt vmcnt(8)
	s_waitcnt lgkmcnt(0)
	s_barrier
	s_setprio 1
	s_waitcnt lgkmcnt(0)
	v_mfma_f32_16x16x32_bf16 v[60:63], v[160:163], v[202:205], v[60:63]
	v_mfma_f32_16x16x32_bf16 v[56:59], v[168:171], v[202:205], v[56:59]
	v_mfma_f32_16x16x32_bf16 v[44:47], v[160:163], v[210:213], v[44:47]
	v_mfma_f32_16x16x32_bf16 v[40:43], v[168:171], v[210:213], v[40:43]
	v_mfma_f32_16x16x32_bf16 v[28:31], v[160:163], v[218:221], v[28:31]
	v_mfma_f32_16x16x32_bf16 v[24:27], v[168:171], v[218:221], v[24:27]
	v_mfma_f32_16x16x32_bf16 v[12:15], v[160:163], v[226:229], v[12:15]
	v_mfma_f32_16x16x32_bf16 v[8:11], v[168:171], v[226:229], v[8:11]
	v_mfma_f32_16x16x32_bf16 v[60:63], v[164:167], v[206:209], v[60:63]
	v_mfma_f32_16x16x32_bf16 v[56:59], v[172:175], v[206:209], v[56:59]
	v_mfma_f32_16x16x32_bf16 v[44:47], v[164:167], v[214:217], v[44:47]
	v_mfma_f32_16x16x32_bf16 v[40:43], v[172:175], v[214:217], v[40:43]
	v_mfma_f32_16x16x32_bf16 v[28:31], v[164:167], v[222:225], v[28:31]
	v_mfma_f32_16x16x32_bf16 v[24:27], v[172:175], v[222:225], v[24:27]
	v_mfma_f32_16x16x32_bf16 v[12:15], v[164:167], v[230:233], v[12:15]
	v_mfma_f32_16x16x32_bf16 v[8:11], v[172:175], v[230:233], v[8:11]
	s_setprio 0
	s_setprio 1
	v_mfma_f32_16x16x32_bf16 v[52:55], v[176:179], v[202:205], v[52:55]
	v_mfma_f32_16x16x32_bf16 v[48:51], v[186:189], v[202:205], v[48:51]
	v_mfma_f32_16x16x32_bf16 v[36:39], v[176:179], v[210:213], v[36:39]
	v_mfma_f32_16x16x32_bf16 v[32:35], v[186:189], v[210:213], v[32:35]
	v_mfma_f32_16x16x32_bf16 v[20:23], v[176:179], v[218:221], v[20:23]
	v_mfma_f32_16x16x32_bf16 v[16:19], v[186:189], v[218:221], v[16:19]
	v_mfma_f32_16x16x32_bf16 v[4:7], v[176:179], v[226:229], v[4:7]
	v_mfma_f32_16x16x32_bf16 v[0:3], v[186:189], v[226:229], v[0:3]
	v_mfma_f32_16x16x32_bf16 v[52:55], v[182:185], v[206:209], v[52:55]
	v_mfma_f32_16x16x32_bf16 v[48:51], v[190:193], v[206:209], v[48:51]
	v_mfma_f32_16x16x32_bf16 v[36:39], v[182:185], v[214:217], v[36:39]
	v_mfma_f32_16x16x32_bf16 v[32:35], v[190:193], v[214:217], v[32:35]
	v_mfma_f32_16x16x32_bf16 v[20:23], v[182:185], v[222:225], v[20:23]
	v_mfma_f32_16x16x32_bf16 v[16:19], v[190:193], v[222:225], v[16:19]
	v_mfma_f32_16x16x32_bf16 v[4:7], v[182:185], v[230:233], v[4:7]
	v_mfma_f32_16x16x32_bf16 v[0:3], v[190:193], v[230:233], v[0:3]
	s_setprio 0
	s_barrier
	s_add_i32 s48, 0, 0x18000
	v_add_u32_e32 v159, s48, v147
	s_add_i32 s49, 0, 0x1c000
	ds_read_b128 v[160:163], v159
	ds_read_b128 v[164:167], v159 offset:1024
	ds_read_b128 v[168:171], v159 offset:2048
	ds_read_b128 v[172:175], v159 offset:3072
	v_add_u32_e32 v159, s49, v147
	ds_read_b128 v[176:179], v159
	ds_read_b128 v[182:185], v159 offset:1024
	ds_read_b128 v[186:189], v159 offset:2048
	ds_read_b128 v[190:193], v159 offset:3072
	s_add_u32 s24, s30, 0xb0000
	s_addc_u32 s25, s31, 0
	s_mov_b32 m0, s36
	v_lshl_add_u64 v[238:239], s[24:25], 0, v[128:129]
	ds_read_b128 v[202:205], v158 offset:32768
	ds_read_b128 v[206:209], v158 offset:33792
	ds_read_b128 v[210:213], v158 offset:34816
	ds_read_b128 v[214:217], v158 offset:35840
	ds_read_b128 v[218:221], v158 offset:36864
	ds_read_b128 v[222:225], v158 offset:37888
	ds_read_b128 v[226:229], v158 offset:38912
	ds_read_b128 v[230:233], v158 offset:39936
	global_load_lds_dwordx4 v[238:239], off
	v_lshl_add_u64 v[238:239], s[24:25], 0, v[132:133]
	s_mov_b32 m0, s37
	s_nop 0
	global_load_lds_dwordx4 v[238:239], off
	s_waitcnt vmcnt(8)
	s_waitcnt lgkmcnt(0)
	s_barrier
; #define PG8_STAGE(bufoff, gbase, voff) do { _Pragma("unroll") for (int _i = 0; _i < 2; ++_i) \
;         __builtin_amdgcn_global_load_lds((const unsigned*)((const char*)(gbase) + (voff)[_i]), (PG8_LAS unsigned*)(lds + (bufoff) + ldsw + _i * 8192), 16, 0, 0); } while (0)
; #define PG8_LDA(dst, b, h) do { _Pragma("unroll") for (int m = 0; m < 4; ++m) _Pragma("unroll") for (int k = 0; k < 2; ++k) dst[m][k] = *(const PG8_LAS bf16x8*)(lds + PG8_SA(b, h) + aoff + m * 2048 + k * 1024); } while (0)
; #define PG8_MMA(ai, bj, At, Bt) do { __builtin_amdgcn_s_setprio(1); _Pragma("unroll") for (int m = 0; m < 4; ++m) _Pragma("unroll") for (int n = 0; n < 2; ++n) _Pragma("unroll") for (int k = 0; k < 2; ++k) \
;         acc[ai][bj][m][n] = __builtin_amdgcn_mfma_f32_16x16x32_bf16(Bt[n][k], At[m][k], acc[ai][bj][m][n], 0, 0, 0); __builtin_amdgcn_s_setprio(0); } while (0)
; #define PG8_WAIT_V(n) asm volatile("s_waitcnt vmcnt(" #n ")" ::: "memory")
; #define PG8_WAIT_L(n) asm volatile("s_waitcnt lgkmcnt(" #n ")" ::: "memory")
; #define PG8_BAR __builtin_amdgcn_s_barrier()
; #define PG8_SCHED __builtin_amdgcn_sched_barrier(0)
; template <class Epi, class Sched, bool ALIGN_EPI = false, bool SP2 = false>
; __device__ __forceinline__ void gemm_phase(PG8_LAS unsigned char* lds, const Gemm g, const Sched& S, const Epi& E, const int tid_arg) {
;     ...
;             PG8_WAIT_V(8); PG8_WAIT_L(0); PG8_BAR; PG8_MMA(0, 0, At, B0); PG8_MMA(0, 1, At, B1); PG8_BAR; PG8_SCHED;
;             PG8_LDA(At, 1, 1); PG8_STAGE(PG8_SB(1, 0), b3, voffB); PG8_STAGE(PG8_SB(1, 1), b3 + hstep, voffB); PG8_STAGE(PG8_SA(1, 0), a3, voffA);
;             PG8_WAIT_V(8); PG8_WAIT_L(0); PG8_BAR; PG8_MMA(1, 0, At, B0); PG8_MMA(1, 1, At, B1); PG8_BAR; PG8_SCHED;
	s_setprio 1
	s_waitcnt lgkmcnt(0)
	v_mfma_f32_16x16x32_bf16 v[124:127], v[160:163], v[202:205], v[124:127]
	v_mfma_f32_16x16x32_bf16 v[120:123], v[168:171], v[202:205], v[120:123]
	v_mfma_f32_16x16x32_bf16 v[108:111], v[160:163], v[210:213], v[108:111]
	v_mfma_f32_16x16x32_bf16 v[104:107], v[168:171], v[210:213], v[104:107]
	v_mfma_f32_16x16x32_bf16 v[92:95], v[160:163], v[218:221], v[92:95]
	v_mfma_f32_16x16x32_bf16 v[88:91], v[168:171], v[218:221], v[88:91]
	v_mfma_f32_16x16x32_bf16 v[76:79], v[160:163], v[226:229], v[76:79]
	v_mfma_f32_16x16x32_bf16 v[72:75], v[168:171], v[226:229], v[72:75]
	v_mfma_f32_16x16x32_bf16 v[124:127], v[164:167], v[206:209], v[124:127]
	v_mfma_f32_16x16x32_bf16 v[120:123], v[172:175], v[206:209], v[120:123]
	v_mfma_f32_16x16x32_bf16 v[108:111], v[164:167], v[214:217], v[108:111]
	v_mfma_f32_16x16x32_bf16 v[104:107], v[172:175], v[214:217], v[104:107]
	v_mfma_f32_16x16x32_bf16 v[92:95], v[164:167], v[222:225], v[92:95]
	v_mfma_f32_16x16x32_bf16 v[88:91], v[172:175], v[222:225], v[88:91]
	v_mfma_f32_16x16x32_bf16 v[76:79], v[164:167], v[230:233], v[76:79]
	v_mfma_f32_16x16x32_bf16 v[72:75], v[172:175], v[230:233], v[72:75]
	s_setprio 0
	s_setprio 1
	v_mfma_f32_16x16x32_bf16 v[116:119], v[176:179], v[202:205], v[116:119]
	v_mfma_f32_16x16x32_bf16 v[112:115], v[186:189], v[202:205], v[112:115]
	v_mfma_f32_16x16x32_bf16 v[100:103], v[176:179], v[210:213], v[100:103]
	v_mfma_f32_16x16x32_bf16 v[96:99], v[186:189], v[210:213], v[96:99]
	v_mfma_f32_16x16x32_bf16 v[84:87], v[176:179], v[218:221], v[84:87]
	v_mfma_f32_16x16x32_bf16 v[80:83], v[186:189], v[218:221], v[80:83]
	v_mfma_f32_16x16x32_bf16 v[68:71], v[176:179], v[226:229], v[68:71]
	v_mfma_f32_16x16x32_bf16 v[64:67], v[186:189], v[226:229], v[64:67]
	v_mfma_f32_16x16x32_bf16 v[116:119], v[182:185], v[206:209], v[116:119]
	v_mfma_f32_16x16x32_bf16 v[112:115], v[190:193], v[206:209], v[112:115]
	v_mfma_f32_16x16x32_bf16 v[100:103], v[182:185], v[214:217], v[100:103]
	v_mfma_f32_16x16x32_bf16 v[96:99], v[190:193], v[214:217], v[96:99]
	v_mfma_f32_16x16x32_bf16 v[84:87], v[182:185], v[222:225], v[84:87]
	v_mfma_f32_16x16x32_bf16 v[80:83], v[190:193], v[222:225], v[80:83]
	v_mfma_f32_16x16x32_bf16 v[68:71], v[182:185], v[230:233], v[68:71]
	v_mfma_f32_16x16x32_bf16 v[64:67], v[190:193], v[230:233], v[64:67]
	s_setprio 0
	s_barrier
	s_add_i32 s24, s48, s33
	v_lshl_add_u64 v[144:145], v[144:145], 0, s[16:17]
	s_mov_b32 m0, s24
	ds_read_b128 v[202:205], v158 offset:49152
	ds_read_b128 v[206:209], v158 offset:50176
	ds_read_b128 v[210:213], v158 offset:51200
	ds_read_b128 v[214:217], v158 offset:52224
	ds_read_b128 v[218:221], v158 offset:53248
	ds_read_b128 v[222:225], v158 offset:54272
	ds_read_b128 v[226:229], v158 offset:55296
	ds_read_b128 v[230:233], v158 offset:56320
	global_load_lds_dwordx4 v[144:145], off
	s_add_i32 m0, s24, 0x2000
	s_add_u32 s24, s28, 0xb0080
	v_lshl_add_u64 v[144:145], v[194:195], 0, s[16:17]
	s_addc_u32 s25, s29, 0
	s_add_i32 s28, s49, s33
	global_load_lds_dwordx4 v[144:145], off
	v_lshl_add_u64 v[144:145], s[24:25], 0, v[130:131]
	s_mov_b32 m0, s28
	s_nop 0
	global_load_lds_dwordx4 v[144:145], off
	v_lshl_add_u64 v[144:145], s[24:25], 0, v[134:135]
	s_add_i32 m0, s28, 0x2000
	s_nop 0
	global_load_lds_dwordx4 v[144:145], off
	v_lshl_add_u64 v[144:145], v[234:235], 0, s[16:17]
	s_mov_b32 m0, s39
	s_nop 0
	global_load_lds_dwordx4 v[144:145], off
	v_lshl_add_u64 v[144:145], v[236:237], 0, s[16:17]
	s_mov_b32 m0, s40
	s_nop 0
	global_load_lds_dwordx4 v[144:145], off
	s_waitcnt vmcnt(8)
	s_waitcnt lgkmcnt(0)
	s_barrier
	s_setprio 1
	s_waitcnt lgkmcnt(0)
	v_mfma_f32_16x16x32_bf16 v[60:63], v[160:163], v[202:205], v[60:63]
	v_mfma_f32_16x16x32_bf16 v[56:59], v[168:171], v[202:205], v[56:59]
	v_mfma_f32_16x16x32_bf16 v[44:47], v[160:163], v[210:213], v[44:47]
	v_mfma_f32_16x16x32_bf16 v[40:43], v[168:171], v[210:213], v[40:43]
	v_mfma_f32_16x16x32_bf16 v[28:31], v[160:163], v[218:221], v[28:31]
	v_mfma_f32_16x16x32_bf16 v[24:27], v[168:171], v[218:221], v[24:27]
	v_mfma_f32_16x16x32_bf16 v[12:15], v[160:163], v[226:229], v[12:15]
	v_mfma_f32_16x16x32_bf16 v[8:11], v[168:171], v[226:229], v[8:11]
	v_mfma_f32_16x16x32_bf16 v[60:63], v[164:167], v[206:209], v[60:63]
	v_mfma_f32_16x16x32_bf16 v[56:59], v[172:175], v[206:209], v[56:59]
	v_mfma_f32_16x16x32_bf16 v[44:47], v[164:167], v[214:217], v[44:47]
	v_mfma_f32_16x16x32_bf16 v[40:43], v[172:175], v[214:217], v[40:43]
	v_mfma_f32_16x16x32_bf16 v[28:31], v[164:167], v[222:225], v[28:31]
	v_mfma_f32_16x16x32_bf16 v[24:27], v[172:175], v[222:225], v[24:27]
	v_mfma_f32_16x16x32_bf16 v[12:15], v[164:167], v[230:233], v[12:15]
	v_mfma_f32_16x16x32_bf16 v[8:11], v[172:175], v[230:233], v[8:11]
	s_setprio 0
	s_setprio 1
	v_mfma_f32_16x16x32_bf16 v[52:55], v[176:179], v[202:205], v[52:55]
	v_mfma_f32_16x16x32_bf16 v[48:51], v[186:189], v[202:205], v[48:51]
	v_mfma_f32_16x16x32_bf16 v[36:39], v[176:179], v[210:213], v[36:39]
	v_mfma_f32_16x16x32_bf16 v[32:35], v[186:189], v[210:213], v[32:35]
	v_mfma_f32_16x16x32_bf16 v[20:23], v[176:179], v[218:221], v[20:23]
	v_mfma_f32_16x16x32_bf16 v[16:19], v[186:189], v[218:221], v[16:19]
	v_mfma_f32_16x16x32_bf16 v[4:7], v[176:179], v[226:229], v[4:7]
	v_mfma_f32_16x16x32_bf16 v[0:3], v[186:189], v[226:229], v[0:3]
	v_mfma_f32_16x16x32_bf16 v[52:55], v[182:185], v[206:209], v[52:55]
	v_mfma_f32_16x16x32_bf16 v[48:51], v[190:193], v[206:209], v[48:51]
	v_mfma_f32_16x16x32_bf16 v[36:39], v[182:185], v[214:217], v[36:39]
	v_mfma_f32_16x16x32_bf16 v[32:35], v[190:193], v[214:217], v[32:35]
	v_mfma_f32_16x16x32_bf16 v[20:23], v[182:185], v[222:225], v[20:23]
	v_mfma_f32_16x16x32_bf16 v[16:19], v[190:193], v[222:225], v[16:19]
	v_mfma_f32_16x16x32_bf16 v[4:7], v[182:185], v[230:233], v[4:7]
	v_mfma_f32_16x16x32_bf16 v[0:3], v[190:193], v[230:233], v[0:3]
	s_setprio 0
	s_barrier
	s_add_i32 s47, s47, 2
	s_add_u32 s23, s23, 0x100
	s_addc_u32 s46, s46, 0
	s_cmp_gt_u32 s47, 41
	s_mov_b64 s[24:25], s[26:27]
	s_cbranch_scc0 .LBB0_1170
	s_and_b64 vcc, exec, s[18:19]
	s_cbranch_vccz .LBB0_1173
	s_barrier

; __device__ __forceinline__ unsigned xb_ld(unsigned* p)              { return __hip_atomic_load(p, __ATOMIC_RELAXED, __HIP_MEMORY_SCOPE_AGENT); }
; __device__ __forceinline__ unsigned xb_add(unsigned* p, unsigned v) { return __hip_atomic_fetch_add(p, v, __ATOMIC_RELAXED, __HIP_MEMORY_SCOPE_AGENT); }
; #define XB_SPIN(cond, bar) do { unsigned _sp = 0; while (cond) { __builtin_amdgcn_s_sleep(1); \
;     if ((++_sp & 255u) == 0u) { if (xb_ld(&(bar)[XB_TMO])) break; if (_sp > XB_SPIN_CAP) { atomicAdd(&(bar)[XB_TMO], 1u); break; } } } } while (0)
; __device__ __forceinline__ void xcd_barrier(const XcdBarrier& b, const bool leader) {
;     ...
;         const unsigned old = xb_add(&bar[XB_XSUB(b.x)], 1u);
;         const unsigned gen = old / nloc;
;         if (old + 1u == (gen + 1u) * nloc) {
;             __builtin_amdgcn_fence(__ATOMIC_RELEASE, "agent");
;             asm volatile("s_waitcnt vmcnt(0)" ::: "memory");
;             const unsigned og = xb_add(&bar[XB_TOP], 1u);
;             const unsigned tg = og / nx;
;             if (og + 1u == (tg + 1u) * nx) xb_add(&bar[XB_TOPGEN], 1u);
;             else XB_SPIN(xb_ld(&bar[XB_TOPGEN]) == tg, bar);
;             __builtin_amdgcn_fence(__ATOMIC_ACQUIRE, "agent");
;             xb_add(&bar[XB_XGEN(b.x)], 1u);
;             asm volatile("s_waitcnt vmcnt(0)" ::: "memory");
;         } else {
;             XB_SPIN(xb_ld(&bar[XB_XGEN(b.x)]) == gen, bar);
.LBB0_1198:
	s_or_b64 exec, exec, s[10:11]
	v_cvt_f32_u32_e32 v4, v2
	s_waitcnt vmcnt(0)
	v_readfirstlane_b32 s0, v3
	v_sub_u32_e32 v3, 0, v2
	v_rcp_iflag_f32_e32 v4, v4
	v_add_u32_e32 v5, s0, v1
	v_mul_f32_e32 v4, 0x4f7ffffe, v4
	v_cvt_u32_f32_e32 v4, v4
	v_mul_lo_u32 v1, v3, v4
	v_mul_hi_u32 v1, v4, v1
	v_add_u32_e32 v1, v4, v1
	v_mul_hi_u32 v1, v5, v1
	v_mul_lo_u32 v3, v1, v2
	v_sub_u32_e32 v3, v5, v3
	v_add_u32_e32 v4, 1, v1
	v_cmp_ge_u32_e32 vcc, v3, v2
	s_nop 1
	v_cndmask_b32_e32 v1, v1, v4, vcc
	v_sub_u32_e32 v4, v3, v2
	v_cndmask_b32_e32 v3, v3, v4, vcc
	v_add_u32_e32 v4, 1, v1
	v_cmp_ge_u32_e32 vcc, v3, v2
	v_add_u32_e32 v3, 1, v5
	s_nop 0
	v_cndmask_b32_e32 v1, v1, v4, vcc
	v_mul_lo_u32 v4, v2, v1
	v_add_u32_e32 v2, v4, v2
	v_cmp_ne_u32_e32 vcc, v3, v2
	s_and_saveexec_b64 s[0:1], vcc
	s_xor_b64 s[8:9], exec, s[0:1]
	s_cbranch_execz .LBB0_1212
	buffer_inv sc1
	s_waitcnt lgkmcnt(0)
	v_mov_b32_e32 v0, 0x2000
	s_load_dwordx2 s[14:15], s[90:91], 0xb0
	s_waitcnt lgkmcnt(0)
	s_add_u32 s14, s14, 0x1d79b500
	s_addc_u32 s15, s15, 0
	v_mov_b32_e32 v0, 0
	global_load_dword v0, v0, s[14:15] sc1
	s_waitcnt vmcnt(0)
	v_cmp_eq_u32_e32 vcc, v0, v1
	s_and_saveexec_b64 s[10:11], vcc
	s_cbranch_execz .LBB0_1211
	s_add_u32 s12, s4, 0x1d798200
	s_addc_u32 s13, s5, 0
	s_mov_b32 s0, 1
	s_mov_b64 s[16:17], 0
	v_mov_b32_e32 v0, 0
	s_branch .LBB0_1202

; __device__ __forceinline__ unsigned xb_add(unsigned* p, unsigned v) { return __hip_atomic_fetch_add(p, v, __ATOMIC_RELAXED, __HIP_MEMORY_SCOPE_AGENT); }
; __device__ __forceinline__ void xcd_barrier(const XcdBarrier& b, const bool leader) {
;     ...
;         if (old + 1u == (gen + 1u) * nloc) {
;             __builtin_amdgcn_fence(__ATOMIC_RELEASE, "agent");
;             asm volatile("s_waitcnt vmcnt(0)" ::: "memory");
;             const unsigned og = xb_add(&bar[XB_TOP], 1u);
;             const unsigned tg = og / nx;
;             if (og + 1u == (tg + 1u) * nx) xb_add(&bar[XB_TOPGEN], 1u);
.LBB0_1212:
	s_andn2_saveexec_b64 s[0:1], s[8:9]
	s_cbranch_execz .LBB0_1232
	s_mov_b64 s[8:9], exec
	buffer_wbl2 sc1
	buffer_inv sc1
	s_waitcnt lgkmcnt(0)
	s_waitcnt vmcnt(0)
	v_mbcnt_lo_u32_b32 v1, s8, 0
	v_mbcnt_hi_u32_b32 v1, s9, v1
	v_cmp_eq_u32_e32 vcc, 0, v1
	s_and_saveexec_b64 s[10:11], vcc
	s_cbranch_execz .LBB0_1215
	s_bcnt1_i32_b64 s0, s[8:9]
	v_mov_b32_e32 v2, 0x1d79b000
	v_mov_b32_e32 v3, s0
	global_atomic_add v2, v2, v3, s[4:5] offset:1024 sc0
